# v34 + K-loop vmcnt/lgkmcnt waits merged into one instruction + no s_sleep in the group-barrier and exchange spin loops
# baseline (speedup 1.0000x reference)
; #define PG8_STAGE(bufoff, gbase, voff) do { _Pragma("unroll") for (int _i = 0; _i < 2; ++_i) \
;         __builtin_amdgcn_global_load_lds((const unsigned*)((const char*)(gbase) + (voff)[_i]), (PG8_LAS unsigned*)(lds + (bufoff) + ldsw + _i * 8192), 16, 0, 0); } while (0)
; #define PG8_LDA(dst, b, h) do { _Pragma("unroll") for (int m = 0; m < 4; ++m) _Pragma("unroll") for (int k = 0; k < 2; ++k) dst[m][k] = *(const PG8_LAS bf16x8*)(lds + PG8_SA(b, h) + aoff + m * 2048 + k * 1024); } while (0)
; #define PG8_LDB(dst, b, h) do { _Pragma("unroll") for (int n = 0; n < 2; ++n) _Pragma("unroll") for (int k = 0; k < 2; ++k) dst[n][k] = *(const PG8_LAS bf16x8*)(lds + PG8_SB(b, h) + boff + n * 2048 + k * 1024); } while (0)
; #define PG8_MMA(ai, bj, At, Bt) do { __builtin_amdgcn_s_setprio(1); _Pragma("unroll") for (int m = 0; m < 4; ++m) _Pragma("unroll") for (int n = 0; n < 2; ++n) _Pragma("unroll") for (int k = 0; k < 2; ++k) \
;         acc[ai][bj][m][n] = __builtin_amdgcn_mfma_f32_16x16x32_bf16(Bt[n][k], At[m][k], acc[ai][bj][m][n], 0, 0, 0); __builtin_amdgcn_s_setprio(0); } while (0)
; template <class Epi, class Sched, bool ALIGN_EPI = false, bool SP2 = false>
; __device__ __forceinline__ void gemm_phase(PG8_LAS unsigned char* lds, const Gemm g, const Sched& S, const Epi& E) {
;     ...
;         const char* nA = has_next ? (const char*)g.A + (size_t)nxt.pm * tstep : cA; const char* nB = has_next ? (const char*)g.Bt + (size_t)nxt.pn * tstep : cB;
;         for (int t = 0; t < nt; t += 2) {
;             if constexpr (Epi::HAS_MID) { if (t == nt / 2) E.mid(acc, cur, wr, wc, fr, fq); }
;             const bool last = (t == nt - 2);
;             const char* a1 = cA + (size_t)(t + 1) * kstep;
;             const char* a2 = last ? nA : cA + (size_t)(t + 2) * kstep; const char* b2 = last ? nB : cB + (size_t)(t + 2) * kstep;
;             const char* a3 = a2 + kstep; const char* b3 = b2 + kstep;
;             if (last && has_next) S.a_ready(nxt);
;             if constexpr (SP2) {
;             PG8_LDB(B0, 0, 0); PG8_LDB(B1, 0, 1); PG8_SCHED; PG8_LDA(At, 0, 0); PG8_STAGE(PG8_SA(1, 1), a1 + hstep, voffA);
;             PG8_WAIT_V(8); PG8_WAIT_L(0); PG8_BAR; PG8_MMA(0, 0, At, B0); PG8_MMA(0, 1, At, B1); PG8_BAR; PG8_SCHED;
;             PG8_LDA(At, 0, 1); PG8_STAGE(PG8_SB(0, 0), b2, voffB); PG8_STAGE(PG8_SB(0, 1), b2 + hstepB, voffB); PG8_STAGE(PG8_SA(0, 0), a2, voffA);
.LBB0_191:
	s_ashr_i32 s13, s12, 31
	s_lshl_b64 s[14:15], s[12:13], 19
	v_readlane_b32 s16, v241, 53
	v_readlane_b32 s17, v241, 54
	s_add_u32 s14, s16, s14
	s_addc_u32 s15, s17, s15
	s_and_b64 s[16:17], s[2:3], exec
	s_cselect_b32 s5, s15, s21
	s_cselect_b32 s13, s14, s20
	s_ashr_i32 s11, s10, 31
	s_lshl_b64 s[16:17], s[10:11], 19
	v_readlane_b32 s24, v241, 36
	v_readlane_b32 s25, v241, 37
	s_add_u32 s16, s24, s16
	s_addc_u32 s17, s25, s17
	s_and_b64 s[24:25], s[2:3], exec
	s_cselect_b32 s11, s17, s23
	s_cselect_b32 s19, s16, s22
	s_add_u32 s20, s20, 0x40080
	s_addc_u32 s21, s21, 0
	s_add_u32 s73, s22, 0x100
	s_addc_u32 s74, s23, 0
	s_mov_b32 s75, -2
	ds_read_b128 v[146:149], v152
	ds_read_b128 v[156:159], v152 offset:1024
	ds_read_b128 v[160:163], v152 offset:2048
	ds_read_b128 v[164:167], v152 offset:3072
	ds_read_b128 v[168:171], v153
	ds_read_b128 v[172:175], v153 offset:1024
	ds_read_b128 v[176:179], v153 offset:2048
	ds_read_b128 v[180:183], v153 offset:3072
	s_add_u32 s22, s20, 0xfffc0080
	s_addc_u32 s23, s21, -1
	s_cmp_eq_u32 s75, 12
	s_cselect_b32 s25, s5, s23
	s_cselect_b32 s24, s13, s22
	s_cselect_b32 s23, s11, s74
	s_cselect_b32 s22, s19, s73
	v_lshl_add_u64 v[216:217], s[20:21], 0, v[138:139]
	s_add_i32 m0, s27, 0xc000
	ds_read_b128 v[184:187], v154
	ds_read_b128 v[188:191], v154 offset:1024
	ds_read_b128 v[192:195], v154 offset:2048
	ds_read_b128 v[196:199], v154 offset:3072
	ds_read_b128 v[200:203], v154 offset:4096
	ds_read_b128 v[204:207], v154 offset:5120
	ds_read_b128 v[208:211], v154 offset:6144
	ds_read_b128 v[212:215], v154 offset:7168
	global_load_lds_dwordx4 v[216:217], off
	v_lshl_add_u64 v[216:217], s[20:21], 0, v[140:141]
	s_add_i32 m0, s27, 0xe000
	s_nop 0
	global_load_lds_dwordx4 v[216:217], off
	s_waitcnt vmcnt(8) lgkmcnt(0)
	s_barrier
	v_mfma_f32_16x16x32_bf16 v[126:129], v[146:149], v[184:187], 0
	v_mfma_f32_16x16x32_bf16 v[122:125], v[160:163], v[184:187], 0
	v_mfma_f32_16x16x32_bf16 v[114:117], v[146:149], v[192:195], 0
	v_mfma_f32_16x16x32_bf16 v[106:109], v[160:163], v[192:195], 0
	v_mfma_f32_16x16x32_bf16 v[98:101], v[146:149], v[200:203], 0
	v_mfma_f32_16x16x32_bf16 v[90:93], v[160:163], v[200:203], 0
	v_mfma_f32_16x16x32_bf16 v[82:85], v[146:149], v[208:211], 0
	v_mfma_f32_16x16x32_bf16 v[74:77], v[160:163], v[208:211], 0
	v_mfma_f32_16x16x32_bf16 v[126:129], v[156:159], v[188:191], v[126:129]
	v_mfma_f32_16x16x32_bf16 v[122:125], v[164:167], v[188:191], v[122:125]
	v_mfma_f32_16x16x32_bf16 v[114:117], v[156:159], v[196:199], v[114:117]
	v_mfma_f32_16x16x32_bf16 v[106:109], v[164:167], v[196:199], v[106:109]
	v_mfma_f32_16x16x32_bf16 v[98:101], v[156:159], v[204:207], v[98:101]
	v_mfma_f32_16x16x32_bf16 v[90:93], v[164:167], v[204:207], v[90:93]
	v_mfma_f32_16x16x32_bf16 v[82:85], v[156:159], v[212:215], v[82:85]
	v_mfma_f32_16x16x32_bf16 v[74:77], v[164:167], v[212:215], v[74:77]
	v_mfma_f32_16x16x32_bf16 v[118:121], v[168:171], v[184:187], 0
	v_mfma_f32_16x16x32_bf16 v[110:113], v[176:179], v[184:187], 0
	v_mfma_f32_16x16x32_bf16 v[102:105], v[168:171], v[192:195], 0
	v_mfma_f32_16x16x32_bf16 v[94:97], v[176:179], v[192:195], 0
	v_mfma_f32_16x16x32_bf16 v[86:89], v[168:171], v[200:203], 0
	v_mfma_f32_16x16x32_bf16 v[78:81], v[176:179], v[200:203], 0
	v_mfma_f32_16x16x32_bf16 v[70:73], v[168:171], v[208:211], 0
	v_mfma_f32_16x16x32_bf16 v[66:69], v[176:179], v[208:211], 0
	v_mfma_f32_16x16x32_bf16 v[118:121], v[172:175], v[188:191], v[118:121]
	v_mfma_f32_16x16x32_bf16 v[110:113], v[180:183], v[188:191], v[110:113]
	v_mfma_f32_16x16x32_bf16 v[102:105], v[172:175], v[196:199], v[102:105]
	v_mfma_f32_16x16x32_bf16 v[94:97], v[180:183], v[196:199], v[94:97]
	v_mfma_f32_16x16x32_bf16 v[86:89], v[172:175], v[204:207], v[86:89]
	v_mfma_f32_16x16x32_bf16 v[78:81], v[180:183], v[204:207], v[78:81]
	v_mfma_f32_16x16x32_bf16 v[70:73], v[172:175], v[212:215], v[70:73]
	v_mfma_f32_16x16x32_bf16 v[66:69], v[180:183], v[212:215], v[66:69]
	s_barrier
	s_add_i32 s76, s69, s26
	v_lshl_add_u64 v[216:217], s[22:23], 0, v[132:133]
	s_mov_b32 m0, s76
	ds_read_b128 v[184:187], v154 offset:16384
	ds_read_b128 v[188:191], v154 offset:17408
	ds_read_b128 v[192:195], v154 offset:18432
	ds_read_b128 v[196:199], v154 offset:19456
	ds_read_b128 v[200:203], v154 offset:20480
	ds_read_b128 v[204:207], v154 offset:21504
	ds_read_b128 v[208:211], v154 offset:22528
	ds_read_b128 v[212:215], v154 offset:23552
	global_load_lds_dwordx4 v132, s[22:23]
	s_add_i32 m0, s76, 0x2000
	s_add_u32 s76, s22, 0x10000
	v_lshl_add_u64 v[218:219], s[22:23], 0, v[136:137]
	s_addc_u32 s77, s23, 0
	s_add_i32 s78, s70, s26
	global_load_lds_dwordx4 v136, s[22:23]
	s_mov_b32 m0, s78
	v_lshl_add_u64 v[222:223], s[24:25], 0, v[134:135]
	global_load_lds_dwordx4 v132, s[76:77]
	s_add_i32 m0, s78, 0x2000
	s_nop 0
	global_load_lds_dwordx4 v136, s[76:77]
	v_lshl_add_u64 v[220:221], s[24:25], 0, v[130:131]
	s_mov_b32 m0, s27
	s_nop 0
	global_load_lds_dwordx4 v130, s[24:25]
	s_mov_b32 m0, s28
	s_nop 0
	global_load_lds_dwordx4 v134, s[24:25]
	s_waitcnt vmcnt(8) lgkmcnt(0)
	s_barrier
; #define PG8_STAGE(bufoff, gbase, voff) do { _Pragma("unroll") for (int _i = 0; _i < 2; ++_i) \
;         __builtin_amdgcn_global_load_lds((const unsigned*)((const char*)(gbase) + (voff)[_i]), (PG8_LAS unsigned*)(lds + (bufoff) + ldsw + _i * 8192), 16, 0, 0); } while (0)
; #define PG8_LDA(dst, b, h) do { _Pragma("unroll") for (int m = 0; m < 4; ++m) _Pragma("unroll") for (int k = 0; k < 2; ++k) dst[m][k] = *(const PG8_LAS bf16x8*)(lds + PG8_SA(b, h) + aoff + m * 2048 + k * 1024); } while (0)
; #define PG8_LDB(dst, b, h) do { _Pragma("unroll") for (int n = 0; n < 2; ++n) _Pragma("unroll") for (int k = 0; k < 2; ++k) dst[n][k] = *(const PG8_LAS bf16x8*)(lds + PG8_SB(b, h) + boff + n * 2048 + k * 1024); } while (0)
; #define PG8_MMA(ai, bj, At, Bt) do { __builtin_amdgcn_s_setprio(1); _Pragma("unroll") for (int m = 0; m < 4; ++m) _Pragma("unroll") for (int n = 0; n < 2; ++n) _Pragma("unroll") for (int k = 0; k < 2; ++k) \
;         acc[ai][bj][m][n] = __builtin_amdgcn_mfma_f32_16x16x32_bf16(Bt[n][k], At[m][k], acc[ai][bj][m][n], 0, 0, 0); __builtin_amdgcn_s_setprio(0); } while (0)
; #define PG8_WAIT_V(n) asm volatile("s_waitcnt vmcnt(" #n ")" ::: "memory")
; #define PG8_WAIT_L(n) asm volatile("s_waitcnt lgkmcnt(" #n ")" ::: "memory")
; #define PG8_BAR __builtin_amdgcn_s_barrier()
; #define PG8_SCHED __builtin_amdgcn_sched_barrier(0)
; template <class Epi, class Sched, bool ALIGN_EPI = false, bool SP2 = false>
; __device__ __forceinline__ void gemm_phase(PG8_LAS unsigned char* lds, const Gemm g, const Sched& S, const Epi& E) {
;     ...
;             PG8_WAIT_V(8); PG8_WAIT_L(0); PG8_BAR; PG8_MMA(1, 0, At, B0); PG8_MMA(1, 1, At, B1); PG8_BAR; PG8_SCHED;
;             PG8_LDB(B0, 1, 0); PG8_LDB(B1, 1, 1); PG8_SCHED; PG8_LDA(At, 1, 0); PG8_STAGE(PG8_SA(0, 1), a2 + hstep, voffA);
;             PG8_WAIT_V(8); PG8_WAIT_L(0); PG8_BAR; PG8_MMA(0, 0, At, B0); PG8_MMA(0, 1, At, B1); PG8_BAR; PG8_SCHED;
	v_mfma_f32_16x16x32_bf16 v[62:65], v[146:149], v[184:187], 0
	v_mfma_f32_16x16x32_bf16 v[58:61], v[160:163], v[184:187], 0
	v_mfma_f32_16x16x32_bf16 v[50:53], v[146:149], v[192:195], 0
	v_mfma_f32_16x16x32_bf16 v[42:45], v[160:163], v[192:195], 0
	v_mfma_f32_16x16x32_bf16 v[34:37], v[146:149], v[200:203], 0
	v_mfma_f32_16x16x32_bf16 v[26:29], v[160:163], v[200:203], 0
	v_mfma_f32_16x16x32_bf16 v[18:21], v[146:149], v[208:211], 0
	v_mfma_f32_16x16x32_bf16 v[10:13], v[160:163], v[208:211], 0
	v_mfma_f32_16x16x32_bf16 v[62:65], v[156:159], v[188:191], v[62:65]
	v_mfma_f32_16x16x32_bf16 v[58:61], v[164:167], v[188:191], v[58:61]
	v_mfma_f32_16x16x32_bf16 v[50:53], v[156:159], v[196:199], v[50:53]
	v_mfma_f32_16x16x32_bf16 v[42:45], v[164:167], v[196:199], v[42:45]
	v_mfma_f32_16x16x32_bf16 v[34:37], v[156:159], v[204:207], v[34:37]
	v_mfma_f32_16x16x32_bf16 v[26:29], v[164:167], v[204:207], v[26:29]
	v_mfma_f32_16x16x32_bf16 v[18:21], v[156:159], v[212:215], v[18:21]
	v_mfma_f32_16x16x32_bf16 v[10:13], v[164:167], v[212:215], v[10:13]
	v_mfma_f32_16x16x32_bf16 v[54:57], v[168:171], v[184:187], 0
	v_mfma_f32_16x16x32_bf16 v[46:49], v[176:179], v[184:187], 0
	v_mfma_f32_16x16x32_bf16 v[38:41], v[168:171], v[192:195], 0
	v_mfma_f32_16x16x32_bf16 v[30:33], v[176:179], v[192:195], 0
	v_mfma_f32_16x16x32_bf16 v[22:25], v[168:171], v[200:203], 0
	v_mfma_f32_16x16x32_bf16 v[14:17], v[176:179], v[200:203], 0
	v_mfma_f32_16x16x32_bf16 v[6:9], v[168:171], v[208:211], 0
	v_mfma_f32_16x16x32_bf16 v[2:5], v[176:179], v[208:211], 0
	v_mfma_f32_16x16x32_bf16 v[54:57], v[172:175], v[188:191], v[54:57]
	v_mfma_f32_16x16x32_bf16 v[46:49], v[180:183], v[188:191], v[46:49]
	v_mfma_f32_16x16x32_bf16 v[38:41], v[172:175], v[196:199], v[38:41]
	v_mfma_f32_16x16x32_bf16 v[30:33], v[180:183], v[196:199], v[30:33]
	v_mfma_f32_16x16x32_bf16 v[22:25], v[172:175], v[204:207], v[22:25]
	v_mfma_f32_16x16x32_bf16 v[14:17], v[180:183], v[204:207], v[14:17]
	v_mfma_f32_16x16x32_bf16 v[6:9], v[172:175], v[212:215], v[6:9]
	v_mfma_f32_16x16x32_bf16 v[2:5], v[180:183], v[212:215], v[2:5]
	s_barrier
	s_add_i32 s76, 0, 0x18000
	v_add_u32_e32 v155, s76, v150
	s_add_i32 s77, 0, 0x1c000
	ds_read_b128 v[146:149], v155
	ds_read_b128 v[156:159], v155 offset:1024
	ds_read_b128 v[160:163], v155 offset:2048
	ds_read_b128 v[164:167], v155 offset:3072
	v_add_u32_e32 v155, s77, v150
	ds_read_b128 v[168:171], v155
	ds_read_b128 v[172:175], v155 offset:1024
	ds_read_b128 v[176:179], v155 offset:2048
	ds_read_b128 v[180:183], v155 offset:3072
	s_add_u32 s24, s24, 0x40000
	s_addc_u32 s25, s25, 0
	s_mov_b32 m0, s29
	ds_read_b128 v[184:187], v154 offset:32768
	ds_read_b128 v[188:191], v154 offset:33792
	ds_read_b128 v[192:195], v154 offset:34816
	ds_read_b128 v[196:199], v154 offset:35840
	ds_read_b128 v[200:203], v154 offset:36864
	ds_read_b128 v[204:207], v154 offset:37888
	ds_read_b128 v[208:211], v154 offset:38912
	ds_read_b128 v[212:215], v154 offset:39936
	global_load_lds_dwordx4 v130, s[24:25]
	s_mov_b32 m0, s30
	s_nop 0
	global_load_lds_dwordx4 v134, s[24:25]
	s_waitcnt vmcnt(8) lgkmcnt(0)
	s_barrier
	v_mfma_f32_16x16x32_bf16 v[126:129], v[146:149], v[184:187], v[126:129]
	v_mfma_f32_16x16x32_bf16 v[122:125], v[160:163], v[184:187], v[122:125]
	v_mfma_f32_16x16x32_bf16 v[114:117], v[146:149], v[192:195], v[114:117]
	v_mfma_f32_16x16x32_bf16 v[106:109], v[160:163], v[192:195], v[106:109]
	v_mfma_f32_16x16x32_bf16 v[98:101], v[146:149], v[200:203], v[98:101]
	v_mfma_f32_16x16x32_bf16 v[90:93], v[160:163], v[200:203], v[90:93]
	v_mfma_f32_16x16x32_bf16 v[82:85], v[146:149], v[208:211], v[82:85]
	v_mfma_f32_16x16x32_bf16 v[74:77], v[160:163], v[208:211], v[74:77]
	v_mfma_f32_16x16x32_bf16 v[126:129], v[156:159], v[188:191], v[126:129]
	v_mfma_f32_16x16x32_bf16 v[122:125], v[164:167], v[188:191], v[122:125]
	v_mfma_f32_16x16x32_bf16 v[114:117], v[156:159], v[196:199], v[114:117]
	v_mfma_f32_16x16x32_bf16 v[106:109], v[164:167], v[196:199], v[106:109]
	v_mfma_f32_16x16x32_bf16 v[98:101], v[156:159], v[204:207], v[98:101]
	v_mfma_f32_16x16x32_bf16 v[90:93], v[164:167], v[204:207], v[90:93]
	v_mfma_f32_16x16x32_bf16 v[82:85], v[156:159], v[212:215], v[82:85]
	v_mfma_f32_16x16x32_bf16 v[74:77], v[164:167], v[212:215], v[74:77]
	v_mfma_f32_16x16x32_bf16 v[118:121], v[168:171], v[184:187], v[118:121]
	v_mfma_f32_16x16x32_bf16 v[110:113], v[176:179], v[184:187], v[110:113]
	v_mfma_f32_16x16x32_bf16 v[102:105], v[168:171], v[192:195], v[102:105]
	v_mfma_f32_16x16x32_bf16 v[94:97], v[176:179], v[192:195], v[94:97]
	v_mfma_f32_16x16x32_bf16 v[86:89], v[168:171], v[200:203], v[86:89]
	v_mfma_f32_16x16x32_bf16 v[78:81], v[176:179], v[200:203], v[78:81]
	v_mfma_f32_16x16x32_bf16 v[70:73], v[168:171], v[208:211], v[70:73]
	v_mfma_f32_16x16x32_bf16 v[66:69], v[176:179], v[208:211], v[66:69]
	v_mfma_f32_16x16x32_bf16 v[118:121], v[172:175], v[188:191], v[118:121]
	v_mfma_f32_16x16x32_bf16 v[110:113], v[180:183], v[188:191], v[110:113]
	v_mfma_f32_16x16x32_bf16 v[102:105], v[172:175], v[196:199], v[102:105]
	v_mfma_f32_16x16x32_bf16 v[94:97], v[180:183], v[196:199], v[94:97]
	v_mfma_f32_16x16x32_bf16 v[86:89], v[172:175], v[204:207], v[86:89]
	v_mfma_f32_16x16x32_bf16 v[78:81], v[180:183], v[204:207], v[78:81]
	v_mfma_f32_16x16x32_bf16 v[70:73], v[172:175], v[212:215], v[70:73]
	v_mfma_f32_16x16x32_bf16 v[66:69], v[180:183], v[212:215], v[66:69]
	s_barrier
; #define PG8_STAGE(bufoff, gbase, voff) do { _Pragma("unroll") for (int _i = 0; _i < 2; ++_i) \
;         __builtin_amdgcn_global_load_lds((const unsigned*)((const char*)(gbase) + (voff)[_i]), (PG8_LAS unsigned*)(lds + (bufoff) + ldsw + _i * 8192), 16, 0, 0); } while (0)
; #define PG8_LDA(dst, b, h) do { _Pragma("unroll") for (int m = 0; m < 4; ++m) _Pragma("unroll") for (int k = 0; k < 2; ++k) dst[m][k] = *(const PG8_LAS bf16x8*)(lds + PG8_SA(b, h) + aoff + m * 2048 + k * 1024); } while (0)
; #define PG8_LDB(dst, b, h) do { _Pragma("unroll") for (int n = 0; n < 2; ++n) _Pragma("unroll") for (int k = 0; k < 2; ++k) dst[n][k] = *(const PG8_LAS bf16x8*)(lds + PG8_SB(b, h) + boff + n * 2048 + k * 1024); } while (0)
; #define PG8_MMA(ai, bj, At, Bt) do { __builtin_amdgcn_s_setprio(1); _Pragma("unroll") for (int m = 0; m < 4; ++m) _Pragma("unroll") for (int n = 0; n < 2; ++n) _Pragma("unroll") for (int k = 0; k < 2; ++k) \
;         acc[ai][bj][m][n] = __builtin_amdgcn_mfma_f32_16x16x32_bf16(Bt[n][k], At[m][k], acc[ai][bj][m][n], 0, 0, 0); __builtin_amdgcn_s_setprio(0); } while (0)
; #define PG8_WAIT_V(n) asm volatile("s_waitcnt vmcnt(" #n ")" ::: "memory")
; #define PG8_WAIT_L(n) asm volatile("s_waitcnt lgkmcnt(" #n ")" ::: "memory")
; #define PG8_BAR __builtin_amdgcn_s_barrier()
; #define PG8_SCHED __builtin_amdgcn_sched_barrier(0)
; template <class Epi, class Sched, bool ALIGN_EPI = false, bool SP2 = false>
; __device__ __forceinline__ void gemm_phase(PG8_LAS unsigned char* lds, const Gemm g, const Sched& S, const Epi& E) {
;     ...
;             PG8_LDB(B0, 0, 0); PG8_LDB(B1, 0, 1); PG8_SCHED; PG8_LDA(At, 0, 0); PG8_STAGE(PG8_SA(1, 1), a1 + hstep, voffA);
;             PG8_WAIT_V(8); PG8_WAIT_L(0); PG8_BAR; PG8_MMA(0, 0, At, B0); PG8_MMA(0, 1, At, B1); PG8_BAR; PG8_SCHED;
;     ...
;             PG8_LDA(At, 1, 1); PG8_STAGE(PG8_SB(1, 0), b3, voffB); PG8_STAGE(PG8_SB(1, 1), b3 + hstepB, voffB); PG8_STAGE(PG8_SA(1, 0), a3, voffA);
;             PG8_WAIT_V(8); PG8_WAIT_L(0); PG8_BAR; PG8_MMA(1, 0, At, B0); PG8_MMA(1, 1, At, B1); PG8_BAR; PG8_SCHED;
	s_add_i32 s24, s76, s26
	v_lshl_add_u64 v[216:217], v[216:217], 0, s[6:7]
	s_mov_b32 m0, s24
	ds_read_b128 v[184:187], v154 offset:49152
	ds_read_b128 v[188:191], v154 offset:50176
	ds_read_b128 v[192:195], v154 offset:51200
	ds_read_b128 v[196:199], v154 offset:52224
	ds_read_b128 v[200:203], v154 offset:53248
	ds_read_b128 v[204:207], v154 offset:54272
	ds_read_b128 v[208:211], v154 offset:55296
	ds_read_b128 v[212:215], v154 offset:56320
	global_load_lds_dwordx4 v[216:217], off
	s_add_i32 m0, s24, 0x2000
	s_add_u32 s22, s22, 0x10080
	v_lshl_add_u64 v[216:217], v[218:219], 0, s[6:7]
	s_addc_u32 s23, s23, 0
	s_add_i32 s24, s77, s26
	global_load_lds_dwordx4 v[216:217], off
	s_mov_b32 m0, s24
	s_nop 0
	global_load_lds_dwordx4 v132, s[22:23]
	s_add_i32 m0, s24, 0x2000
	s_nop 0
	global_load_lds_dwordx4 v136, s[22:23]
	v_lshl_add_u64 v[216:217], v[220:221], 0, s[6:7]
	s_mov_b32 m0, s33
	s_nop 0
	global_load_lds_dwordx4 v[216:217], off
	v_lshl_add_u64 v[216:217], v[222:223], 0, s[6:7]
	s_mov_b32 m0, s34
	s_nop 0
	global_load_lds_dwordx4 v[216:217], off
	s_waitcnt vmcnt(8) lgkmcnt(0)
	s_barrier
	v_mfma_f32_16x16x32_bf16 v[62:65], v[146:149], v[184:187], v[62:65]
	v_mfma_f32_16x16x32_bf16 v[58:61], v[160:163], v[184:187], v[58:61]
	v_mfma_f32_16x16x32_bf16 v[50:53], v[146:149], v[192:195], v[50:53]
	v_mfma_f32_16x16x32_bf16 v[42:45], v[160:163], v[192:195], v[42:45]
	v_mfma_f32_16x16x32_bf16 v[34:37], v[146:149], v[200:203], v[34:37]
	v_mfma_f32_16x16x32_bf16 v[26:29], v[160:163], v[200:203], v[26:29]
	v_mfma_f32_16x16x32_bf16 v[18:21], v[146:149], v[208:211], v[18:21]
	v_mfma_f32_16x16x32_bf16 v[10:13], v[160:163], v[208:211], v[10:13]
	v_mfma_f32_16x16x32_bf16 v[62:65], v[156:159], v[188:191], v[62:65]
	v_mfma_f32_16x16x32_bf16 v[58:61], v[164:167], v[188:191], v[58:61]
	v_mfma_f32_16x16x32_bf16 v[50:53], v[156:159], v[196:199], v[50:53]
	v_mfma_f32_16x16x32_bf16 v[42:45], v[164:167], v[196:199], v[42:45]
	v_mfma_f32_16x16x32_bf16 v[34:37], v[156:159], v[204:207], v[34:37]
	v_mfma_f32_16x16x32_bf16 v[26:29], v[164:167], v[204:207], v[26:29]
	v_mfma_f32_16x16x32_bf16 v[18:21], v[156:159], v[212:215], v[18:21]
	v_mfma_f32_16x16x32_bf16 v[10:13], v[164:167], v[212:215], v[10:13]
	v_mfma_f32_16x16x32_bf16 v[54:57], v[168:171], v[184:187], v[54:57]
	v_mfma_f32_16x16x32_bf16 v[46:49], v[176:179], v[184:187], v[46:49]
	v_mfma_f32_16x16x32_bf16 v[38:41], v[168:171], v[192:195], v[38:41]
	v_mfma_f32_16x16x32_bf16 v[30:33], v[176:179], v[192:195], v[30:33]
	v_mfma_f32_16x16x32_bf16 v[22:25], v[168:171], v[200:203], v[22:25]
	v_mfma_f32_16x16x32_bf16 v[14:17], v[176:179], v[200:203], v[14:17]
	v_mfma_f32_16x16x32_bf16 v[6:9], v[168:171], v[208:211], v[6:9]
	v_mfma_f32_16x16x32_bf16 v[2:5], v[176:179], v[208:211], v[2:5]
	v_mfma_f32_16x16x32_bf16 v[54:57], v[172:175], v[188:191], v[54:57]
	v_mfma_f32_16x16x32_bf16 v[46:49], v[180:183], v[188:191], v[46:49]
	v_mfma_f32_16x16x32_bf16 v[38:41], v[172:175], v[196:199], v[38:41]
	v_mfma_f32_16x16x32_bf16 v[30:33], v[180:183], v[196:199], v[30:33]
	v_mfma_f32_16x16x32_bf16 v[22:25], v[172:175], v[204:207], v[22:25]
	v_mfma_f32_16x16x32_bf16 v[14:17], v[180:183], v[204:207], v[14:17]
	v_mfma_f32_16x16x32_bf16 v[6:9], v[172:175], v[212:215], v[6:9]
	v_mfma_f32_16x16x32_bf16 v[2:5], v[180:183], v[212:215], v[2:5]
	s_barrier
	s_add_i32 s75, s75, 2
	s_add_u32 s20, s20, 0x100
	s_addc_u32 s21, s21, 0
	s_add_u32 s73, s73, 0x100
	s_addc_u32 s74, s74, 0
	s_cmp_gt_u32 s75, 13
	s_cbranch_scc1 .Lpp0_x
.LBB0_192:
	ds_read_b128 v[146:149], v152
	ds_read_b128 v[156:159], v152 offset:1024
	ds_read_b128 v[160:163], v152 offset:2048
	ds_read_b128 v[164:167], v152 offset:3072
	ds_read_b128 v[168:171], v153
	ds_read_b128 v[172:175], v153 offset:1024
	ds_read_b128 v[176:179], v153 offset:2048
	ds_read_b128 v[180:183], v153 offset:3072
	s_add_u32 s22, s20, 0xfffc0080
	s_addc_u32 s23, s21, -1
	s_cmp_eq_u32 s75, 12
	s_cselect_b32 s25, s5, s23
	s_cselect_b32 s24, s13, s22
	s_cselect_b32 s23, s11, s74
	s_cselect_b32 s22, s19, s73
	v_lshl_add_u64 v[216:217], s[20:21], 0, v[138:139]
	s_add_i32 m0, s27, 0xc000
	ds_read_b128 v[184:187], v154
	ds_read_b128 v[188:191], v154 offset:1024
	ds_read_b128 v[192:195], v154 offset:2048
	ds_read_b128 v[196:199], v154 offset:3072
	ds_read_b128 v[200:203], v154 offset:4096
	ds_read_b128 v[204:207], v154 offset:5120
	ds_read_b128 v[208:211], v154 offset:6144
	ds_read_b128 v[212:215], v154 offset:7168
	global_load_lds_dwordx4 v[216:217], off
	v_lshl_add_u64 v[216:217], s[20:21], 0, v[140:141]
	s_add_i32 m0, s27, 0xe000
	s_nop 0
	global_load_lds_dwordx4 v[216:217], off
	s_waitcnt vmcnt(8) lgkmcnt(0)
	s_barrier
; #define PG8_STAGE(bufoff, gbase, voff) do { _Pragma("unroll") for (int _i = 0; _i < 2; ++_i) \
;         __builtin_amdgcn_global_load_lds((const unsigned*)((const char*)(gbase) + (voff)[_i]), (PG8_LAS unsigned*)(lds + (bufoff) + ldsw + _i * 8192), 16, 0, 0); } while (0)
; #define PG8_LDA(dst, b, h) do { _Pragma("unroll") for (int m = 0; m < 4; ++m) _Pragma("unroll") for (int k = 0; k < 2; ++k) dst[m][k] = *(const PG8_LAS bf16x8*)(lds + PG8_SA(b, h) + aoff + m * 2048 + k * 1024); } while (0)
; #define PG8_MMA(ai, bj, At, Bt) do { __builtin_amdgcn_s_setprio(1); _Pragma("unroll") for (int m = 0; m < 4; ++m) _Pragma("unroll") for (int n = 0; n < 2; ++n) _Pragma("unroll") for (int k = 0; k < 2; ++k) \
;         acc[ai][bj][m][n] = __builtin_amdgcn_mfma_f32_16x16x32_bf16(Bt[n][k], At[m][k], acc[ai][bj][m][n], 0, 0, 0); __builtin_amdgcn_s_setprio(0); } while (0)
; #define PG8_WAIT_V(n) asm volatile("s_waitcnt vmcnt(" #n ")" ::: "memory")
; #define PG8_WAIT_L(n) asm volatile("s_waitcnt lgkmcnt(" #n ")" ::: "memory")
; #define PG8_BAR __builtin_amdgcn_s_barrier()
; #define PG8_SCHED __builtin_amdgcn_sched_barrier(0)
; template <class Epi, class Sched, bool ALIGN_EPI = false, bool SP2 = false>
; __device__ __forceinline__ void gemm_phase(PG8_LAS unsigned char* lds, const Gemm g, const Sched& S, const Epi& E) {
;     ...
;             PG8_WAIT_V(8); PG8_WAIT_L(0); PG8_BAR; PG8_MMA(0, 0, At, B0); PG8_MMA(0, 1, At, B1); PG8_BAR; PG8_SCHED;
;             PG8_LDA(At, 0, 1); PG8_STAGE(PG8_SB(0, 0), b2, voffB); PG8_STAGE(PG8_SB(0, 1), b2 + hstepB, voffB); PG8_STAGE(PG8_SA(0, 0), a2, voffA);
;             PG8_WAIT_V(8); PG8_WAIT_L(0); PG8_BAR; PG8_MMA(1, 0, At, B0); PG8_MMA(1, 1, At, B1); PG8_BAR; PG8_SCHED;
	v_mfma_f32_16x16x32_bf16 v[126:129], v[146:149], v[184:187], v[126:129]
	v_mfma_f32_16x16x32_bf16 v[122:125], v[160:163], v[184:187], v[122:125]
	v_mfma_f32_16x16x32_bf16 v[114:117], v[146:149], v[192:195], v[114:117]
	v_mfma_f32_16x16x32_bf16 v[106:109], v[160:163], v[192:195], v[106:109]
	v_mfma_f32_16x16x32_bf16 v[98:101], v[146:149], v[200:203], v[98:101]
	v_mfma_f32_16x16x32_bf16 v[90:93], v[160:163], v[200:203], v[90:93]
	v_mfma_f32_16x16x32_bf16 v[82:85], v[146:149], v[208:211], v[82:85]
	v_mfma_f32_16x16x32_bf16 v[74:77], v[160:163], v[208:211], v[74:77]
	v_mfma_f32_16x16x32_bf16 v[126:129], v[156:159], v[188:191], v[126:129]
	v_mfma_f32_16x16x32_bf16 v[122:125], v[164:167], v[188:191], v[122:125]
	v_mfma_f32_16x16x32_bf16 v[114:117], v[156:159], v[196:199], v[114:117]
	v_mfma_f32_16x16x32_bf16 v[106:109], v[164:167], v[196:199], v[106:109]
	v_mfma_f32_16x16x32_bf16 v[98:101], v[156:159], v[204:207], v[98:101]
	v_mfma_f32_16x16x32_bf16 v[90:93], v[164:167], v[204:207], v[90:93]
	v_mfma_f32_16x16x32_bf16 v[82:85], v[156:159], v[212:215], v[82:85]
	v_mfma_f32_16x16x32_bf16 v[74:77], v[164:167], v[212:215], v[74:77]
	v_mfma_f32_16x16x32_bf16 v[118:121], v[168:171], v[184:187], v[118:121]
	v_mfma_f32_16x16x32_bf16 v[110:113], v[176:179], v[184:187], v[110:113]
	v_mfma_f32_16x16x32_bf16 v[102:105], v[168:171], v[192:195], v[102:105]
	v_mfma_f32_16x16x32_bf16 v[94:97], v[176:179], v[192:195], v[94:97]
	v_mfma_f32_16x16x32_bf16 v[86:89], v[168:171], v[200:203], v[86:89]
	v_mfma_f32_16x16x32_bf16 v[78:81], v[176:179], v[200:203], v[78:81]
	v_mfma_f32_16x16x32_bf16 v[70:73], v[168:171], v[208:211], v[70:73]
	v_mfma_f32_16x16x32_bf16 v[66:69], v[176:179], v[208:211], v[66:69]
	v_mfma_f32_16x16x32_bf16 v[118:121], v[172:175], v[188:191], v[118:121]
	v_mfma_f32_16x16x32_bf16 v[110:113], v[180:183], v[188:191], v[110:113]
	v_mfma_f32_16x16x32_bf16 v[102:105], v[172:175], v[196:199], v[102:105]
	v_mfma_f32_16x16x32_bf16 v[94:97], v[180:183], v[196:199], v[94:97]
	v_mfma_f32_16x16x32_bf16 v[86:89], v[172:175], v[204:207], v[86:89]
	v_mfma_f32_16x16x32_bf16 v[78:81], v[180:183], v[204:207], v[78:81]
	v_mfma_f32_16x16x32_bf16 v[70:73], v[172:175], v[212:215], v[70:73]
	v_mfma_f32_16x16x32_bf16 v[66:69], v[180:183], v[212:215], v[66:69]
	s_barrier
	s_add_i32 s76, s69, s26
	v_lshl_add_u64 v[216:217], s[22:23], 0, v[132:133]
	s_mov_b32 m0, s76
	ds_read_b128 v[184:187], v154 offset:16384
	ds_read_b128 v[188:191], v154 offset:17408
	ds_read_b128 v[192:195], v154 offset:18432
	ds_read_b128 v[196:199], v154 offset:19456
	ds_read_b128 v[200:203], v154 offset:20480
	ds_read_b128 v[204:207], v154 offset:21504
	ds_read_b128 v[208:211], v154 offset:22528
	ds_read_b128 v[212:215], v154 offset:23552
	global_load_lds_dwordx4 v132, s[22:23]
	s_add_i32 m0, s76, 0x2000
	s_add_u32 s76, s22, 0x10000
	v_lshl_add_u64 v[218:219], s[22:23], 0, v[136:137]
	s_addc_u32 s77, s23, 0
	s_add_i32 s78, s70, s26
	global_load_lds_dwordx4 v136, s[22:23]
	s_mov_b32 m0, s78
	v_lshl_add_u64 v[222:223], s[24:25], 0, v[134:135]
	global_load_lds_dwordx4 v132, s[76:77]
	s_add_i32 m0, s78, 0x2000
	s_nop 0
	global_load_lds_dwordx4 v136, s[76:77]
	v_lshl_add_u64 v[220:221], s[24:25], 0, v[130:131]
	s_mov_b32 m0, s27
	s_nop 0
	global_load_lds_dwordx4 v130, s[24:25]
	s_mov_b32 m0, s28
	s_nop 0
	global_load_lds_dwordx4 v134, s[24:25]
	s_waitcnt vmcnt(8) lgkmcnt(0)
	s_barrier
	v_mfma_f32_16x16x32_bf16 v[62:65], v[146:149], v[184:187], v[62:65]
	v_mfma_f32_16x16x32_bf16 v[58:61], v[160:163], v[184:187], v[58:61]
	v_mfma_f32_16x16x32_bf16 v[50:53], v[146:149], v[192:195], v[50:53]
	v_mfma_f32_16x16x32_bf16 v[42:45], v[160:163], v[192:195], v[42:45]
	v_mfma_f32_16x16x32_bf16 v[34:37], v[146:149], v[200:203], v[34:37]
	v_mfma_f32_16x16x32_bf16 v[26:29], v[160:163], v[200:203], v[26:29]
	v_mfma_f32_16x16x32_bf16 v[18:21], v[146:149], v[208:211], v[18:21]
	v_mfma_f32_16x16x32_bf16 v[10:13], v[160:163], v[208:211], v[10:13]
	v_mfma_f32_16x16x32_bf16 v[62:65], v[156:159], v[188:191], v[62:65]
	v_mfma_f32_16x16x32_bf16 v[58:61], v[164:167], v[188:191], v[58:61]
	v_mfma_f32_16x16x32_bf16 v[50:53], v[156:159], v[196:199], v[50:53]
	v_mfma_f32_16x16x32_bf16 v[42:45], v[164:167], v[196:199], v[42:45]
	v_mfma_f32_16x16x32_bf16 v[34:37], v[156:159], v[204:207], v[34:37]
	v_mfma_f32_16x16x32_bf16 v[26:29], v[164:167], v[204:207], v[26:29]
	v_mfma_f32_16x16x32_bf16 v[18:21], v[156:159], v[212:215], v[18:21]
	v_mfma_f32_16x16x32_bf16 v[10:13], v[164:167], v[212:215], v[10:13]
	v_mfma_f32_16x16x32_bf16 v[54:57], v[168:171], v[184:187], v[54:57]
	v_mfma_f32_16x16x32_bf16 v[46:49], v[176:179], v[184:187], v[46:49]
	v_mfma_f32_16x16x32_bf16 v[38:41], v[168:171], v[192:195], v[38:41]
	v_mfma_f32_16x16x32_bf16 v[30:33], v[176:179], v[192:195], v[30:33]
	v_mfma_f32_16x16x32_bf16 v[22:25], v[168:171], v[200:203], v[22:25]
	v_mfma_f32_16x16x32_bf16 v[14:17], v[176:179], v[200:203], v[14:17]
	v_mfma_f32_16x16x32_bf16 v[6:9], v[168:171], v[208:211], v[6:9]
	v_mfma_f32_16x16x32_bf16 v[2:5], v[176:179], v[208:211], v[2:5]
	v_mfma_f32_16x16x32_bf16 v[54:57], v[172:175], v[188:191], v[54:57]
	v_mfma_f32_16x16x32_bf16 v[46:49], v[180:183], v[188:191], v[46:49]
	v_mfma_f32_16x16x32_bf16 v[38:41], v[172:175], v[196:199], v[38:41]
	v_mfma_f32_16x16x32_bf16 v[30:33], v[180:183], v[196:199], v[30:33]
	v_mfma_f32_16x16x32_bf16 v[22:25], v[172:175], v[204:207], v[22:25]
	v_mfma_f32_16x16x32_bf16 v[14:17], v[180:183], v[204:207], v[14:17]
	v_mfma_f32_16x16x32_bf16 v[6:9], v[172:175], v[212:215], v[6:9]
	v_mfma_f32_16x16x32_bf16 v[2:5], v[180:183], v[212:215], v[2:5]
	s_barrier
; #define PG8_STAGE(bufoff, gbase, voff) do { _Pragma("unroll") for (int _i = 0; _i < 2; ++_i) \
;         __builtin_amdgcn_global_load_lds((const unsigned*)((const char*)(gbase) + (voff)[_i]), (PG8_LAS unsigned*)(lds + (bufoff) + ldsw + _i * 8192), 16, 0, 0); } while (0)
; #define PG8_LDA(dst, b, h) do { _Pragma("unroll") for (int m = 0; m < 4; ++m) _Pragma("unroll") for (int k = 0; k < 2; ++k) dst[m][k] = *(const PG8_LAS bf16x8*)(lds + PG8_SA(b, h) + aoff + m * 2048 + k * 1024); } while (0)
; #define PG8_LDB(dst, b, h) do { _Pragma("unroll") for (int n = 0; n < 2; ++n) _Pragma("unroll") for (int k = 0; k < 2; ++k) dst[n][k] = *(const PG8_LAS bf16x8*)(lds + PG8_SB(b, h) + boff + n * 2048 + k * 1024); } while (0)
; #define PG8_MMA(ai, bj, At, Bt) do { __builtin_amdgcn_s_setprio(1); _Pragma("unroll") for (int m = 0; m < 4; ++m) _Pragma("unroll") for (int n = 0; n < 2; ++n) _Pragma("unroll") for (int k = 0; k < 2; ++k) \
;         acc[ai][bj][m][n] = __builtin_amdgcn_mfma_f32_16x16x32_bf16(Bt[n][k], At[m][k], acc[ai][bj][m][n], 0, 0, 0); __builtin_amdgcn_s_setprio(0); } while (0)
; #define PG8_WAIT_V(n) asm volatile("s_waitcnt vmcnt(" #n ")" ::: "memory")
; #define PG8_WAIT_L(n) asm volatile("s_waitcnt lgkmcnt(" #n ")" ::: "memory")
; #define PG8_BAR __builtin_amdgcn_s_barrier()
; #define PG8_SCHED __builtin_amdgcn_sched_barrier(0)
; template <class Epi, class Sched, bool ALIGN_EPI = false, bool SP2 = false>
; __device__ __forceinline__ void gemm_phase(PG8_LAS unsigned char* lds, const Gemm g, const Sched& S, const Epi& E) {
;     ...
;             PG8_LDB(B0, 1, 0); PG8_LDB(B1, 1, 1); PG8_SCHED; PG8_LDA(At, 1, 0); PG8_STAGE(PG8_SA(0, 1), a2 + hstep, voffA);
;             PG8_WAIT_V(8); PG8_WAIT_L(0); PG8_BAR; PG8_MMA(0, 0, At, B0); PG8_MMA(0, 1, At, B1); PG8_BAR; PG8_SCHED;
;             PG8_LDA(At, 1, 1); PG8_STAGE(PG8_SB(1, 0), b3, voffB); PG8_STAGE(PG8_SB(1, 1), b3 + hstepB, voffB); PG8_STAGE(PG8_SA(1, 0), a3, voffA);
;             PG8_WAIT_V(8); PG8_WAIT_L(0); PG8_BAR; PG8_MMA(1, 0, At, B0); PG8_MMA(1, 1, At, B1); PG8_BAR; PG8_SCHED;
	s_add_i32 s76, 0, 0x18000
	v_add_u32_e32 v155, s76, v150
	s_add_i32 s77, 0, 0x1c000
	ds_read_b128 v[146:149], v155
	ds_read_b128 v[156:159], v155 offset:1024
	ds_read_b128 v[160:163], v155 offset:2048
	ds_read_b128 v[164:167], v155 offset:3072
	v_add_u32_e32 v155, s77, v150
	ds_read_b128 v[168:171], v155
	ds_read_b128 v[172:175], v155 offset:1024
	ds_read_b128 v[176:179], v155 offset:2048
	ds_read_b128 v[180:183], v155 offset:3072
	s_add_u32 s24, s24, 0x40000
	s_addc_u32 s25, s25, 0
	s_mov_b32 m0, s29
	ds_read_b128 v[184:187], v154 offset:32768
	ds_read_b128 v[188:191], v154 offset:33792
	ds_read_b128 v[192:195], v154 offset:34816
	ds_read_b128 v[196:199], v154 offset:35840
	ds_read_b128 v[200:203], v154 offset:36864
	ds_read_b128 v[204:207], v154 offset:37888
	ds_read_b128 v[208:211], v154 offset:38912
	ds_read_b128 v[212:215], v154 offset:39936
	global_load_lds_dwordx4 v130, s[24:25]
	s_mov_b32 m0, s30
	s_nop 0
	global_load_lds_dwordx4 v134, s[24:25]
	s_waitcnt vmcnt(8) lgkmcnt(0)
	s_barrier
	v_mfma_f32_16x16x32_bf16 v[126:129], v[146:149], v[184:187], v[126:129]
	v_mfma_f32_16x16x32_bf16 v[122:125], v[160:163], v[184:187], v[122:125]
	v_mfma_f32_16x16x32_bf16 v[114:117], v[146:149], v[192:195], v[114:117]
	v_mfma_f32_16x16x32_bf16 v[106:109], v[160:163], v[192:195], v[106:109]
	v_mfma_f32_16x16x32_bf16 v[98:101], v[146:149], v[200:203], v[98:101]
	v_mfma_f32_16x16x32_bf16 v[90:93], v[160:163], v[200:203], v[90:93]
	v_mfma_f32_16x16x32_bf16 v[82:85], v[146:149], v[208:211], v[82:85]
	v_mfma_f32_16x16x32_bf16 v[74:77], v[160:163], v[208:211], v[74:77]
	v_mfma_f32_16x16x32_bf16 v[126:129], v[156:159], v[188:191], v[126:129]
	v_mfma_f32_16x16x32_bf16 v[122:125], v[164:167], v[188:191], v[122:125]
	v_mfma_f32_16x16x32_bf16 v[114:117], v[156:159], v[196:199], v[114:117]
	v_mfma_f32_16x16x32_bf16 v[106:109], v[164:167], v[196:199], v[106:109]
	v_mfma_f32_16x16x32_bf16 v[98:101], v[156:159], v[204:207], v[98:101]
	v_mfma_f32_16x16x32_bf16 v[90:93], v[164:167], v[204:207], v[90:93]
	v_mfma_f32_16x16x32_bf16 v[82:85], v[156:159], v[212:215], v[82:85]
	v_mfma_f32_16x16x32_bf16 v[74:77], v[164:167], v[212:215], v[74:77]
	v_mfma_f32_16x16x32_bf16 v[118:121], v[168:171], v[184:187], v[118:121]
	v_mfma_f32_16x16x32_bf16 v[110:113], v[176:179], v[184:187], v[110:113]
	v_mfma_f32_16x16x32_bf16 v[102:105], v[168:171], v[192:195], v[102:105]
	v_mfma_f32_16x16x32_bf16 v[94:97], v[176:179], v[192:195], v[94:97]
	v_mfma_f32_16x16x32_bf16 v[86:89], v[168:171], v[200:203], v[86:89]
	v_mfma_f32_16x16x32_bf16 v[78:81], v[176:179], v[200:203], v[78:81]
	v_mfma_f32_16x16x32_bf16 v[70:73], v[168:171], v[208:211], v[70:73]
	v_mfma_f32_16x16x32_bf16 v[66:69], v[176:179], v[208:211], v[66:69]
	v_mfma_f32_16x16x32_bf16 v[118:121], v[172:175], v[188:191], v[118:121]
	v_mfma_f32_16x16x32_bf16 v[110:113], v[180:183], v[188:191], v[110:113]
	v_mfma_f32_16x16x32_bf16 v[102:105], v[172:175], v[196:199], v[102:105]
	v_mfma_f32_16x16x32_bf16 v[94:97], v[180:183], v[196:199], v[94:97]
	v_mfma_f32_16x16x32_bf16 v[86:89], v[172:175], v[204:207], v[86:89]
	v_mfma_f32_16x16x32_bf16 v[78:81], v[180:183], v[204:207], v[78:81]
	v_mfma_f32_16x16x32_bf16 v[70:73], v[172:175], v[212:215], v[70:73]
	v_mfma_f32_16x16x32_bf16 v[66:69], v[180:183], v[212:215], v[66:69]
	s_barrier
	s_add_i32 s24, s76, s26
	v_lshl_add_u64 v[216:217], v[216:217], 0, s[6:7]
	s_mov_b32 m0, s24
	ds_read_b128 v[184:187], v154 offset:49152
	ds_read_b128 v[188:191], v154 offset:50176
	ds_read_b128 v[192:195], v154 offset:51200
	ds_read_b128 v[196:199], v154 offset:52224
	ds_read_b128 v[200:203], v154 offset:53248
	ds_read_b128 v[204:207], v154 offset:54272
	ds_read_b128 v[208:211], v154 offset:55296
	ds_read_b128 v[212:215], v154 offset:56320
	global_load_lds_dwordx4 v[216:217], off
	s_add_i32 m0, s24, 0x2000
	s_add_u32 s22, s22, 0x10080
	v_lshl_add_u64 v[216:217], v[218:219], 0, s[6:7]
	s_addc_u32 s23, s23, 0
	s_add_i32 s24, s77, s26
	global_load_lds_dwordx4 v[216:217], off
	s_mov_b32 m0, s24
	s_nop 0
	global_load_lds_dwordx4 v132, s[22:23]
	s_add_i32 m0, s24, 0x2000
	s_nop 0
	global_load_lds_dwordx4 v136, s[22:23]
	v_lshl_add_u64 v[216:217], v[220:221], 0, s[6:7]
	s_mov_b32 m0, s33
	s_nop 0
	global_load_lds_dwordx4 v[216:217], off
	v_lshl_add_u64 v[216:217], v[222:223], 0, s[6:7]
	s_mov_b32 m0, s34
	s_nop 0
	global_load_lds_dwordx4 v[216:217], off
	s_waitcnt vmcnt(8) lgkmcnt(0)
	s_barrier
	v_mfma_f32_16x16x32_bf16 v[62:65], v[146:149], v[184:187], v[62:65]
	v_mfma_f32_16x16x32_bf16 v[58:61], v[160:163], v[184:187], v[58:61]
	v_mfma_f32_16x16x32_bf16 v[50:53], v[146:149], v[192:195], v[50:53]
	v_mfma_f32_16x16x32_bf16 v[42:45], v[160:163], v[192:195], v[42:45]
	v_mfma_f32_16x16x32_bf16 v[34:37], v[146:149], v[200:203], v[34:37]
	v_mfma_f32_16x16x32_bf16 v[26:29], v[160:163], v[200:203], v[26:29]
	v_mfma_f32_16x16x32_bf16 v[18:21], v[146:149], v[208:211], v[18:21]
	v_mfma_f32_16x16x32_bf16 v[10:13], v[160:163], v[208:211], v[10:13]
	v_mfma_f32_16x16x32_bf16 v[62:65], v[156:159], v[188:191], v[62:65]
	v_mfma_f32_16x16x32_bf16 v[58:61], v[164:167], v[188:191], v[58:61]
	v_mfma_f32_16x16x32_bf16 v[50:53], v[156:159], v[196:199], v[50:53]
	v_mfma_f32_16x16x32_bf16 v[42:45], v[164:167], v[196:199], v[42:45]
	v_mfma_f32_16x16x32_bf16 v[34:37], v[156:159], v[204:207], v[34:37]
	v_mfma_f32_16x16x32_bf16 v[26:29], v[164:167], v[204:207], v[26:29]
	v_mfma_f32_16x16x32_bf16 v[18:21], v[156:159], v[212:215], v[18:21]
	v_mfma_f32_16x16x32_bf16 v[10:13], v[164:167], v[212:215], v[10:13]
	v_mfma_f32_16x16x32_bf16 v[54:57], v[168:171], v[184:187], v[54:57]
	v_mfma_f32_16x16x32_bf16 v[46:49], v[176:179], v[184:187], v[46:49]
	v_mfma_f32_16x16x32_bf16 v[38:41], v[168:171], v[192:195], v[38:41]
	v_mfma_f32_16x16x32_bf16 v[30:33], v[176:179], v[192:195], v[30:33]
	v_mfma_f32_16x16x32_bf16 v[22:25], v[168:171], v[200:203], v[22:25]
	v_mfma_f32_16x16x32_bf16 v[14:17], v[176:179], v[200:203], v[14:17]
	v_mfma_f32_16x16x32_bf16 v[6:9], v[168:171], v[208:211], v[6:9]
	v_mfma_f32_16x16x32_bf16 v[2:5], v[176:179], v[208:211], v[2:5]
	v_mfma_f32_16x16x32_bf16 v[54:57], v[172:175], v[188:191], v[54:57]
	v_mfma_f32_16x16x32_bf16 v[46:49], v[180:183], v[188:191], v[46:49]
	v_mfma_f32_16x16x32_bf16 v[38:41], v[172:175], v[196:199], v[38:41]
	v_mfma_f32_16x16x32_bf16 v[30:33], v[180:183], v[196:199], v[30:33]
	v_mfma_f32_16x16x32_bf16 v[22:25], v[172:175], v[204:207], v[22:25]
	v_mfma_f32_16x16x32_bf16 v[14:17], v[180:183], v[204:207], v[14:17]
	v_mfma_f32_16x16x32_bf16 v[6:9], v[172:175], v[212:215], v[6:9]
	v_mfma_f32_16x16x32_bf16 v[2:5], v[180:183], v[212:215], v[2:5]
	s_barrier
	s_add_i32 s75, s75, 2
	s_add_u32 s20, s20, 0x100
	s_addc_u32 s21, s21, 0
	s_add_u32 s73, s73, 0x100
	s_addc_u32 s74, s74, 0
	s_cmp_gt_u32 s75, 13
	s_cbranch_scc0 .LBB0_192

; __device__ __forceinline__ unsigned xb_ld(unsigned* p)              { return __hip_atomic_load(p, __ATOMIC_RELAXED, __HIP_MEMORY_SCOPE_AGENT); }
; __device__ __forceinline__ unsigned xb_add(unsigned* p, unsigned v) { return __hip_atomic_fetch_add(p, v, __ATOMIC_RELAXED, __HIP_MEMORY_SCOPE_AGENT); }
; #define XB_SPIN(cond, bar) do { unsigned _sp = 0; while (cond) { __builtin_amdgcn_s_sleep(1); \
;     if ((++_sp & 255u) == 0u) { if (xb_ld(&(bar)[XB_TMO])) break; if (_sp > XB_SPIN_CAP) { atomicAdd(&(bar)[XB_TMO], 1u); break; } } } } while (0)
; __device__ __forceinline__ void xcd_barrier(const XcdBarrier& b) {
;     ...
;             else XB_SPIN(xb_ld(&bar[XB_TOPGEN]) == tg, bar);
;             asm volatile("" ::: "memory");
;             xb_add(&bar[XB_XGEN(b.x)], 1u);
;             asm volatile("s_waitcnt vmcnt(0)" ::: "memory");
;         } else {
;             XB_SPIN(xb_ld(&bar[XB_XGEN(b.x)]) == gen, bar);
.Lgb_spin1:
	global_load_dword v4, v3, s[88:89] offset:1024 sc1
	s_waitcnt vmcnt(0)
	v_cmp_ne_u32_e32 vcc, 0, v4
	s_cmp_eq_u32 vcc_lo, -1
	s_cbranch_scc1 .Lgb_done1
	s_add_i32 s100, s100, 1
	s_cmp_lt_u32 s100, 0x40000
	s_cbranch_scc1 .Lgb_spin1

; __device__ __forceinline__ unsigned xb_ld(unsigned* p)              { return __hip_atomic_load(p, __ATOMIC_RELAXED, __HIP_MEMORY_SCOPE_AGENT); }
; __device__ __forceinline__ unsigned xb_add(unsigned* p, unsigned v) { return __hip_atomic_fetch_add(p, v, __ATOMIC_RELAXED, __HIP_MEMORY_SCOPE_AGENT); }
; #define XB_SPIN(cond, bar) do { unsigned _sp = 0; while (cond) { __builtin_amdgcn_s_sleep(1); \
;     if ((++_sp & 255u) == 0u) { if (xb_ld(&(bar)[XB_TMO])) break; if (_sp > XB_SPIN_CAP) { atomicAdd(&(bar)[XB_TMO], 1u); break; } } } } while (0)
; __device__ __forceinline__ void xcd_barrier(const XcdBarrier& b) {
;     ...
;             else XB_SPIN(xb_ld(&bar[XB_TOPGEN]) == tg, bar);
;             asm volatile("" ::: "memory");
;             xb_add(&bar[XB_XGEN(b.x)], 1u);
;             asm volatile("s_waitcnt vmcnt(0)" ::: "memory");
;         } else {
;             XB_SPIN(xb_ld(&bar[XB_XGEN(b.x)]) == gen, bar);
.Lgb_spin2:
	global_load_dword v4, v3, s[88:89] offset:2048 sc1
	s_waitcnt vmcnt(0)
	v_cmp_ne_u32_e32 vcc, 0, v4
	s_cmp_eq_u32 vcc_lo, -1
	s_cbranch_scc1 .Lgb_done2
	s_add_i32 s100, s100, 1
	s_cmp_lt_u32 s100, 0x40000
	s_cbranch_scc1 .Lgb_spin2

; __device__ __forceinline__ unsigned xb_ld(unsigned* p)              { return __hip_atomic_load(p, __ATOMIC_RELAXED, __HIP_MEMORY_SCOPE_AGENT); }
; __device__ __forceinline__ unsigned xb_add(unsigned* p, unsigned v) { return __hip_atomic_fetch_add(p, v, __ATOMIC_RELAXED, __HIP_MEMORY_SCOPE_AGENT); }
; #define XB_SPIN(cond, bar) do { unsigned _sp = 0; while (cond) { __builtin_amdgcn_s_sleep(1); \
;     if ((++_sp & 255u) == 0u) { if (xb_ld(&(bar)[XB_TMO])) break; if (_sp > XB_SPIN_CAP) { atomicAdd(&(bar)[XB_TMO], 1u); break; } } } } while (0)
; __device__ __forceinline__ void xcd_barrier(const XcdBarrier& b) {
;     ...
;             else XB_SPIN(xb_ld(&bar[XB_TOPGEN]) == tg, bar);
;             asm volatile("" ::: "memory");
;             xb_add(&bar[XB_XGEN(b.x)], 1u);
;             asm volatile("s_waitcnt vmcnt(0)" ::: "memory");
;         } else {
;             XB_SPIN(xb_ld(&bar[XB_XGEN(b.x)]) == gen, bar);
.Lgb_spin3:
	global_load_dword v4, v3, s[88:89] offset:3072 sc1
	s_waitcnt vmcnt(0)
	v_cmp_ne_u32_e32 vcc, 0, v4
	s_cmp_eq_u32 vcc_lo, -1
	s_cbranch_scc1 .Lgb_done3
	s_add_i32 s100, s100, 1
	s_cmp_lt_u32 s100, 0x40000
	s_cbranch_scc1 .Lgb_spin3

; #define PG8_STAGE(bufoff, gbase, voff) do { _Pragma("unroll") for (int _i = 0; _i < 2; ++_i) \
;         __builtin_amdgcn_global_load_lds((const unsigned*)((const char*)(gbase) + (voff)[_i]), (PG8_LAS unsigned*)(lds + (bufoff) + ldsw + _i * 8192), 16, 0, 0); } while (0)
; #define PG8_LDA(dst, b, h) do { _Pragma("unroll") for (int m = 0; m < 4; ++m) _Pragma("unroll") for (int k = 0; k < 2; ++k) dst[m][k] = *(const PG8_LAS bf16x8*)(lds + PG8_SA(b, h) + aoff + m * 2048 + k * 1024); } while (0)
; #define PG8_LDB(dst, b, h) do { _Pragma("unroll") for (int n = 0; n < 2; ++n) _Pragma("unroll") for (int k = 0; k < 2; ++k) dst[n][k] = *(const PG8_LAS bf16x8*)(lds + PG8_SB(b, h) + boff + n * 2048 + k * 1024); } while (0)
; #define PG8_MMA(ai, bj, At, Bt) do { __builtin_amdgcn_s_setprio(1); _Pragma("unroll") for (int m = 0; m < 4; ++m) _Pragma("unroll") for (int n = 0; n < 2; ++n) _Pragma("unroll") for (int k = 0; k < 2; ++k) \
;         acc[ai][bj][m][n] = __builtin_amdgcn_mfma_f32_16x16x32_bf16(Bt[n][k], At[m][k], acc[ai][bj][m][n], 0, 0, 0); __builtin_amdgcn_s_setprio(0); } while (0)
; #define PG8_WAIT_V(n) asm volatile("s_waitcnt vmcnt(" #n ")" ::: "memory")
; #define PG8_WAIT_L(n) asm volatile("s_waitcnt lgkmcnt(" #n ")" ::: "memory")
; #define PG8_BAR __builtin_amdgcn_s_barrier()
; #define PG8_SCHED __builtin_amdgcn_sched_barrier(0)
; template <class Epi, class Sched, bool ALIGN_EPI = false, bool SP2 = false>
; __device__ __forceinline__ void gemm_phase(PG8_LAS unsigned char* lds, const Gemm g, const Sched& S, const Epi& E) {
;     ...
;             const bool last = (t == nt - 2);
;             const char* a1 = cA + (size_t)(t + 1) * kstep;
;             const char* a2 = last ? nA : cA + (size_t)(t + 2) * kstep; const char* b2 = last ? nB : cB + (size_t)(t + 2) * kstep;
;             const char* a3 = a2 + kstep; const char* b3 = b2 + kstep;
;             if (last && has_next) S.a_ready(nxt);
;             if constexpr (SP2) {
;             PG8_LDB(B0, 0, 0); PG8_LDB(B1, 0, 1); PG8_SCHED; PG8_LDA(At, 0, 0); PG8_STAGE(PG8_SA(1, 1), a1 + hstep, voffA);
;             PG8_WAIT_V(8); PG8_WAIT_L(0); PG8_BAR; PG8_MMA(0, 0, At, B0); PG8_MMA(0, 1, At, B1); PG8_BAR; PG8_SCHED;
;             PG8_LDA(At, 0, 1); PG8_STAGE(PG8_SB(0, 0), b2, voffB); PG8_STAGE(PG8_SB(0, 1), b2 + hstepB, voffB); PG8_STAGE(PG8_SA(0, 0), a2, voffA);
.LBB0_1094:
	v_add_u32_e32 v3, s46, v224
	ds_read_b128 v[134:137], v3
	ds_read_b128 v[138:141], v3 offset:1024
	ds_read_b128 v[142:145], v3 offset:2048
	ds_read_b128 v[146:149], v3 offset:3072
	v_add_u32_e32 v3, s47, v224
	s_add_u32 s26, s22, s24
	ds_read_b128 v[150:153], v3
	ds_read_b128 v[154:157], v3 offset:1024
	ds_read_b128 v[158:161], v3 offset:2048
	ds_read_b128 v[162:165], v3 offset:3072
	s_addc_u32 s27, s23, s25
	s_add_u32 s26, s26, 0x100
	s_addc_u32 s27, s27, 0
	s_add_u32 s58, s62, s24
	s_addc_u32 s59, s63, s25
	s_cmpk_eq_i32 s24, 0x700
	s_cselect_b32 s29, s17, s27
	s_cselect_b32 s28, s54, s26
	s_cselect_b32 s27, s56, s59
	s_cselect_b32 s26, s57, s58
	v_lshl_add_u64 v[4:5], v[214:215], 0, s[24:25]
	s_add_i32 m0, s33, 0xc000
	ds_read_b128 v[166:169], v226
	ds_read_b128 v[170:173], v226 offset:1024
	ds_read_b128 v[174:177], v226 offset:2048
	ds_read_b128 v[178:181], v226 offset:3072
	ds_read_b128 v[182:185], v226 offset:4096
	ds_read_b128 v[186:189], v226 offset:5120
	ds_read_b128 v[190:193], v226 offset:6144
	ds_read_b128 v[194:197], v226 offset:7168
	global_load_lds_dwordx4 v[4:5], off
	v_lshl_add_u64 v[4:5], v[216:217], 0, s[24:25]
	s_add_i32 m0, s33, 0xe000
	s_nop 0
	global_load_lds_dwordx4 v[4:5], off
	s_waitcnt vmcnt(8) lgkmcnt(0)
	s_barrier
	v_mfma_f32_16x16x32_bf16 v[130:133], v[134:137], v[166:169], v[130:133]
	v_mfma_f32_16x16x32_bf16 v[126:129], v[142:145], v[166:169], v[126:129]
	v_mfma_f32_16x16x32_bf16 v[114:117], v[134:137], v[174:177], v[114:117]
	v_mfma_f32_16x16x32_bf16 v[110:113], v[142:145], v[174:177], v[110:113]
	v_mfma_f32_16x16x32_bf16 v[98:101], v[134:137], v[182:185], v[98:101]
	v_mfma_f32_16x16x32_bf16 v[94:97], v[142:145], v[182:185], v[94:97]
	v_mfma_f32_16x16x32_bf16 v[82:85], v[134:137], v[190:193], v[82:85]
	v_mfma_f32_16x16x32_bf16 v[78:81], v[142:145], v[190:193], v[78:81]
	v_mfma_f32_16x16x32_bf16 v[130:133], v[138:141], v[170:173], v[130:133]
	v_mfma_f32_16x16x32_bf16 v[126:129], v[146:149], v[170:173], v[126:129]
	v_mfma_f32_16x16x32_bf16 v[114:117], v[138:141], v[178:181], v[114:117]
	v_mfma_f32_16x16x32_bf16 v[110:113], v[146:149], v[178:181], v[110:113]
	v_mfma_f32_16x16x32_bf16 v[98:101], v[138:141], v[186:189], v[98:101]
	v_mfma_f32_16x16x32_bf16 v[94:97], v[146:149], v[186:189], v[94:97]
	v_mfma_f32_16x16x32_bf16 v[82:85], v[138:141], v[194:197], v[82:85]
	v_mfma_f32_16x16x32_bf16 v[78:81], v[146:149], v[194:197], v[78:81]
	v_mfma_f32_16x16x32_bf16 v[122:125], v[150:153], v[166:169], v[122:125]
	v_mfma_f32_16x16x32_bf16 v[118:121], v[158:161], v[166:169], v[118:121]
	v_mfma_f32_16x16x32_bf16 v[106:109], v[150:153], v[174:177], v[106:109]
	v_mfma_f32_16x16x32_bf16 v[102:105], v[158:161], v[174:177], v[102:105]
	v_mfma_f32_16x16x32_bf16 v[90:93], v[150:153], v[182:185], v[90:93]
	v_mfma_f32_16x16x32_bf16 v[86:89], v[158:161], v[182:185], v[86:89]
	v_mfma_f32_16x16x32_bf16 v[74:77], v[150:153], v[190:193], v[74:77]
	v_mfma_f32_16x16x32_bf16 v[70:73], v[158:161], v[190:193], v[70:73]
	v_mfma_f32_16x16x32_bf16 v[122:125], v[154:157], v[170:173], v[122:125]
	v_mfma_f32_16x16x32_bf16 v[118:121], v[162:165], v[170:173], v[118:121]
	v_mfma_f32_16x16x32_bf16 v[106:109], v[154:157], v[178:181], v[106:109]
	v_mfma_f32_16x16x32_bf16 v[102:105], v[162:165], v[178:181], v[102:105]
	v_mfma_f32_16x16x32_bf16 v[90:93], v[154:157], v[186:189], v[90:93]
	v_mfma_f32_16x16x32_bf16 v[86:89], v[162:165], v[186:189], v[86:89]
	v_mfma_f32_16x16x32_bf16 v[74:77], v[154:157], v[194:197], v[74:77]
	v_mfma_f32_16x16x32_bf16 v[70:73], v[162:165], v[194:197], v[70:73]
	s_barrier
	s_add_i32 s58, s46, s31
	v_lshl_add_u64 v[218:219], s[26:27], 0, v[200:201]
	s_mov_b32 m0, s58
	ds_read_b128 v[166:169], v226 offset:16384
	ds_read_b128 v[170:173], v226 offset:17408
	ds_read_b128 v[174:177], v226 offset:18432
	ds_read_b128 v[178:181], v226 offset:19456
	ds_read_b128 v[182:185], v226 offset:20480
	ds_read_b128 v[186:189], v226 offset:21504
	ds_read_b128 v[190:193], v226 offset:22528
	ds_read_b128 v[194:197], v226 offset:23552
	global_load_lds_dwordx4 v200, s[26:27]
	s_add_i32 m0, s58, 0x2000
	s_add_u32 s58, s26, 0x10000
	v_lshl_add_u64 v[220:221], s[26:27], 0, v[204:205]
	s_addc_u32 s59, s27, 0
	s_add_i32 s65, s47, s31
	global_load_lds_dwordx4 v204, s[26:27]
	s_mov_b32 m0, s65
	v_lshl_add_u64 v[228:229], s[28:29], 0, v[198:199]
	global_load_lds_dwordx4 v200, s[58:59]
	s_add_i32 m0, s65, 0x2000
	v_lshl_add_u64 v[230:231], s[28:29], 0, v[202:203]
	global_load_lds_dwordx4 v204, s[58:59]
	s_mov_b32 m0, s33
	s_nop 0
	global_load_lds_dwordx4 v198, s[28:29]
	s_mov_b32 m0, s34
	s_nop 0
	global_load_lds_dwordx4 v202, s[28:29]
	s_waitcnt vmcnt(8) lgkmcnt(0)
	s_barrier
; #define PG8_STAGE(bufoff, gbase, voff) do { _Pragma("unroll") for (int _i = 0; _i < 2; ++_i) \
;         __builtin_amdgcn_global_load_lds((const unsigned*)((const char*)(gbase) + (voff)[_i]), (PG8_LAS unsigned*)(lds + (bufoff) + ldsw + _i * 8192), 16, 0, 0); } while (0)
; #define PG8_LDA(dst, b, h) do { _Pragma("unroll") for (int m = 0; m < 4; ++m) _Pragma("unroll") for (int k = 0; k < 2; ++k) dst[m][k] = *(const PG8_LAS bf16x8*)(lds + PG8_SA(b, h) + aoff + m * 2048 + k * 1024); } while (0)
; #define PG8_LDB(dst, b, h) do { _Pragma("unroll") for (int n = 0; n < 2; ++n) _Pragma("unroll") for (int k = 0; k < 2; ++k) dst[n][k] = *(const PG8_LAS bf16x8*)(lds + PG8_SB(b, h) + boff + n * 2048 + k * 1024); } while (0)
; #define PG8_MMA(ai, bj, At, Bt) do { __builtin_amdgcn_s_setprio(1); _Pragma("unroll") for (int m = 0; m < 4; ++m) _Pragma("unroll") for (int n = 0; n < 2; ++n) _Pragma("unroll") for (int k = 0; k < 2; ++k) \
;         acc[ai][bj][m][n] = __builtin_amdgcn_mfma_f32_16x16x32_bf16(Bt[n][k], At[m][k], acc[ai][bj][m][n], 0, 0, 0); __builtin_amdgcn_s_setprio(0); } while (0)
; #define PG8_WAIT_V(n) asm volatile("s_waitcnt vmcnt(" #n ")" ::: "memory")
; #define PG8_WAIT_L(n) asm volatile("s_waitcnt lgkmcnt(" #n ")" ::: "memory")
; #define PG8_BAR __builtin_amdgcn_s_barrier()
; #define PG8_SCHED __builtin_amdgcn_sched_barrier(0)
; template <class Epi, class Sched, bool ALIGN_EPI = false, bool SP2 = false>
; __device__ __forceinline__ void gemm_phase(PG8_LAS unsigned char* lds, const Gemm g, const Sched& S, const Epi& E) {
;     ...
;             PG8_WAIT_V(8); PG8_WAIT_L(0); PG8_BAR; PG8_MMA(1, 0, At, B0); PG8_MMA(1, 1, At, B1); PG8_BAR; PG8_SCHED;
;             PG8_LDB(B0, 1, 0); PG8_LDB(B1, 1, 1); PG8_SCHED; PG8_LDA(At, 1, 0); PG8_STAGE(PG8_SA(0, 1), a2 + hstep, voffA);
;             PG8_WAIT_V(8); PG8_WAIT_L(0); PG8_BAR; PG8_MMA(0, 0, At, B0); PG8_MMA(0, 1, At, B1); PG8_BAR; PG8_SCHED;
	v_mfma_f32_16x16x32_bf16 v[66:69], v[134:137], v[166:169], v[66:69]
	v_mfma_f32_16x16x32_bf16 v[62:65], v[142:145], v[166:169], v[62:65]
	v_mfma_f32_16x16x32_bf16 v[50:53], v[134:137], v[174:177], v[50:53]
	v_mfma_f32_16x16x32_bf16 v[46:49], v[142:145], v[174:177], v[46:49]
	v_mfma_f32_16x16x32_bf16 v[34:37], v[134:137], v[182:185], v[34:37]
	v_mfma_f32_16x16x32_bf16 v[30:33], v[142:145], v[182:185], v[30:33]
	v_mfma_f32_16x16x32_bf16 v[18:21], v[134:137], v[190:193], v[18:21]
	v_mfma_f32_16x16x32_bf16 v[14:17], v[142:145], v[190:193], v[14:17]
	v_mfma_f32_16x16x32_bf16 v[66:69], v[138:141], v[170:173], v[66:69]
	v_mfma_f32_16x16x32_bf16 v[62:65], v[146:149], v[170:173], v[62:65]
	v_mfma_f32_16x16x32_bf16 v[50:53], v[138:141], v[178:181], v[50:53]
	v_mfma_f32_16x16x32_bf16 v[46:49], v[146:149], v[178:181], v[46:49]
	v_mfma_f32_16x16x32_bf16 v[34:37], v[138:141], v[186:189], v[34:37]
	v_mfma_f32_16x16x32_bf16 v[30:33], v[146:149], v[186:189], v[30:33]
	v_mfma_f32_16x16x32_bf16 v[18:21], v[138:141], v[194:197], v[18:21]
	v_mfma_f32_16x16x32_bf16 v[14:17], v[146:149], v[194:197], v[14:17]
	v_mfma_f32_16x16x32_bf16 v[58:61], v[150:153], v[166:169], v[58:61]
	v_mfma_f32_16x16x32_bf16 v[54:57], v[158:161], v[166:169], v[54:57]
	v_mfma_f32_16x16x32_bf16 v[42:45], v[150:153], v[174:177], v[42:45]
	v_mfma_f32_16x16x32_bf16 v[38:41], v[158:161], v[174:177], v[38:41]
	v_mfma_f32_16x16x32_bf16 v[26:29], v[150:153], v[182:185], v[26:29]
	v_mfma_f32_16x16x32_bf16 v[22:25], v[158:161], v[182:185], v[22:25]
	v_mfma_f32_16x16x32_bf16 v[10:13], v[150:153], v[190:193], v[10:13]
	v_mfma_f32_16x16x32_bf16 v[4:7], v[158:161], v[190:193], v[6:9]
	v_mfma_f32_16x16x32_bf16 v[58:61], v[154:157], v[170:173], v[58:61]
	v_mfma_f32_16x16x32_bf16 v[54:57], v[162:165], v[170:173], v[54:57]
	v_mfma_f32_16x16x32_bf16 v[42:45], v[154:157], v[178:181], v[42:45]
	v_mfma_f32_16x16x32_bf16 v[38:41], v[162:165], v[178:181], v[38:41]
	v_mfma_f32_16x16x32_bf16 v[26:29], v[154:157], v[186:189], v[26:29]
	v_mfma_f32_16x16x32_bf16 v[22:25], v[162:165], v[186:189], v[22:25]
	v_mfma_f32_16x16x32_bf16 v[10:13], v[154:157], v[194:197], v[10:13]
	v_mfma_f32_16x16x32_bf16 v[4:7], v[162:165], v[194:197], v[4:7]
	s_barrier
	s_add_i32 s58, 0, 0x18000
	v_add_u32_e32 v3, s58, v224
	s_add_i32 s59, 0, 0x1c000
	ds_read_b128 v[134:137], v3
	ds_read_b128 v[138:141], v3 offset:1024
	ds_read_b128 v[142:145], v3 offset:2048
	ds_read_b128 v[146:149], v3 offset:3072
	v_add_u32_e32 v3, s59, v224
	ds_read_b128 v[150:153], v3
	ds_read_b128 v[154:157], v3 offset:1024
	ds_read_b128 v[158:161], v3 offset:2048
	ds_read_b128 v[162:165], v3 offset:3072
	s_add_u32 s28, s28, 0x40000
	s_addc_u32 s29, s29, 0
	s_mov_b32 m0, s35
	ds_read_b128 v[166:169], v226 offset:32768
	ds_read_b128 v[170:173], v226 offset:33792
	ds_read_b128 v[174:177], v226 offset:34816
	ds_read_b128 v[178:181], v226 offset:35840
	ds_read_b128 v[182:185], v226 offset:36864
	ds_read_b128 v[186:189], v226 offset:37888
	ds_read_b128 v[190:193], v226 offset:38912
	ds_read_b128 v[194:197], v226 offset:39936
	global_load_lds_dwordx4 v198, s[28:29]
	s_mov_b32 m0, s36
	s_nop 0
	global_load_lds_dwordx4 v202, s[28:29]
	s_waitcnt vmcnt(8) lgkmcnt(0)
	s_barrier
	v_mfma_f32_16x16x32_bf16 v[130:133], v[134:137], v[166:169], v[130:133]
	v_mfma_f32_16x16x32_bf16 v[126:129], v[142:145], v[166:169], v[126:129]
	v_mfma_f32_16x16x32_bf16 v[114:117], v[134:137], v[174:177], v[114:117]
	v_mfma_f32_16x16x32_bf16 v[110:113], v[142:145], v[174:177], v[110:113]
	v_mfma_f32_16x16x32_bf16 v[98:101], v[134:137], v[182:185], v[98:101]
	v_mfma_f32_16x16x32_bf16 v[94:97], v[142:145], v[182:185], v[94:97]
	v_mfma_f32_16x16x32_bf16 v[82:85], v[134:137], v[190:193], v[82:85]
	v_mfma_f32_16x16x32_bf16 v[78:81], v[142:145], v[190:193], v[78:81]
	v_mfma_f32_16x16x32_bf16 v[130:133], v[138:141], v[170:173], v[130:133]
	v_mfma_f32_16x16x32_bf16 v[126:129], v[146:149], v[170:173], v[126:129]
	v_mfma_f32_16x16x32_bf16 v[114:117], v[138:141], v[178:181], v[114:117]
	v_mfma_f32_16x16x32_bf16 v[110:113], v[146:149], v[178:181], v[110:113]
	v_mfma_f32_16x16x32_bf16 v[98:101], v[138:141], v[186:189], v[98:101]
	v_mfma_f32_16x16x32_bf16 v[94:97], v[146:149], v[186:189], v[94:97]
	v_mfma_f32_16x16x32_bf16 v[82:85], v[138:141], v[194:197], v[82:85]
	v_mfma_f32_16x16x32_bf16 v[78:81], v[146:149], v[194:197], v[78:81]
	v_mfma_f32_16x16x32_bf16 v[122:125], v[150:153], v[166:169], v[122:125]
	v_mfma_f32_16x16x32_bf16 v[118:121], v[158:161], v[166:169], v[118:121]
	v_mfma_f32_16x16x32_bf16 v[106:109], v[150:153], v[174:177], v[106:109]
	v_mfma_f32_16x16x32_bf16 v[102:105], v[158:161], v[174:177], v[102:105]
	v_mfma_f32_16x16x32_bf16 v[90:93], v[150:153], v[182:185], v[90:93]
	v_mfma_f32_16x16x32_bf16 v[86:89], v[158:161], v[182:185], v[86:89]
	v_mfma_f32_16x16x32_bf16 v[74:77], v[150:153], v[190:193], v[74:77]
	v_mfma_f32_16x16x32_bf16 v[70:73], v[158:161], v[190:193], v[70:73]
	v_mfma_f32_16x16x32_bf16 v[122:125], v[154:157], v[170:173], v[122:125]
	v_mfma_f32_16x16x32_bf16 v[118:121], v[162:165], v[170:173], v[118:121]
	v_mfma_f32_16x16x32_bf16 v[106:109], v[154:157], v[178:181], v[106:109]
	v_mfma_f32_16x16x32_bf16 v[102:105], v[162:165], v[178:181], v[102:105]
	v_mfma_f32_16x16x32_bf16 v[90:93], v[154:157], v[186:189], v[90:93]
	v_mfma_f32_16x16x32_bf16 v[86:89], v[162:165], v[186:189], v[86:89]
	v_mfma_f32_16x16x32_bf16 v[74:77], v[154:157], v[194:197], v[74:77]
	v_mfma_f32_16x16x32_bf16 v[70:73], v[162:165], v[194:197], v[70:73]
	s_barrier
; #define PG8_STAGE(bufoff, gbase, voff) do { _Pragma("unroll") for (int _i = 0; _i < 2; ++_i) \
;         __builtin_amdgcn_global_load_lds((const unsigned*)((const char*)(gbase) + (voff)[_i]), (PG8_LAS unsigned*)(lds + (bufoff) + ldsw + _i * 8192), 16, 0, 0); } while (0)
; #define PG8_LDA(dst, b, h) do { _Pragma("unroll") for (int m = 0; m < 4; ++m) _Pragma("unroll") for (int k = 0; k < 2; ++k) dst[m][k] = *(const PG8_LAS bf16x8*)(lds + PG8_SA(b, h) + aoff + m * 2048 + k * 1024); } while (0)
; #define PG8_MMA(ai, bj, At, Bt) do { __builtin_amdgcn_s_setprio(1); _Pragma("unroll") for (int m = 0; m < 4; ++m) _Pragma("unroll") for (int n = 0; n < 2; ++n) _Pragma("unroll") for (int k = 0; k < 2; ++k) \
;         acc[ai][bj][m][n] = __builtin_amdgcn_mfma_f32_16x16x32_bf16(Bt[n][k], At[m][k], acc[ai][bj][m][n], 0, 0, 0); __builtin_amdgcn_s_setprio(0); } while (0)
; #define PG8_WAIT_V(n) asm volatile("s_waitcnt vmcnt(" #n ")" ::: "memory")
; #define PG8_WAIT_L(n) asm volatile("s_waitcnt lgkmcnt(" #n ")" ::: "memory")
; #define PG8_BAR __builtin_amdgcn_s_barrier()
; #define PG8_SCHED __builtin_amdgcn_sched_barrier(0)
; template <class Epi, class Sched, bool ALIGN_EPI = false, bool SP2 = false>
; __device__ __forceinline__ void gemm_phase(PG8_LAS unsigned char* lds, const Gemm g, const Sched& S, const Epi& E) {
;     ...
;             PG8_LDA(At, 1, 1); PG8_STAGE(PG8_SB(1, 0), b3, voffB); PG8_STAGE(PG8_SB(1, 1), b3 + hstepB, voffB); PG8_STAGE(PG8_SA(1, 0), a3, voffA);
;             PG8_WAIT_V(8); PG8_WAIT_L(0); PG8_BAR; PG8_MMA(1, 0, At, B0); PG8_MMA(1, 1, At, B1); PG8_BAR; PG8_SCHED;
	s_add_i32 s28, s58, s31
	v_lshl_add_u64 v[8:9], v[218:219], 0, s[10:11]
	s_mov_b32 m0, s28
	ds_read_b128 v[166:169], v226 offset:49152
	ds_read_b128 v[170:173], v226 offset:50176
	ds_read_b128 v[174:177], v226 offset:51200
	ds_read_b128 v[178:181], v226 offset:52224
	ds_read_b128 v[182:185], v226 offset:53248
	ds_read_b128 v[186:189], v226 offset:54272
	ds_read_b128 v[190:193], v226 offset:55296
	ds_read_b128 v[194:197], v226 offset:56320
	global_load_lds_dwordx4 v[8:9], off
	s_add_i32 m0, s28, 0x2000
	s_add_u32 s26, s26, 0x10080
	v_lshl_add_u64 v[8:9], v[220:221], 0, s[10:11]
	s_addc_u32 s27, s27, 0
	s_add_i32 s28, s59, s31
	global_load_lds_dwordx4 v[8:9], off
	s_mov_b32 m0, s28
	s_nop 0
	global_load_lds_dwordx4 v200, s[26:27]
	s_add_i32 m0, s28, 0x2000
	s_nop 0
	global_load_lds_dwordx4 v204, s[26:27]
	v_lshl_add_u64 v[8:9], v[228:229], 0, s[10:11]
	s_mov_b32 m0, s39
	s_nop 0
	global_load_lds_dwordx4 v[8:9], off
	v_lshl_add_u64 v[8:9], v[230:231], 0, s[10:11]
	s_mov_b32 m0, s42
	s_nop 0
	global_load_lds_dwordx4 v[8:9], off
	s_waitcnt vmcnt(8) lgkmcnt(0)
	s_barrier
	v_mfma_f32_16x16x32_bf16 v[66:69], v[134:137], v[166:169], v[66:69]
	v_mfma_f32_16x16x32_bf16 v[62:65], v[142:145], v[166:169], v[62:65]
	v_mfma_f32_16x16x32_bf16 v[50:53], v[134:137], v[174:177], v[50:53]
	v_mfma_f32_16x16x32_bf16 v[46:49], v[142:145], v[174:177], v[46:49]
	v_mfma_f32_16x16x32_bf16 v[34:37], v[134:137], v[182:185], v[34:37]
	v_mfma_f32_16x16x32_bf16 v[30:33], v[142:145], v[182:185], v[30:33]
	v_mfma_f32_16x16x32_bf16 v[18:21], v[134:137], v[190:193], v[18:21]
	v_mfma_f32_16x16x32_bf16 v[14:17], v[142:145], v[190:193], v[14:17]
	v_mfma_f32_16x16x32_bf16 v[66:69], v[138:141], v[170:173], v[66:69]
	v_mfma_f32_16x16x32_bf16 v[62:65], v[146:149], v[170:173], v[62:65]
	v_mfma_f32_16x16x32_bf16 v[50:53], v[138:141], v[178:181], v[50:53]
	v_mfma_f32_16x16x32_bf16 v[46:49], v[146:149], v[178:181], v[46:49]
	v_mfma_f32_16x16x32_bf16 v[34:37], v[138:141], v[186:189], v[34:37]
	v_mfma_f32_16x16x32_bf16 v[30:33], v[146:149], v[186:189], v[30:33]
	v_mfma_f32_16x16x32_bf16 v[18:21], v[138:141], v[194:197], v[18:21]
	v_mfma_f32_16x16x32_bf16 v[14:17], v[146:149], v[194:197], v[14:17]
	v_mfma_f32_16x16x32_bf16 v[58:61], v[150:153], v[166:169], v[58:61]
	v_mfma_f32_16x16x32_bf16 v[54:57], v[158:161], v[166:169], v[54:57]
	v_mfma_f32_16x16x32_bf16 v[42:45], v[150:153], v[174:177], v[42:45]
	v_mfma_f32_16x16x32_bf16 v[38:41], v[158:161], v[174:177], v[38:41]
	v_mfma_f32_16x16x32_bf16 v[26:29], v[150:153], v[182:185], v[26:29]
	v_mfma_f32_16x16x32_bf16 v[22:25], v[158:161], v[182:185], v[22:25]
	v_mfma_f32_16x16x32_bf16 v[8:11], v[150:153], v[190:193], v[10:13]
	v_mfma_f32_16x16x32_bf16 v[4:7], v[158:161], v[190:193], v[4:7]
	v_mfma_f32_16x16x32_bf16 v[58:61], v[154:157], v[170:173], v[58:61]
	v_mfma_f32_16x16x32_bf16 v[54:57], v[162:165], v[170:173], v[54:57]
	v_mfma_f32_16x16x32_bf16 v[42:45], v[154:157], v[178:181], v[42:45]
	v_mfma_f32_16x16x32_bf16 v[38:41], v[162:165], v[178:181], v[38:41]
	v_mfma_f32_16x16x32_bf16 v[26:29], v[154:157], v[186:189], v[26:29]
	v_mfma_f32_16x16x32_bf16 v[22:25], v[162:165], v[186:189], v[22:25]
	v_mfma_f32_16x16x32_bf16 v[10:13], v[154:157], v[194:197], v[8:11]
	v_mfma_f32_16x16x32_bf16 v[6:9], v[162:165], v[194:197], v[4:7]
	s_barrier
	s_add_i32 s64, s64, 2
	s_add_u32 s24, s24, 0x100
	s_addc_u32 s25, s25, 0
	s_cmp_gt_u32 s64, 13
	s_cbranch_scc1 .LBB0_1097

; #define PG8_STAGE(bufoff, gbase, voff) do { _Pragma("unroll") for (int _i = 0; _i < 2; ++_i) \
;         __builtin_amdgcn_global_load_lds((const unsigned*)((const char*)(gbase) + (voff)[_i]), (PG8_LAS unsigned*)(lds + (bufoff) + ldsw + _i * 8192), 16, 0, 0); } while (0)
; #define PG8_LDA(dst, b, h) do { _Pragma("unroll") for (int m = 0; m < 4; ++m) _Pragma("unroll") for (int k = 0; k < 2; ++k) dst[m][k] = *(const PG8_LAS bf16x8*)(lds + PG8_SA(b, h) + aoff + m * 2048 + k * 1024); } while (0)
; #define PG8_LDB(dst, b, h) do { _Pragma("unroll") for (int n = 0; n < 2; ++n) _Pragma("unroll") for (int k = 0; k < 2; ++k) dst[n][k] = *(const PG8_LAS bf16x8*)(lds + PG8_SB(b, h) + boff + n * 2048 + k * 1024); } while (0)
; #define PG8_MMA(ai, bj, At, Bt) do { __builtin_amdgcn_s_setprio(1); _Pragma("unroll") for (int m = 0; m < 4; ++m) _Pragma("unroll") for (int n = 0; n < 2; ++n) _Pragma("unroll") for (int k = 0; k < 2; ++k) \
;         acc[ai][bj][m][n] = __builtin_amdgcn_mfma_f32_16x16x32_bf16(Bt[n][k], At[m][k], acc[ai][bj][m][n], 0, 0, 0); __builtin_amdgcn_s_setprio(0); } while (0)
; #define PG8_WAIT_V(n) asm volatile("s_waitcnt vmcnt(" #n ")" ::: "memory")
; #define PG8_WAIT_L(n) asm volatile("s_waitcnt lgkmcnt(" #n ")" ::: "memory")
; #define PG8_BAR __builtin_amdgcn_s_barrier()
; #define PG8_SCHED __builtin_amdgcn_sched_barrier(0)
; template <class Epi, class Sched, bool ALIGN_EPI = false, bool SP2 = false>
; __device__ __forceinline__ void gemm_phase(PG8_LAS unsigned char* lds, const Gemm g, const Sched& S, const Epi& E) {
;     ...
;             const bool last = (t == nt - 2);
;             const char* a1 = cA + (size_t)(t + 1) * kstep;
;             const char* a2 = last ? nA : cA + (size_t)(t + 2) * kstep; const char* b2 = last ? nB : cB + (size_t)(t + 2) * kstep;
;             const char* a3 = a2 + kstep; const char* b3 = b2 + kstep;
;             if (last && has_next) S.a_ready(nxt);
;             if constexpr (SP2) {
;             PG8_LDB(B0, 0, 0); PG8_LDB(B1, 0, 1); PG8_SCHED; PG8_LDA(At, 0, 0); PG8_STAGE(PG8_SA(1, 1), a1 + hstep, voffA);
;             PG8_WAIT_V(8); PG8_WAIT_L(0); PG8_BAR; PG8_MMA(0, 0, At, B0); PG8_MMA(0, 1, At, B1); PG8_BAR; PG8_SCHED;
;             PG8_LDA(At, 0, 1); PG8_STAGE(PG8_SB(0, 0), b2, voffB); PG8_STAGE(PG8_SB(0, 1), b2 + hstepB, voffB); PG8_STAGE(PG8_SA(0, 0), a2, voffA);
.LBB0_1180:
	v_add_u32_e32 v144, s55, v142
	ds_read_b128 v[154:157], v144
	ds_read_b128 v[158:161], v144 offset:1024
	ds_read_b128 v[162:165], v144 offset:2048
	ds_read_b128 v[166:169], v144 offset:3072
	v_add_u32_e32 v144, s56, v142
	s_add_u32 s34, s10, s28
	ds_read_b128 v[170:173], v144
	ds_read_b128 v[174:177], v144 offset:1024
	ds_read_b128 v[178:181], v144 offset:2048
	ds_read_b128 v[182:185], v144 offset:3072
	s_addc_u32 s35, s11, s29
	s_add_u32 s34, s34, 0x100
	s_addc_u32 s35, s35, 0
	s_add_u32 s61, s25, s28
	s_addc_u32 s62, s57, s29
	s_cmpk_eq_i32 s28, 0x700
	s_cselect_b32 s37, s21, s35
	s_cselect_b32 s36, s58, s34
	s_cselect_b32 s35, s19, s62
	s_cselect_b32 s34, s59, s61
	v_lshl_add_u64 v[144:145], v[138:139], 0, s[28:29]
	s_add_i32 m0, s39, 0xc000
	ds_read_b128 v[186:189], v143
	ds_read_b128 v[190:193], v143 offset:1024
	ds_read_b128 v[194:197], v143 offset:2048
	ds_read_b128 v[198:201], v143 offset:3072
	ds_read_b128 v[202:205], v143 offset:4096
	ds_read_b128 v[206:209], v143 offset:5120
	ds_read_b128 v[216:219], v143 offset:6144
	ds_read_b128 v[224:227], v143 offset:7168
	global_load_lds_dwordx4 v[144:145], off
	v_lshl_add_u64 v[144:145], v[140:141], 0, s[28:29]
	s_add_i32 m0, s39, 0xe000
	s_nop 0
	global_load_lds_dwordx4 v[144:145], off
	s_waitcnt vmcnt(8) lgkmcnt(0)
	s_barrier
	v_mfma_f32_16x16x32_bf16 v[150:153], v[154:157], v[186:189], v[150:153]
	v_mfma_f32_16x16x32_bf16 v[144:147], v[162:165], v[186:189], v[146:149]
	v_mfma_f32_16x16x32_bf16 v[110:113], v[154:157], v[194:197], v[110:113]
	v_mfma_f32_16x16x32_bf16 v[106:109], v[162:165], v[194:197], v[106:109]
	v_mfma_f32_16x16x32_bf16 v[94:97], v[154:157], v[202:205], v[94:97]
	v_mfma_f32_16x16x32_bf16 v[90:93], v[162:165], v[202:205], v[90:93]
	v_mfma_f32_16x16x32_bf16 v[78:81], v[154:157], v[216:219], v[78:81]
	v_mfma_f32_16x16x32_bf16 v[74:77], v[162:165], v[216:219], v[74:77]
	v_mfma_f32_16x16x32_bf16 v[150:153], v[158:161], v[190:193], v[150:153]
	v_mfma_f32_16x16x32_bf16 v[144:147], v[166:169], v[190:193], v[144:147]
	v_mfma_f32_16x16x32_bf16 v[110:113], v[158:161], v[198:201], v[110:113]
	v_mfma_f32_16x16x32_bf16 v[106:109], v[166:169], v[198:201], v[106:109]
	v_mfma_f32_16x16x32_bf16 v[94:97], v[158:161], v[206:209], v[94:97]
	v_mfma_f32_16x16x32_bf16 v[90:93], v[166:169], v[206:209], v[90:93]
	v_mfma_f32_16x16x32_bf16 v[78:81], v[158:161], v[224:227], v[78:81]
	v_mfma_f32_16x16x32_bf16 v[74:77], v[166:169], v[224:227], v[74:77]
	v_mfma_f32_16x16x32_bf16 v[118:121], v[170:173], v[186:189], v[118:121]
	v_mfma_f32_16x16x32_bf16 v[114:117], v[178:181], v[186:189], v[114:117]
	v_mfma_f32_16x16x32_bf16 v[102:105], v[170:173], v[194:197], v[102:105]
	v_mfma_f32_16x16x32_bf16 v[98:101], v[178:181], v[194:197], v[98:101]
	v_mfma_f32_16x16x32_bf16 v[86:89], v[170:173], v[202:205], v[86:89]
	v_mfma_f32_16x16x32_bf16 v[82:85], v[178:181], v[202:205], v[82:85]
	v_mfma_f32_16x16x32_bf16 v[70:73], v[170:173], v[216:219], v[70:73]
	v_mfma_f32_16x16x32_bf16 v[66:69], v[178:181], v[216:219], v[66:69]
	v_mfma_f32_16x16x32_bf16 v[118:121], v[174:177], v[190:193], v[118:121]
	v_mfma_f32_16x16x32_bf16 v[114:117], v[182:185], v[190:193], v[114:117]
	v_mfma_f32_16x16x32_bf16 v[102:105], v[174:177], v[198:201], v[102:105]
	v_mfma_f32_16x16x32_bf16 v[98:101], v[182:185], v[198:201], v[98:101]
	v_mfma_f32_16x16x32_bf16 v[86:89], v[174:177], v[206:209], v[86:89]
	v_mfma_f32_16x16x32_bf16 v[82:85], v[182:185], v[206:209], v[82:85]
	v_mfma_f32_16x16x32_bf16 v[70:73], v[174:177], v[224:227], v[70:73]
	v_mfma_f32_16x16x32_bf16 v[66:69], v[182:185], v[224:227], v[66:69]
	s_barrier
	s_add_i32 s61, s55, s38
	v_lshl_add_u64 v[210:211], s[34:35], 0, v[124:125]
	s_mov_b32 m0, s61
	ds_read_b128 v[186:189], v143 offset:16384
	ds_read_b128 v[190:193], v143 offset:17408
	ds_read_b128 v[194:197], v143 offset:18432
	ds_read_b128 v[198:201], v143 offset:19456
	ds_read_b128 v[202:205], v143 offset:20480
	ds_read_b128 v[206:209], v143 offset:21504
	ds_read_b128 v[216:219], v143 offset:22528
	ds_read_b128 v[224:227], v143 offset:23552
	global_load_lds_dwordx4 v124, s[34:35]
	s_add_i32 m0, s61, 0x2000
	s_add_u32 s62, s34, 0x10000
	v_lshl_add_u64 v[220:221], s[34:35], 0, v[128:129]
	s_addc_u32 s63, s35, 0
	s_add_i32 s61, s56, s38
	global_load_lds_dwordx4 v128, s[34:35]
	s_mov_b32 m0, s61
	v_lshl_add_u64 v[228:229], s[36:37], 0, v[122:123]
	global_load_lds_dwordx4 v124, s[62:63]
	v_lshl_add_u64 v[148:149], s[62:63], 0, v[128:129]
	s_add_i32 m0, s61, 0x2000
	v_lshl_add_u64 v[230:231], s[36:37], 0, v[126:127]
	global_load_lds_dwordx4 v128, s[62:63]
	s_mov_b32 m0, s39
	s_nop 0
	global_load_lds_dwordx4 v122, s[36:37]
	s_mov_b32 m0, s42
	s_nop 0
	global_load_lds_dwordx4 v126, s[36:37]
	s_waitcnt vmcnt(8) lgkmcnt(0)
	s_barrier
; #define PG8_STAGE(bufoff, gbase, voff) do { _Pragma("unroll") for (int _i = 0; _i < 2; ++_i) \
;         __builtin_amdgcn_global_load_lds((const unsigned*)((const char*)(gbase) + (voff)[_i]), (PG8_LAS unsigned*)(lds + (bufoff) + ldsw + _i * 8192), 16, 0, 0); } while (0)
; #define PG8_LDA(dst, b, h) do { _Pragma("unroll") for (int m = 0; m < 4; ++m) _Pragma("unroll") for (int k = 0; k < 2; ++k) dst[m][k] = *(const PG8_LAS bf16x8*)(lds + PG8_SA(b, h) + aoff + m * 2048 + k * 1024); } while (0)
; #define PG8_LDB(dst, b, h) do { _Pragma("unroll") for (int n = 0; n < 2; ++n) _Pragma("unroll") for (int k = 0; k < 2; ++k) dst[n][k] = *(const PG8_LAS bf16x8*)(lds + PG8_SB(b, h) + boff + n * 2048 + k * 1024); } while (0)
; #define PG8_MMA(ai, bj, At, Bt) do { __builtin_amdgcn_s_setprio(1); _Pragma("unroll") for (int m = 0; m < 4; ++m) _Pragma("unroll") for (int n = 0; n < 2; ++n) _Pragma("unroll") for (int k = 0; k < 2; ++k) \
;         acc[ai][bj][m][n] = __builtin_amdgcn_mfma_f32_16x16x32_bf16(Bt[n][k], At[m][k], acc[ai][bj][m][n], 0, 0, 0); __builtin_amdgcn_s_setprio(0); } while (0)
; #define PG8_WAIT_V(n) asm volatile("s_waitcnt vmcnt(" #n ")" ::: "memory")
; #define PG8_WAIT_L(n) asm volatile("s_waitcnt lgkmcnt(" #n ")" ::: "memory")
; #define PG8_BAR __builtin_amdgcn_s_barrier()
; #define PG8_SCHED __builtin_amdgcn_sched_barrier(0)
; template <class Epi, class Sched, bool ALIGN_EPI = false, bool SP2 = false>
; __device__ __forceinline__ void gemm_phase(PG8_LAS unsigned char* lds, const Gemm g, const Sched& S, const Epi& E) {
;     ...
;             PG8_WAIT_V(8); PG8_WAIT_L(0); PG8_BAR; PG8_MMA(1, 0, At, B0); PG8_MMA(1, 1, At, B1); PG8_BAR; PG8_SCHED;
;             PG8_LDB(B0, 1, 0); PG8_LDB(B1, 1, 1); PG8_SCHED; PG8_LDA(At, 1, 0); PG8_STAGE(PG8_SA(0, 1), a2 + hstep, voffA);
;             PG8_WAIT_V(8); PG8_WAIT_L(0); PG8_BAR; PG8_MMA(0, 0, At, B0); PG8_MMA(0, 1, At, B1); PG8_BAR; PG8_SCHED;
	v_mfma_f32_16x16x32_bf16 v[62:65], v[154:157], v[186:189], v[62:65]
	v_mfma_f32_16x16x32_bf16 v[58:61], v[162:165], v[186:189], v[58:61]
	v_mfma_f32_16x16x32_bf16 v[46:49], v[154:157], v[194:197], v[46:49]
	v_mfma_f32_16x16x32_bf16 v[42:45], v[162:165], v[194:197], v[42:45]
	v_mfma_f32_16x16x32_bf16 v[30:33], v[154:157], v[202:205], v[30:33]
	v_mfma_f32_16x16x32_bf16 v[26:29], v[162:165], v[202:205], v[26:29]
	v_mfma_f32_16x16x32_bf16 v[14:17], v[154:157], v[216:219], v[14:17]
	v_mfma_f32_16x16x32_bf16 v[10:13], v[162:165], v[216:219], v[10:13]
	v_mfma_f32_16x16x32_bf16 v[62:65], v[158:161], v[190:193], v[62:65]
	v_mfma_f32_16x16x32_bf16 v[58:61], v[166:169], v[190:193], v[58:61]
	v_mfma_f32_16x16x32_bf16 v[46:49], v[158:161], v[198:201], v[46:49]
	v_mfma_f32_16x16x32_bf16 v[42:45], v[166:169], v[198:201], v[42:45]
	v_mfma_f32_16x16x32_bf16 v[30:33], v[158:161], v[206:209], v[30:33]
	v_mfma_f32_16x16x32_bf16 v[26:29], v[166:169], v[206:209], v[26:29]
	v_mfma_f32_16x16x32_bf16 v[14:17], v[158:161], v[224:227], v[14:17]
	v_mfma_f32_16x16x32_bf16 v[10:13], v[166:169], v[224:227], v[10:13]
	v_mfma_f32_16x16x32_bf16 v[54:57], v[170:173], v[186:189], v[54:57]
	v_mfma_f32_16x16x32_bf16 v[50:53], v[178:181], v[186:189], v[50:53]
	v_mfma_f32_16x16x32_bf16 v[38:41], v[170:173], v[194:197], v[38:41]
	v_mfma_f32_16x16x32_bf16 v[34:37], v[178:181], v[194:197], v[34:37]
	v_mfma_f32_16x16x32_bf16 v[22:25], v[170:173], v[202:205], v[22:25]
	v_mfma_f32_16x16x32_bf16 v[18:21], v[178:181], v[202:205], v[18:21]
	v_mfma_f32_16x16x32_bf16 v[6:9], v[170:173], v[216:219], v[6:9]
	v_mfma_f32_16x16x32_bf16 v[2:5], v[178:181], v[216:219], v[2:5]
	v_mfma_f32_16x16x32_bf16 v[54:57], v[174:177], v[190:193], v[54:57]
	v_mfma_f32_16x16x32_bf16 v[50:53], v[182:185], v[190:193], v[50:53]
	v_mfma_f32_16x16x32_bf16 v[38:41], v[174:177], v[198:201], v[38:41]
	v_mfma_f32_16x16x32_bf16 v[34:37], v[182:185], v[198:201], v[34:37]
	v_mfma_f32_16x16x32_bf16 v[22:25], v[174:177], v[206:209], v[22:25]
	v_mfma_f32_16x16x32_bf16 v[18:21], v[182:185], v[206:209], v[18:21]
	v_mfma_f32_16x16x32_bf16 v[6:9], v[174:177], v[224:227], v[6:9]
	v_mfma_f32_16x16x32_bf16 v[2:5], v[182:185], v[224:227], v[2:5]
	s_barrier
	s_add_i32 s61, 0, 0x18000
	v_add_u32_e32 v148, s61, v142
	s_add_i32 s62, 0, 0x1c000
	ds_read_b128 v[154:157], v148
	ds_read_b128 v[158:161], v148 offset:1024
	ds_read_b128 v[162:165], v148 offset:2048
	ds_read_b128 v[166:169], v148 offset:3072
	v_add_u32_e32 v148, s62, v142
	ds_read_b128 v[170:173], v148
	ds_read_b128 v[174:177], v148 offset:1024
	ds_read_b128 v[178:181], v148 offset:2048
	ds_read_b128 v[182:185], v148 offset:3072
	s_add_u32 s36, s36, 0x40000
	s_addc_u32 s37, s37, 0
	s_mov_b32 m0, s44
	ds_read_b128 v[186:189], v143 offset:32768
	ds_read_b128 v[190:193], v143 offset:33792
	ds_read_b128 v[194:197], v143 offset:34816
	ds_read_b128 v[198:201], v143 offset:35840
	ds_read_b128 v[202:205], v143 offset:36864
	ds_read_b128 v[206:209], v143 offset:37888
	ds_read_b128 v[216:219], v143 offset:38912
	ds_read_b128 v[224:227], v143 offset:39936
	global_load_lds_dwordx4 v122, s[36:37]
	s_mov_b32 m0, s45
	s_nop 0
	global_load_lds_dwordx4 v126, s[36:37]
	s_waitcnt vmcnt(8) lgkmcnt(0)
	s_barrier
	v_mfma_f32_16x16x32_bf16 v[148:151], v[154:157], v[186:189], v[150:153]
	v_mfma_f32_16x16x32_bf16 v[144:147], v[162:165], v[186:189], v[144:147]
	v_mfma_f32_16x16x32_bf16 v[110:113], v[154:157], v[194:197], v[110:113]
	v_mfma_f32_16x16x32_bf16 v[106:109], v[162:165], v[194:197], v[106:109]
	v_mfma_f32_16x16x32_bf16 v[94:97], v[154:157], v[202:205], v[94:97]
	v_mfma_f32_16x16x32_bf16 v[90:93], v[162:165], v[202:205], v[90:93]
	v_mfma_f32_16x16x32_bf16 v[78:81], v[154:157], v[216:219], v[78:81]
	v_mfma_f32_16x16x32_bf16 v[74:77], v[162:165], v[216:219], v[74:77]
	v_mfma_f32_16x16x32_bf16 v[150:153], v[158:161], v[190:193], v[148:151]
	v_mfma_f32_16x16x32_bf16 v[146:149], v[166:169], v[190:193], v[144:147]
	v_mfma_f32_16x16x32_bf16 v[110:113], v[158:161], v[198:201], v[110:113]
	v_mfma_f32_16x16x32_bf16 v[106:109], v[166:169], v[198:201], v[106:109]
	v_mfma_f32_16x16x32_bf16 v[94:97], v[158:161], v[206:209], v[94:97]
	v_mfma_f32_16x16x32_bf16 v[90:93], v[166:169], v[206:209], v[90:93]
	v_mfma_f32_16x16x32_bf16 v[78:81], v[158:161], v[224:227], v[78:81]
	v_mfma_f32_16x16x32_bf16 v[74:77], v[166:169], v[224:227], v[74:77]
	v_mfma_f32_16x16x32_bf16 v[118:121], v[170:173], v[186:189], v[118:121]
	v_mfma_f32_16x16x32_bf16 v[114:117], v[178:181], v[186:189], v[114:117]
	v_mfma_f32_16x16x32_bf16 v[102:105], v[170:173], v[194:197], v[102:105]
	v_mfma_f32_16x16x32_bf16 v[98:101], v[178:181], v[194:197], v[98:101]
	v_mfma_f32_16x16x32_bf16 v[86:89], v[170:173], v[202:205], v[86:89]
	v_mfma_f32_16x16x32_bf16 v[82:85], v[178:181], v[202:205], v[82:85]
	v_mfma_f32_16x16x32_bf16 v[70:73], v[170:173], v[216:219], v[70:73]
	v_mfma_f32_16x16x32_bf16 v[66:69], v[178:181], v[216:219], v[66:69]
	v_mfma_f32_16x16x32_bf16 v[118:121], v[174:177], v[190:193], v[118:121]
	v_mfma_f32_16x16x32_bf16 v[114:117], v[182:185], v[190:193], v[114:117]
	v_mfma_f32_16x16x32_bf16 v[102:105], v[174:177], v[198:201], v[102:105]
	v_mfma_f32_16x16x32_bf16 v[98:101], v[182:185], v[198:201], v[98:101]
	v_mfma_f32_16x16x32_bf16 v[86:89], v[174:177], v[206:209], v[86:89]
	v_mfma_f32_16x16x32_bf16 v[82:85], v[182:185], v[206:209], v[82:85]
	v_mfma_f32_16x16x32_bf16 v[70:73], v[174:177], v[224:227], v[70:73]
	v_mfma_f32_16x16x32_bf16 v[66:69], v[182:185], v[224:227], v[66:69]
	s_barrier
; #define PG8_STAGE(bufoff, gbase, voff) do { _Pragma("unroll") for (int _i = 0; _i < 2; ++_i) \
;         __builtin_amdgcn_global_load_lds((const unsigned*)((const char*)(gbase) + (voff)[_i]), (PG8_LAS unsigned*)(lds + (bufoff) + ldsw + _i * 8192), 16, 0, 0); } while (0)
; #define PG8_LDA(dst, b, h) do { _Pragma("unroll") for (int m = 0; m < 4; ++m) _Pragma("unroll") for (int k = 0; k < 2; ++k) dst[m][k] = *(const PG8_LAS bf16x8*)(lds + PG8_SA(b, h) + aoff + m * 2048 + k * 1024); } while (0)
; #define PG8_MMA(ai, bj, At, Bt) do { __builtin_amdgcn_s_setprio(1); _Pragma("unroll") for (int m = 0; m < 4; ++m) _Pragma("unroll") for (int n = 0; n < 2; ++n) _Pragma("unroll") for (int k = 0; k < 2; ++k) \
;         acc[ai][bj][m][n] = __builtin_amdgcn_mfma_f32_16x16x32_bf16(Bt[n][k], At[m][k], acc[ai][bj][m][n], 0, 0, 0); __builtin_amdgcn_s_setprio(0); } while (0)
; #define PG8_WAIT_V(n) asm volatile("s_waitcnt vmcnt(" #n ")" ::: "memory")
; #define PG8_WAIT_L(n) asm volatile("s_waitcnt lgkmcnt(" #n ")" ::: "memory")
; #define PG8_BAR __builtin_amdgcn_s_barrier()
; #define PG8_SCHED __builtin_amdgcn_sched_barrier(0)
; template <class Epi, class Sched, bool ALIGN_EPI = false, bool SP2 = false>
; __device__ __forceinline__ void gemm_phase(PG8_LAS unsigned char* lds, const Gemm g, const Sched& S, const Epi& E) {
;     ...
;             PG8_LDA(At, 1, 1); PG8_STAGE(PG8_SB(1, 0), b3, voffB); PG8_STAGE(PG8_SB(1, 1), b3 + hstepB, voffB); PG8_STAGE(PG8_SA(1, 0), a3, voffA);
;             PG8_WAIT_V(8); PG8_WAIT_L(0); PG8_BAR; PG8_MMA(1, 0, At, B0); PG8_MMA(1, 1, At, B1); PG8_BAR; PG8_SCHED;
;     ...
;         if (!has_next) break;
; #pragma unroll
;         for (int a = 0; a < 2; ++a)
; #pragma unroll
;             for (int b = 0; b < 2; ++b)
; #pragma unroll
;                 for (int m = 0; m < 4; ++m)
; #pragma unroll
;                     for (int n = 0; n < 2; ++n) acc[a][b][m][n] = (f32x4){0.f, 0.f, 0.f, 0.f};
;         cur = nxt; cA = nA; cB = nB; ++ui;
	s_add_i32 s36, s61, s38
	v_lshl_add_u64 v[144:145], v[210:211], 0, s[16:17]
	s_mov_b32 m0, s36
	ds_read_b128 v[186:189], v143 offset:49152
	ds_read_b128 v[190:193], v143 offset:50176
	ds_read_b128 v[194:197], v143 offset:51200
	ds_read_b128 v[198:201], v143 offset:52224
	ds_read_b128 v[202:205], v143 offset:53248
	ds_read_b128 v[206:209], v143 offset:54272
	ds_read_b128 v[216:219], v143 offset:55296
	ds_read_b128 v[224:227], v143 offset:56320
	global_load_lds_dwordx4 v[144:145], off
	s_add_i32 m0, s36, 0x2000
	s_add_u32 s34, s34, 0x10080
	v_lshl_add_u64 v[144:145], v[220:221], 0, s[16:17]
	s_addc_u32 s35, s35, 0
	s_add_i32 s36, s62, s38
	global_load_lds_dwordx4 v[144:145], off
	s_mov_b32 m0, s36
	s_nop 0
	global_load_lds_dwordx4 v124, s[34:35]
	s_add_i32 m0, s36, 0x2000
	s_nop 0
	global_load_lds_dwordx4 v128, s[34:35]
	v_lshl_add_u64 v[144:145], v[228:229], 0, s[16:17]
	s_mov_b32 m0, s46
	s_nop 0
	global_load_lds_dwordx4 v[144:145], off
	v_lshl_add_u64 v[144:145], v[230:231], 0, s[16:17]
	s_mov_b32 m0, s47
	s_nop 0
	global_load_lds_dwordx4 v[144:145], off
	s_waitcnt vmcnt(8) lgkmcnt(0)
	s_barrier
	v_mfma_f32_16x16x32_bf16 v[62:65], v[154:157], v[186:189], v[62:65]
	v_mfma_f32_16x16x32_bf16 v[58:61], v[162:165], v[186:189], v[58:61]
	v_mfma_f32_16x16x32_bf16 v[46:49], v[154:157], v[194:197], v[46:49]
	v_mfma_f32_16x16x32_bf16 v[42:45], v[162:165], v[194:197], v[42:45]
	v_mfma_f32_16x16x32_bf16 v[30:33], v[154:157], v[202:205], v[30:33]
	v_mfma_f32_16x16x32_bf16 v[26:29], v[162:165], v[202:205], v[26:29]
	v_mfma_f32_16x16x32_bf16 v[14:17], v[154:157], v[216:219], v[14:17]
	v_mfma_f32_16x16x32_bf16 v[10:13], v[162:165], v[216:219], v[10:13]
	v_mfma_f32_16x16x32_bf16 v[62:65], v[158:161], v[190:193], v[62:65]
	v_mfma_f32_16x16x32_bf16 v[58:61], v[166:169], v[190:193], v[58:61]
	v_mfma_f32_16x16x32_bf16 v[46:49], v[158:161], v[198:201], v[46:49]
	v_mfma_f32_16x16x32_bf16 v[42:45], v[166:169], v[198:201], v[42:45]
	v_mfma_f32_16x16x32_bf16 v[30:33], v[158:161], v[206:209], v[30:33]
	v_mfma_f32_16x16x32_bf16 v[26:29], v[166:169], v[206:209], v[26:29]
	v_mfma_f32_16x16x32_bf16 v[14:17], v[158:161], v[224:227], v[14:17]
	v_mfma_f32_16x16x32_bf16 v[10:13], v[166:169], v[224:227], v[10:13]
	v_mfma_f32_16x16x32_bf16 v[54:57], v[170:173], v[186:189], v[54:57]
	v_mfma_f32_16x16x32_bf16 v[50:53], v[178:181], v[186:189], v[50:53]
	v_mfma_f32_16x16x32_bf16 v[38:41], v[170:173], v[194:197], v[38:41]
	v_mfma_f32_16x16x32_bf16 v[34:37], v[178:181], v[194:197], v[34:37]
	v_mfma_f32_16x16x32_bf16 v[22:25], v[170:173], v[202:205], v[22:25]
	v_mfma_f32_16x16x32_bf16 v[18:21], v[178:181], v[202:205], v[18:21]
	v_mfma_f32_16x16x32_bf16 v[6:9], v[170:173], v[216:219], v[6:9]
	v_mfma_f32_16x16x32_bf16 v[2:5], v[178:181], v[216:219], v[2:5]
	v_mfma_f32_16x16x32_bf16 v[54:57], v[174:177], v[190:193], v[54:57]
	v_mfma_f32_16x16x32_bf16 v[50:53], v[182:185], v[190:193], v[50:53]
	v_mfma_f32_16x16x32_bf16 v[38:41], v[174:177], v[198:201], v[38:41]
	v_mfma_f32_16x16x32_bf16 v[34:37], v[182:185], v[198:201], v[34:37]
	v_mfma_f32_16x16x32_bf16 v[22:25], v[174:177], v[206:209], v[22:25]
	v_mfma_f32_16x16x32_bf16 v[18:21], v[182:185], v[206:209], v[18:21]
	v_mfma_f32_16x16x32_bf16 v[6:9], v[174:177], v[224:227], v[6:9]
	v_mfma_f32_16x16x32_bf16 v[2:5], v[182:185], v[224:227], v[2:5]
	s_barrier
	s_add_i32 s60, s60, 2
	s_add_u32 s28, s28, 0x100
	s_addc_u32 s29, s29, 0
	s_cmp_gt_u32 s60, 13
	s_cbranch_scc0 .LBB0_1180
	s_add_u32 s28, s25, 0xffffff00
	s_addc_u32 s29, s57, -1
	s_andn2_b64 vcc, exec, s[8:9]
	s_cbranch_vccnz .LBB0_1171
	v_mov_b32_e32 v2, 0
	s_mov_b32 s0, s18
	s_mov_b32 s14, s20
	s_mov_b64 s[10:11], s[26:27]
	s_mov_b32 s54, s24
	v_mov_b32_e32 v3, 0
	v_mov_b64_e32 v[4:5], 0
	v_mov_b64_e32 v[6:7], 0
	v_mov_b64_e32 v[8:9], 0
	v_mov_b64_e32 v[18:19], 0
	v_mov_b64_e32 v[20:21], 0
	v_mov_b64_e32 v[22:23], 0
	v_mov_b64_e32 v[24:25], 0
	v_mov_b64_e32 v[34:35], 0
	v_mov_b64_e32 v[36:37], 0
	v_mov_b64_e32 v[38:39], 0
	v_mov_b64_e32 v[40:41], 0
	v_mov_b64_e32 v[50:51], 0
	v_mov_b64_e32 v[52:53], 0
	v_mov_b64_e32 v[54:55], 0
	v_mov_b64_e32 v[56:57], 0
	v_mov_b64_e32 v[10:11], 0
	v_mov_b64_e32 v[12:13], 0
	v_mov_b64_e32 v[14:15], 0
	v_mov_b64_e32 v[16:17], 0
	v_mov_b64_e32 v[26:27], 0
	v_mov_b64_e32 v[28:29], 0
	v_mov_b64_e32 v[30:31], 0
	v_mov_b64_e32 v[32:33], 0
	v_mov_b64_e32 v[42:43], 0
	v_mov_b64_e32 v[44:45], 0
	v_mov_b64_e32 v[46:47], 0
	v_mov_b64_e32 v[48:49], 0
	v_mov_b64_e32 v[58:59], 0
	v_mov_b64_e32 v[60:61], 0
	v_mov_b64_e32 v[62:63], 0
	v_mov_b64_e32 v[64:65], 0
	v_mov_b64_e32 v[66:67], 0
	v_mov_b64_e32 v[68:69], 0
	v_mov_b64_e32 v[70:71], 0
	v_mov_b64_e32 v[72:73], 0
	v_mov_b64_e32 v[82:83], 0
	v_mov_b64_e32 v[84:85], 0
	v_mov_b64_e32 v[86:87], 0
	v_mov_b64_e32 v[88:89], 0
	v_mov_b64_e32 v[98:99], 0
	v_mov_b64_e32 v[100:101], 0
	v_mov_b64_e32 v[102:103], 0
	v_mov_b64_e32 v[104:105], 0
	v_mov_b64_e32 v[114:115], 0
	v_mov_b64_e32 v[116:117], 0
	v_mov_b64_e32 v[118:119], 0
	v_mov_b64_e32 v[120:121], 0
	v_mov_b64_e32 v[74:75], 0
	v_mov_b64_e32 v[76:77], 0
	v_mov_b64_e32 v[78:79], 0
	v_mov_b64_e32 v[80:81], 0
	v_mov_b64_e32 v[90:91], 0
	v_mov_b64_e32 v[92:93], 0
	v_mov_b64_e32 v[94:95], 0
	v_mov_b64_e32 v[96:97], 0
	v_mov_b64_e32 v[106:107], 0
	v_mov_b64_e32 v[108:109], 0
	v_mov_b64_e32 v[110:111], 0
	v_mov_b64_e32 v[112:113], 0
	v_mov_b64_e32 v[146:147], 0
	v_mov_b64_e32 v[148:149], 0
	v_mov_b64_e32 v[150:151], 0
	v_mov_b64_e32 v[152:153], 0
	s_andn2_b64 vcc, exec, s[6:7]
	s_cbranch_vccnz .LBB0_1172

;     __device__ __forceinline__ bool run(const f32x4 (&v)[2][2][4][2], const Unit& u, int wr, int wc, int fr, int fq, PG8_LAS unsigned char* lds, int wid, int lane) const {
;     ...
;         if (wid == 0) {
;             bool dead = false; const unsigned long long t0 = __builtin_amdgcn_s_memrealtime(); const unsigned want = 8u * (unsigned)ntn;
;             for (;;) {
;                 if ((unsigned)__builtin_amdgcn_readfirstlane(__hip_atomic_load(cnt + 64 * u.pm, __ATOMIC_RELAXED, __HIP_MEMORY_SCOPE_AGENT)) >= want) break;
;                 if (__builtin_amdgcn_s_memrealtime() - t0 > 2000000ull) {
;                     if (lane == 0) { unsigned expect = 0u; __hip_atomic_compare_exchange_strong(tmo + 1, &expect, code | (unsigned)(u.pm & 0xff), __ATOMIC_RELAXED, __ATOMIC_RELAXED, __HIP_MEMORY_SCOPE_AGENT);
;                                      __hip_atomic_store(tmo, 1u, __ATOMIC_RELAXED, __HIP_MEMORY_SCOPE_AGENT); }
;                     dead = true; break; }
;                 __builtin_amdgcn_s_sleep(2);
;             }
;             if (lane == 0) flag[0] = dead ? 1u : 0u;
;         }
;         asm volatile("s_waitcnt vmcnt(0) lgkmcnt(0)" ::: "memory"); __builtin_amdgcn_s_barrier(); asm volatile("" ::: "memory");
;         const bool bad = flag[0] != 0u;
;         if (lane < 32) {
;             const unsigned long long* slot = (const unsigned long long*)xbuf + (size_t)(u.pm * BM + row) * 4; float q = 0.f;
; #pragma unroll
;             for (int t = 0; t < 4; ++t) if (t < ntn) { const unsigned long long w = __hip_atomic_load(slot + t, __ATOMIC_RELAXED, __HIP_MEMORY_SCOPE_AGENT); q += __uint_as_float((unsigned)(w >> 32)); }
.Lxp6:
	global_load_dwordx2 v[230:231], v[228:229], off sc1
	global_load_dwordx2 v[232:233], v[228:229], off offset:8 sc1
	global_load_dwordx2 v[234:235], v[228:229], off offset:16 sc1
	global_load_dwordx2 v[236:237], v[228:229], off offset:24 sc1
	s_bitcmp1_b32 s98, 0
	s_cbranch_scc1 .Lxk6
	s_waitcnt vmcnt(0)
	v_and_b32_e32 v225, v230, v232
	v_and_b32_e32 v225, v225, v234
	v_and_b32_e32 v225, v225, v236
	v_cmp_ne_u32_e32 vcc, 1, v225
	s_cbranch_vccz .Lxk6
	s_add_i32 s100, s100, 1
	s_cmp_lt_u32 s100, 0x40000
	s_cbranch_scc1 .Lxp6

; #define PG8_STAGE(bufoff, gbase, voff) do { _Pragma("unroll") for (int _i = 0; _i < 2; ++_i) \
;         __builtin_amdgcn_global_load_lds((const unsigned*)((const char*)(gbase) + (voff)[_i]), (PG8_LAS unsigned*)(lds + (bufoff) + ldsw + _i * 8192), 16, 0, 0); } while (0)
; #define PG8_LDA(dst, b, h) do { _Pragma("unroll") for (int m = 0; m < 4; ++m) _Pragma("unroll") for (int k = 0; k < 2; ++k) dst[m][k] = *(const PG8_LAS bf16x8*)(lds + PG8_SA(b, h) + aoff + m * 2048 + k * 1024); } while (0)
; #define PG8_LDB(dst, b, h) do { _Pragma("unroll") for (int n = 0; n < 2; ++n) _Pragma("unroll") for (int k = 0; k < 2; ++k) dst[n][k] = *(const PG8_LAS bf16x8*)(lds + PG8_SB(b, h) + boff + n * 2048 + k * 1024); } while (0)
; #define PG8_MMA(ai, bj, At, Bt) do { __builtin_amdgcn_s_setprio(1); _Pragma("unroll") for (int m = 0; m < 4; ++m) _Pragma("unroll") for (int n = 0; n < 2; ++n) _Pragma("unroll") for (int k = 0; k < 2; ++k) \
;         acc[ai][bj][m][n] = __builtin_amdgcn_mfma_f32_16x16x32_bf16(Bt[n][k], At[m][k], acc[ai][bj][m][n], 0, 0, 0); __builtin_amdgcn_s_setprio(0); } while (0)
; template <class Epi, class Sched, bool ALIGN_EPI = false, bool SP2 = false>
; __device__ __forceinline__ void gemm_phase(PG8_LAS unsigned char* lds, const Gemm g, const Sched& S, const Epi& E) {
;     ...
;         const char* nA = has_next ? (const char*)g.A + (size_t)nxt.pm * tstep : cA; const char* nB = has_next ? (const char*)g.Bt + (size_t)nxt.pn * tstep : cB;
;         for (int t = 0; t < nt; t += 2) {
;             if constexpr (Epi::HAS_MID) { if (t == nt / 2) E.mid(acc, cur, wr, wc, fr, fq); }
;             const bool last = (t == nt - 2);
;             const char* a1 = cA + (size_t)(t + 1) * kstep;
;             const char* a2 = last ? nA : cA + (size_t)(t + 2) * kstep; const char* b2 = last ? nB : cB + (size_t)(t + 2) * kstep;
;             const char* a3 = a2 + kstep; const char* b3 = b2 + kstep;
;             if (last && has_next) S.a_ready(nxt);
;             if constexpr (SP2) {
;             PG8_LDB(B0, 0, 0); PG8_LDB(B1, 0, 1); PG8_SCHED; PG8_LDA(At, 0, 0); PG8_STAGE(PG8_SA(1, 1), a1 + hstep, voffA);
;             PG8_WAIT_V(8); PG8_WAIT_L(0); PG8_BAR; PG8_MMA(0, 0, At, B0); PG8_MMA(0, 1, At, B1); PG8_BAR; PG8_SCHED;
;             PG8_LDA(At, 0, 1); PG8_STAGE(PG8_SB(0, 0), b2, voffB); PG8_STAGE(PG8_SB(0, 1), b2 + hstepB, voffB); PG8_STAGE(PG8_SA(0, 0), a2, voffA);
.LBB0_1312:
	s_ashr_i32 s27, s26, 31
	s_lshl_b64 s[28:29], s[26:27], 19
	s_add_u32 s28, s12, s28
	s_addc_u32 s29, s13, s29
	s_and_b64 s[34:35], s[6:7], exec
	s_cselect_b32 s9, s29, s39
	s_cselect_b32 s27, s28, s38
	s_ashr_i32 s25, s24, 31
	s_lshl_b64 s[34:35], s[24:25], 19
	s_add_u32 s34, s78, s34
	s_addc_u32 s35, s79, s35
	s_and_b64 s[42:43], s[6:7], exec
	s_cselect_b32 s25, s35, s41
	s_cselect_b32 s37, s34, s40
	s_add_u32 s38, s38, 0x40080
	s_addc_u32 s39, s39, 0
	s_add_u32 s59, s40, 0x100
	s_addc_u32 s60, s41, 0
	s_mov_b32 s61, -2
	ds_read_b128 v[146:149], v154
	ds_read_b128 v[158:161], v154 offset:1024
	ds_read_b128 v[162:165], v154 offset:2048
	ds_read_b128 v[166:169], v154 offset:3072
	ds_read_b128 v[170:173], v155
	ds_read_b128 v[174:177], v155 offset:1024
	ds_read_b128 v[178:181], v155 offset:2048
	ds_read_b128 v[182:185], v155 offset:3072
	s_add_u32 s40, s38, 0xfffc0080
	s_addc_u32 s41, s39, -1
	s_cmp_eq_u32 s61, 12
	s_cselect_b32 s43, s9, s41
	s_cselect_b32 s42, s27, s40
	s_cselect_b32 s41, s25, s60
	s_cselect_b32 s40, s37, s59
	v_lshl_add_u64 v[150:151], s[38:39], 0, v[138:139]
	s_add_i32 m0, s31, 0xc000
	ds_read_b128 v[186:189], v156
	ds_read_b128 v[190:193], v156 offset:1024
	ds_read_b128 v[194:197], v156 offset:2048
	ds_read_b128 v[198:201], v156 offset:3072
	ds_read_b128 v[202:205], v156 offset:4096
	ds_read_b128 v[206:209], v156 offset:5120
	ds_read_b128 v[210:213], v156 offset:6144
	ds_read_b128 v[214:217], v156 offset:7168
	global_load_lds_dwordx4 v[150:151], off
	v_lshl_add_u64 v[150:151], s[38:39], 0, v[140:141]
	s_add_i32 m0, s31, 0xe000
	s_nop 0
	global_load_lds_dwordx4 v[150:151], off
	s_waitcnt vmcnt(8) lgkmcnt(0)
	s_barrier
	v_mfma_f32_16x16x32_bf16 v[126:129], v[146:149], v[186:189], 0
	v_mfma_f32_16x16x32_bf16 v[122:125], v[162:165], v[186:189], 0
	v_mfma_f32_16x16x32_bf16 v[110:113], v[146:149], v[194:197], 0
	v_mfma_f32_16x16x32_bf16 v[106:109], v[162:165], v[194:197], 0
	v_mfma_f32_16x16x32_bf16 v[94:97], v[146:149], v[202:205], 0
	v_mfma_f32_16x16x32_bf16 v[90:93], v[162:165], v[202:205], 0
	v_mfma_f32_16x16x32_bf16 v[78:81], v[146:149], v[210:213], 0
	v_mfma_f32_16x16x32_bf16 v[74:77], v[162:165], v[210:213], 0
	v_mfma_f32_16x16x32_bf16 v[126:129], v[158:161], v[190:193], v[126:129]
	v_mfma_f32_16x16x32_bf16 v[122:125], v[166:169], v[190:193], v[122:125]
	v_mfma_f32_16x16x32_bf16 v[110:113], v[158:161], v[198:201], v[110:113]
	v_mfma_f32_16x16x32_bf16 v[106:109], v[166:169], v[198:201], v[106:109]
	v_mfma_f32_16x16x32_bf16 v[94:97], v[158:161], v[206:209], v[94:97]
	v_mfma_f32_16x16x32_bf16 v[90:93], v[166:169], v[206:209], v[90:93]
	v_mfma_f32_16x16x32_bf16 v[78:81], v[158:161], v[214:217], v[78:81]
	v_mfma_f32_16x16x32_bf16 v[74:77], v[166:169], v[214:217], v[74:77]
	v_mfma_f32_16x16x32_bf16 v[118:121], v[170:173], v[186:189], 0
	v_mfma_f32_16x16x32_bf16 v[114:117], v[178:181], v[186:189], 0
	v_mfma_f32_16x16x32_bf16 v[102:105], v[170:173], v[194:197], 0
	v_mfma_f32_16x16x32_bf16 v[98:101], v[178:181], v[194:197], 0
	v_mfma_f32_16x16x32_bf16 v[86:89], v[170:173], v[202:205], 0
	v_mfma_f32_16x16x32_bf16 v[82:85], v[178:181], v[202:205], 0
	v_mfma_f32_16x16x32_bf16 v[70:73], v[170:173], v[210:213], 0
	v_mfma_f32_16x16x32_bf16 v[66:69], v[178:181], v[210:213], 0
	v_mfma_f32_16x16x32_bf16 v[118:121], v[174:177], v[190:193], v[118:121]
	v_mfma_f32_16x16x32_bf16 v[114:117], v[182:185], v[190:193], v[114:117]
	v_mfma_f32_16x16x32_bf16 v[102:105], v[174:177], v[198:201], v[102:105]
	v_mfma_f32_16x16x32_bf16 v[98:101], v[182:185], v[198:201], v[98:101]
	v_mfma_f32_16x16x32_bf16 v[86:89], v[174:177], v[206:209], v[86:89]
	v_mfma_f32_16x16x32_bf16 v[82:85], v[182:185], v[206:209], v[82:85]
	v_mfma_f32_16x16x32_bf16 v[70:73], v[174:177], v[214:217], v[70:73]
	v_mfma_f32_16x16x32_bf16 v[66:69], v[182:185], v[214:217], v[66:69]
	s_barrier
	s_add_i32 s62, s57, s30
	v_lshl_add_u64 v[150:151], s[40:41], 0, v[132:133]
	s_mov_b32 m0, s62
	ds_read_b128 v[186:189], v156 offset:16384
	ds_read_b128 v[190:193], v156 offset:17408
	ds_read_b128 v[194:197], v156 offset:18432
	ds_read_b128 v[198:201], v156 offset:19456
	ds_read_b128 v[202:205], v156 offset:20480
	ds_read_b128 v[206:209], v156 offset:21504
	ds_read_b128 v[210:213], v156 offset:22528
	ds_read_b128 v[214:217], v156 offset:23552
	global_load_lds_dwordx4 v132, s[40:41]
	s_add_i32 m0, s62, 0x2000
	s_add_u32 s62, s40, 0x10000
	v_lshl_add_u64 v[218:219], s[40:41], 0, v[136:137]
	s_addc_u32 s63, s41, 0
	s_add_i32 s64, s58, s30
	global_load_lds_dwordx4 v136, s[40:41]
	s_mov_b32 m0, s64
	v_lshl_add_u64 v[222:223], s[42:43], 0, v[134:135]
	global_load_lds_dwordx4 v132, s[62:63]
	s_add_i32 m0, s64, 0x2000
	s_nop 0
	global_load_lds_dwordx4 v136, s[62:63]
	v_lshl_add_u64 v[220:221], s[42:43], 0, v[130:131]
	s_mov_b32 m0, s31
	s_nop 0
	global_load_lds_dwordx4 v130, s[42:43]
	s_mov_b32 m0, s33
	s_nop 0
	global_load_lds_dwordx4 v134, s[42:43]
	s_waitcnt vmcnt(8) lgkmcnt(0)
	s_barrier
; #define PG8_STAGE(bufoff, gbase, voff) do { _Pragma("unroll") for (int _i = 0; _i < 2; ++_i) \
;         __builtin_amdgcn_global_load_lds((const unsigned*)((const char*)(gbase) + (voff)[_i]), (PG8_LAS unsigned*)(lds + (bufoff) + ldsw + _i * 8192), 16, 0, 0); } while (0)
; #define PG8_LDA(dst, b, h) do { _Pragma("unroll") for (int m = 0; m < 4; ++m) _Pragma("unroll") for (int k = 0; k < 2; ++k) dst[m][k] = *(const PG8_LAS bf16x8*)(lds + PG8_SA(b, h) + aoff + m * 2048 + k * 1024); } while (0)
; #define PG8_LDB(dst, b, h) do { _Pragma("unroll") for (int n = 0; n < 2; ++n) _Pragma("unroll") for (int k = 0; k < 2; ++k) dst[n][k] = *(const PG8_LAS bf16x8*)(lds + PG8_SB(b, h) + boff + n * 2048 + k * 1024); } while (0)
; #define PG8_MMA(ai, bj, At, Bt) do { __builtin_amdgcn_s_setprio(1); _Pragma("unroll") for (int m = 0; m < 4; ++m) _Pragma("unroll") for (int n = 0; n < 2; ++n) _Pragma("unroll") for (int k = 0; k < 2; ++k) \
;         acc[ai][bj][m][n] = __builtin_amdgcn_mfma_f32_16x16x32_bf16(Bt[n][k], At[m][k], acc[ai][bj][m][n], 0, 0, 0); __builtin_amdgcn_s_setprio(0); } while (0)
; #define PG8_WAIT_V(n) asm volatile("s_waitcnt vmcnt(" #n ")" ::: "memory")
; #define PG8_WAIT_L(n) asm volatile("s_waitcnt lgkmcnt(" #n ")" ::: "memory")
; #define PG8_BAR __builtin_amdgcn_s_barrier()
; #define PG8_SCHED __builtin_amdgcn_sched_barrier(0)
; template <class Epi, class Sched, bool ALIGN_EPI = false, bool SP2 = false>
; __device__ __forceinline__ void gemm_phase(PG8_LAS unsigned char* lds, const Gemm g, const Sched& S, const Epi& E) {
;     ...
;             PG8_WAIT_V(8); PG8_WAIT_L(0); PG8_BAR; PG8_MMA(1, 0, At, B0); PG8_MMA(1, 1, At, B1); PG8_BAR; PG8_SCHED;
;             PG8_LDB(B0, 1, 0); PG8_LDB(B1, 1, 1); PG8_SCHED; PG8_LDA(At, 1, 0); PG8_STAGE(PG8_SA(0, 1), a2 + hstep, voffA);
;             PG8_WAIT_V(8); PG8_WAIT_L(0); PG8_BAR; PG8_MMA(0, 0, At, B0); PG8_MMA(0, 1, At, B1); PG8_BAR; PG8_SCHED;
	v_mfma_f32_16x16x32_bf16 v[62:65], v[146:149], v[186:189], 0
	v_mfma_f32_16x16x32_bf16 v[58:61], v[162:165], v[186:189], 0
	v_mfma_f32_16x16x32_bf16 v[46:49], v[146:149], v[194:197], 0
	v_mfma_f32_16x16x32_bf16 v[42:45], v[162:165], v[194:197], 0
	v_mfma_f32_16x16x32_bf16 v[30:33], v[146:149], v[202:205], 0
	v_mfma_f32_16x16x32_bf16 v[26:29], v[162:165], v[202:205], 0
	v_mfma_f32_16x16x32_bf16 v[14:17], v[146:149], v[210:213], 0
	v_mfma_f32_16x16x32_bf16 v[10:13], v[162:165], v[210:213], 0
	v_mfma_f32_16x16x32_bf16 v[62:65], v[158:161], v[190:193], v[62:65]
	v_mfma_f32_16x16x32_bf16 v[58:61], v[166:169], v[190:193], v[58:61]
	v_mfma_f32_16x16x32_bf16 v[46:49], v[158:161], v[198:201], v[46:49]
	v_mfma_f32_16x16x32_bf16 v[42:45], v[166:169], v[198:201], v[42:45]
	v_mfma_f32_16x16x32_bf16 v[30:33], v[158:161], v[206:209], v[30:33]
	v_mfma_f32_16x16x32_bf16 v[26:29], v[166:169], v[206:209], v[26:29]
	v_mfma_f32_16x16x32_bf16 v[14:17], v[158:161], v[214:217], v[14:17]
	v_mfma_f32_16x16x32_bf16 v[10:13], v[166:169], v[214:217], v[10:13]
	v_mfma_f32_16x16x32_bf16 v[54:57], v[170:173], v[186:189], 0
	v_mfma_f32_16x16x32_bf16 v[50:53], v[178:181], v[186:189], 0
	v_mfma_f32_16x16x32_bf16 v[38:41], v[170:173], v[194:197], 0
	v_mfma_f32_16x16x32_bf16 v[34:37], v[178:181], v[194:197], 0
	v_mfma_f32_16x16x32_bf16 v[22:25], v[170:173], v[202:205], 0
	v_mfma_f32_16x16x32_bf16 v[18:21], v[178:181], v[202:205], 0
	v_mfma_f32_16x16x32_bf16 v[6:9], v[170:173], v[210:213], 0
	v_mfma_f32_16x16x32_bf16 v[2:5], v[178:181], v[210:213], 0
	v_mfma_f32_16x16x32_bf16 v[54:57], v[174:177], v[190:193], v[54:57]
	v_mfma_f32_16x16x32_bf16 v[50:53], v[182:185], v[190:193], v[50:53]
	v_mfma_f32_16x16x32_bf16 v[38:41], v[174:177], v[198:201], v[38:41]
	v_mfma_f32_16x16x32_bf16 v[34:37], v[182:185], v[198:201], v[34:37]
	v_mfma_f32_16x16x32_bf16 v[22:25], v[174:177], v[206:209], v[22:25]
	v_mfma_f32_16x16x32_bf16 v[18:21], v[182:185], v[206:209], v[18:21]
	v_mfma_f32_16x16x32_bf16 v[6:9], v[174:177], v[214:217], v[6:9]
	v_mfma_f32_16x16x32_bf16 v[2:5], v[182:185], v[214:217], v[2:5]
	s_barrier
	s_add_i32 s62, 0, 0x18000
	v_add_u32_e32 v157, s62, v152
	s_add_i32 s63, 0, 0x1c000
	ds_read_b128 v[146:149], v157
	ds_read_b128 v[158:161], v157 offset:1024
	ds_read_b128 v[162:165], v157 offset:2048
	ds_read_b128 v[166:169], v157 offset:3072
	v_add_u32_e32 v157, s63, v152
	ds_read_b128 v[170:173], v157
	ds_read_b128 v[174:177], v157 offset:1024
	ds_read_b128 v[178:181], v157 offset:2048
	ds_read_b128 v[182:185], v157 offset:3072
	s_add_u32 s42, s42, 0x40000
	s_addc_u32 s43, s43, 0
	s_mov_b32 m0, s44
	ds_read_b128 v[186:189], v156 offset:32768
	ds_read_b128 v[190:193], v156 offset:33792
	ds_read_b128 v[194:197], v156 offset:34816
	ds_read_b128 v[198:201], v156 offset:35840
	ds_read_b128 v[202:205], v156 offset:36864
	ds_read_b128 v[206:209], v156 offset:37888
	ds_read_b128 v[210:213], v156 offset:38912
	ds_read_b128 v[214:217], v156 offset:39936
	global_load_lds_dwordx4 v130, s[42:43]
	s_mov_b32 m0, s45
	s_nop 0
	global_load_lds_dwordx4 v134, s[42:43]
	s_waitcnt vmcnt(8) lgkmcnt(0)
	s_barrier
	v_mfma_f32_16x16x32_bf16 v[126:129], v[146:149], v[186:189], v[126:129]
	v_mfma_f32_16x16x32_bf16 v[122:125], v[162:165], v[186:189], v[122:125]
	v_mfma_f32_16x16x32_bf16 v[110:113], v[146:149], v[194:197], v[110:113]
	v_mfma_f32_16x16x32_bf16 v[106:109], v[162:165], v[194:197], v[106:109]
	v_mfma_f32_16x16x32_bf16 v[94:97], v[146:149], v[202:205], v[94:97]
	v_mfma_f32_16x16x32_bf16 v[90:93], v[162:165], v[202:205], v[90:93]
	v_mfma_f32_16x16x32_bf16 v[78:81], v[146:149], v[210:213], v[78:81]
	v_mfma_f32_16x16x32_bf16 v[74:77], v[162:165], v[210:213], v[74:77]
	v_mfma_f32_16x16x32_bf16 v[126:129], v[158:161], v[190:193], v[126:129]
	v_mfma_f32_16x16x32_bf16 v[122:125], v[166:169], v[190:193], v[122:125]
	v_mfma_f32_16x16x32_bf16 v[110:113], v[158:161], v[198:201], v[110:113]
	v_mfma_f32_16x16x32_bf16 v[106:109], v[166:169], v[198:201], v[106:109]
	v_mfma_f32_16x16x32_bf16 v[94:97], v[158:161], v[206:209], v[94:97]
	v_mfma_f32_16x16x32_bf16 v[90:93], v[166:169], v[206:209], v[90:93]
	v_mfma_f32_16x16x32_bf16 v[78:81], v[158:161], v[214:217], v[78:81]
	v_mfma_f32_16x16x32_bf16 v[74:77], v[166:169], v[214:217], v[74:77]
	v_mfma_f32_16x16x32_bf16 v[118:121], v[170:173], v[186:189], v[118:121]
	v_mfma_f32_16x16x32_bf16 v[114:117], v[178:181], v[186:189], v[114:117]
	v_mfma_f32_16x16x32_bf16 v[102:105], v[170:173], v[194:197], v[102:105]
	v_mfma_f32_16x16x32_bf16 v[98:101], v[178:181], v[194:197], v[98:101]
	v_mfma_f32_16x16x32_bf16 v[86:89], v[170:173], v[202:205], v[86:89]
	v_mfma_f32_16x16x32_bf16 v[82:85], v[178:181], v[202:205], v[82:85]
	v_mfma_f32_16x16x32_bf16 v[70:73], v[170:173], v[210:213], v[70:73]
	v_mfma_f32_16x16x32_bf16 v[66:69], v[178:181], v[210:213], v[66:69]
	v_mfma_f32_16x16x32_bf16 v[118:121], v[174:177], v[190:193], v[118:121]
	v_mfma_f32_16x16x32_bf16 v[114:117], v[182:185], v[190:193], v[114:117]
	v_mfma_f32_16x16x32_bf16 v[102:105], v[174:177], v[198:201], v[102:105]
	v_mfma_f32_16x16x32_bf16 v[98:101], v[182:185], v[198:201], v[98:101]
	v_mfma_f32_16x16x32_bf16 v[86:89], v[174:177], v[206:209], v[86:89]
	v_mfma_f32_16x16x32_bf16 v[82:85], v[182:185], v[206:209], v[82:85]
	v_mfma_f32_16x16x32_bf16 v[70:73], v[174:177], v[214:217], v[70:73]
	v_mfma_f32_16x16x32_bf16 v[66:69], v[182:185], v[214:217], v[66:69]
	s_barrier
; #define PG8_STAGE(bufoff, gbase, voff) do { _Pragma("unroll") for (int _i = 0; _i < 2; ++_i) \
;         __builtin_amdgcn_global_load_lds((const unsigned*)((const char*)(gbase) + (voff)[_i]), (PG8_LAS unsigned*)(lds + (bufoff) + ldsw + _i * 8192), 16, 0, 0); } while (0)
; #define PG8_LDA(dst, b, h) do { _Pragma("unroll") for (int m = 0; m < 4; ++m) _Pragma("unroll") for (int k = 0; k < 2; ++k) dst[m][k] = *(const PG8_LAS bf16x8*)(lds + PG8_SA(b, h) + aoff + m * 2048 + k * 1024); } while (0)
; #define PG8_LDB(dst, b, h) do { _Pragma("unroll") for (int n = 0; n < 2; ++n) _Pragma("unroll") for (int k = 0; k < 2; ++k) dst[n][k] = *(const PG8_LAS bf16x8*)(lds + PG8_SB(b, h) + boff + n * 2048 + k * 1024); } while (0)
; #define PG8_MMA(ai, bj, At, Bt) do { __builtin_amdgcn_s_setprio(1); _Pragma("unroll") for (int m = 0; m < 4; ++m) _Pragma("unroll") for (int n = 0; n < 2; ++n) _Pragma("unroll") for (int k = 0; k < 2; ++k) \
;         acc[ai][bj][m][n] = __builtin_amdgcn_mfma_f32_16x16x32_bf16(Bt[n][k], At[m][k], acc[ai][bj][m][n], 0, 0, 0); __builtin_amdgcn_s_setprio(0); } while (0)
; #define PG8_WAIT_V(n) asm volatile("s_waitcnt vmcnt(" #n ")" ::: "memory")
; #define PG8_WAIT_L(n) asm volatile("s_waitcnt lgkmcnt(" #n ")" ::: "memory")
; #define PG8_BAR __builtin_amdgcn_s_barrier()
; #define PG8_SCHED __builtin_amdgcn_sched_barrier(0)
; template <class Epi, class Sched, bool ALIGN_EPI = false, bool SP2 = false>
; __device__ __forceinline__ void gemm_phase(PG8_LAS unsigned char* lds, const Gemm g, const Sched& S, const Epi& E) {
;     ...
;             PG8_LDB(B0, 0, 0); PG8_LDB(B1, 0, 1); PG8_SCHED; PG8_LDA(At, 0, 0); PG8_STAGE(PG8_SA(1, 1), a1 + hstep, voffA);
;             PG8_WAIT_V(8); PG8_WAIT_L(0); PG8_BAR; PG8_MMA(0, 0, At, B0); PG8_MMA(0, 1, At, B1); PG8_BAR; PG8_SCHED;
;     ...
;             PG8_LDA(At, 1, 1); PG8_STAGE(PG8_SB(1, 0), b3, voffB); PG8_STAGE(PG8_SB(1, 1), b3 + hstepB, voffB); PG8_STAGE(PG8_SA(1, 0), a3, voffA);
;             PG8_WAIT_V(8); PG8_WAIT_L(0); PG8_BAR; PG8_MMA(1, 0, At, B0); PG8_MMA(1, 1, At, B1); PG8_BAR; PG8_SCHED;
	s_add_i32 s42, s62, s30
	v_lshl_add_u64 v[150:151], v[150:151], 0, s[10:11]
	s_mov_b32 m0, s42
	ds_read_b128 v[186:189], v156 offset:49152
	ds_read_b128 v[190:193], v156 offset:50176
	ds_read_b128 v[194:197], v156 offset:51200
	ds_read_b128 v[198:201], v156 offset:52224
	ds_read_b128 v[202:205], v156 offset:53248
	ds_read_b128 v[206:209], v156 offset:54272
	ds_read_b128 v[210:213], v156 offset:55296
	ds_read_b128 v[214:217], v156 offset:56320
	global_load_lds_dwordx4 v[150:151], off
	s_add_i32 m0, s42, 0x2000
	s_add_u32 s40, s40, 0x10080
	v_lshl_add_u64 v[150:151], v[218:219], 0, s[10:11]
	s_addc_u32 s41, s41, 0
	s_add_i32 s42, s63, s30
	global_load_lds_dwordx4 v[150:151], off
	s_mov_b32 m0, s42
	s_nop 0
	global_load_lds_dwordx4 v132, s[40:41]
	s_add_i32 m0, s42, 0x2000
	s_nop 0
	global_load_lds_dwordx4 v136, s[40:41]
	v_lshl_add_u64 v[150:151], v[220:221], 0, s[10:11]
	s_mov_b32 m0, s47
	s_nop 0
	global_load_lds_dwordx4 v[150:151], off
	v_lshl_add_u64 v[150:151], v[222:223], 0, s[10:11]
	s_mov_b32 m0, s54
	s_nop 0
	global_load_lds_dwordx4 v[150:151], off
	s_waitcnt vmcnt(8) lgkmcnt(0)
	s_barrier
	v_mfma_f32_16x16x32_bf16 v[62:65], v[146:149], v[186:189], v[62:65]
	v_mfma_f32_16x16x32_bf16 v[58:61], v[162:165], v[186:189], v[58:61]
	v_mfma_f32_16x16x32_bf16 v[46:49], v[146:149], v[194:197], v[46:49]
	v_mfma_f32_16x16x32_bf16 v[42:45], v[162:165], v[194:197], v[42:45]
	v_mfma_f32_16x16x32_bf16 v[30:33], v[146:149], v[202:205], v[30:33]
	v_mfma_f32_16x16x32_bf16 v[26:29], v[162:165], v[202:205], v[26:29]
	v_mfma_f32_16x16x32_bf16 v[14:17], v[146:149], v[210:213], v[14:17]
	v_mfma_f32_16x16x32_bf16 v[10:13], v[162:165], v[210:213], v[10:13]
	v_mfma_f32_16x16x32_bf16 v[62:65], v[158:161], v[190:193], v[62:65]
	v_mfma_f32_16x16x32_bf16 v[58:61], v[166:169], v[190:193], v[58:61]
	v_mfma_f32_16x16x32_bf16 v[46:49], v[158:161], v[198:201], v[46:49]
	v_mfma_f32_16x16x32_bf16 v[42:45], v[166:169], v[198:201], v[42:45]
	v_mfma_f32_16x16x32_bf16 v[30:33], v[158:161], v[206:209], v[30:33]
	v_mfma_f32_16x16x32_bf16 v[26:29], v[166:169], v[206:209], v[26:29]
	v_mfma_f32_16x16x32_bf16 v[14:17], v[158:161], v[214:217], v[14:17]
	v_mfma_f32_16x16x32_bf16 v[10:13], v[166:169], v[214:217], v[10:13]
	v_mfma_f32_16x16x32_bf16 v[54:57], v[170:173], v[186:189], v[54:57]
	v_mfma_f32_16x16x32_bf16 v[50:53], v[178:181], v[186:189], v[50:53]
	v_mfma_f32_16x16x32_bf16 v[38:41], v[170:173], v[194:197], v[38:41]
	v_mfma_f32_16x16x32_bf16 v[34:37], v[178:181], v[194:197], v[34:37]
	v_mfma_f32_16x16x32_bf16 v[22:25], v[170:173], v[202:205], v[22:25]
	v_mfma_f32_16x16x32_bf16 v[18:21], v[178:181], v[202:205], v[18:21]
	v_mfma_f32_16x16x32_bf16 v[6:9], v[170:173], v[210:213], v[6:9]
	v_mfma_f32_16x16x32_bf16 v[2:5], v[178:181], v[210:213], v[2:5]
	v_mfma_f32_16x16x32_bf16 v[54:57], v[174:177], v[190:193], v[54:57]
	v_mfma_f32_16x16x32_bf16 v[50:53], v[182:185], v[190:193], v[50:53]
	v_mfma_f32_16x16x32_bf16 v[38:41], v[174:177], v[198:201], v[38:41]
	v_mfma_f32_16x16x32_bf16 v[34:37], v[182:185], v[198:201], v[34:37]
	v_mfma_f32_16x16x32_bf16 v[22:25], v[174:177], v[206:209], v[22:25]
	v_mfma_f32_16x16x32_bf16 v[18:21], v[182:185], v[206:209], v[18:21]
	v_mfma_f32_16x16x32_bf16 v[6:9], v[174:177], v[214:217], v[6:9]
	v_mfma_f32_16x16x32_bf16 v[2:5], v[182:185], v[214:217], v[2:5]
	s_barrier
	s_add_i32 s61, s61, 2
	s_add_u32 s38, s38, 0x100
	s_addc_u32 s39, s39, 0
	s_add_u32 s59, s59, 0x100
	s_addc_u32 s60, s60, 0
	s_cmp_gt_u32 s61, 13
	s_cbranch_scc1 .Lpp1_x
.LBB0_1313:
	ds_read_b128 v[146:149], v154
	ds_read_b128 v[158:161], v154 offset:1024
	ds_read_b128 v[162:165], v154 offset:2048
	ds_read_b128 v[166:169], v154 offset:3072
	ds_read_b128 v[170:173], v155
	ds_read_b128 v[174:177], v155 offset:1024
	ds_read_b128 v[178:181], v155 offset:2048
	ds_read_b128 v[182:185], v155 offset:3072
	s_add_u32 s40, s38, 0xfffc0080
	s_addc_u32 s41, s39, -1
	s_cmp_eq_u32 s61, 12
	s_cselect_b32 s43, s9, s41
	s_cselect_b32 s42, s27, s40
	s_cselect_b32 s41, s25, s60
	s_cselect_b32 s40, s37, s59
	v_lshl_add_u64 v[150:151], s[38:39], 0, v[138:139]
	s_add_i32 m0, s31, 0xc000
	ds_read_b128 v[186:189], v156
	ds_read_b128 v[190:193], v156 offset:1024
	ds_read_b128 v[194:197], v156 offset:2048
	ds_read_b128 v[198:201], v156 offset:3072
	ds_read_b128 v[202:205], v156 offset:4096
	ds_read_b128 v[206:209], v156 offset:5120
	ds_read_b128 v[210:213], v156 offset:6144
	ds_read_b128 v[214:217], v156 offset:7168
	global_load_lds_dwordx4 v[150:151], off
	v_lshl_add_u64 v[150:151], s[38:39], 0, v[140:141]
	s_add_i32 m0, s31, 0xe000
	s_nop 0
	global_load_lds_dwordx4 v[150:151], off
	s_waitcnt vmcnt(8) lgkmcnt(0)
	s_barrier
; #define PG8_STAGE(bufoff, gbase, voff) do { _Pragma("unroll") for (int _i = 0; _i < 2; ++_i) \
;         __builtin_amdgcn_global_load_lds((const unsigned*)((const char*)(gbase) + (voff)[_i]), (PG8_LAS unsigned*)(lds + (bufoff) + ldsw + _i * 8192), 16, 0, 0); } while (0)
; #define PG8_LDA(dst, b, h) do { _Pragma("unroll") for (int m = 0; m < 4; ++m) _Pragma("unroll") for (int k = 0; k < 2; ++k) dst[m][k] = *(const PG8_LAS bf16x8*)(lds + PG8_SA(b, h) + aoff + m * 2048 + k * 1024); } while (0)
; #define PG8_MMA(ai, bj, At, Bt) do { __builtin_amdgcn_s_setprio(1); _Pragma("unroll") for (int m = 0; m < 4; ++m) _Pragma("unroll") for (int n = 0; n < 2; ++n) _Pragma("unroll") for (int k = 0; k < 2; ++k) \
;         acc[ai][bj][m][n] = __builtin_amdgcn_mfma_f32_16x16x32_bf16(Bt[n][k], At[m][k], acc[ai][bj][m][n], 0, 0, 0); __builtin_amdgcn_s_setprio(0); } while (0)
; #define PG8_WAIT_V(n) asm volatile("s_waitcnt vmcnt(" #n ")" ::: "memory")
; #define PG8_WAIT_L(n) asm volatile("s_waitcnt lgkmcnt(" #n ")" ::: "memory")
; #define PG8_BAR __builtin_amdgcn_s_barrier()
; #define PG8_SCHED __builtin_amdgcn_sched_barrier(0)
; template <class Epi, class Sched, bool ALIGN_EPI = false, bool SP2 = false>
; __device__ __forceinline__ void gemm_phase(PG8_LAS unsigned char* lds, const Gemm g, const Sched& S, const Epi& E) {
;     ...
;             PG8_WAIT_V(8); PG8_WAIT_L(0); PG8_BAR; PG8_MMA(0, 0, At, B0); PG8_MMA(0, 1, At, B1); PG8_BAR; PG8_SCHED;
;             PG8_LDA(At, 0, 1); PG8_STAGE(PG8_SB(0, 0), b2, voffB); PG8_STAGE(PG8_SB(0, 1), b2 + hstepB, voffB); PG8_STAGE(PG8_SA(0, 0), a2, voffA);
;             PG8_WAIT_V(8); PG8_WAIT_L(0); PG8_BAR; PG8_MMA(1, 0, At, B0); PG8_MMA(1, 1, At, B1); PG8_BAR; PG8_SCHED;
	v_mfma_f32_16x16x32_bf16 v[126:129], v[146:149], v[186:189], v[126:129]
	v_mfma_f32_16x16x32_bf16 v[122:125], v[162:165], v[186:189], v[122:125]
	v_mfma_f32_16x16x32_bf16 v[110:113], v[146:149], v[194:197], v[110:113]
	v_mfma_f32_16x16x32_bf16 v[106:109], v[162:165], v[194:197], v[106:109]
	v_mfma_f32_16x16x32_bf16 v[94:97], v[146:149], v[202:205], v[94:97]
	v_mfma_f32_16x16x32_bf16 v[90:93], v[162:165], v[202:205], v[90:93]
	v_mfma_f32_16x16x32_bf16 v[78:81], v[146:149], v[210:213], v[78:81]
	v_mfma_f32_16x16x32_bf16 v[74:77], v[162:165], v[210:213], v[74:77]
	v_mfma_f32_16x16x32_bf16 v[126:129], v[158:161], v[190:193], v[126:129]
	v_mfma_f32_16x16x32_bf16 v[122:125], v[166:169], v[190:193], v[122:125]
	v_mfma_f32_16x16x32_bf16 v[110:113], v[158:161], v[198:201], v[110:113]
	v_mfma_f32_16x16x32_bf16 v[106:109], v[166:169], v[198:201], v[106:109]
	v_mfma_f32_16x16x32_bf16 v[94:97], v[158:161], v[206:209], v[94:97]
	v_mfma_f32_16x16x32_bf16 v[90:93], v[166:169], v[206:209], v[90:93]
	v_mfma_f32_16x16x32_bf16 v[78:81], v[158:161], v[214:217], v[78:81]
	v_mfma_f32_16x16x32_bf16 v[74:77], v[166:169], v[214:217], v[74:77]
	v_mfma_f32_16x16x32_bf16 v[118:121], v[170:173], v[186:189], v[118:121]
	v_mfma_f32_16x16x32_bf16 v[114:117], v[178:181], v[186:189], v[114:117]
	v_mfma_f32_16x16x32_bf16 v[102:105], v[170:173], v[194:197], v[102:105]
	v_mfma_f32_16x16x32_bf16 v[98:101], v[178:181], v[194:197], v[98:101]
	v_mfma_f32_16x16x32_bf16 v[86:89], v[170:173], v[202:205], v[86:89]
	v_mfma_f32_16x16x32_bf16 v[82:85], v[178:181], v[202:205], v[82:85]
	v_mfma_f32_16x16x32_bf16 v[70:73], v[170:173], v[210:213], v[70:73]
	v_mfma_f32_16x16x32_bf16 v[66:69], v[178:181], v[210:213], v[66:69]
	v_mfma_f32_16x16x32_bf16 v[118:121], v[174:177], v[190:193], v[118:121]
	v_mfma_f32_16x16x32_bf16 v[114:117], v[182:185], v[190:193], v[114:117]
	v_mfma_f32_16x16x32_bf16 v[102:105], v[174:177], v[198:201], v[102:105]
	v_mfma_f32_16x16x32_bf16 v[98:101], v[182:185], v[198:201], v[98:101]
	v_mfma_f32_16x16x32_bf16 v[86:89], v[174:177], v[206:209], v[86:89]
	v_mfma_f32_16x16x32_bf16 v[82:85], v[182:185], v[206:209], v[82:85]
	v_mfma_f32_16x16x32_bf16 v[70:73], v[174:177], v[214:217], v[70:73]
	v_mfma_f32_16x16x32_bf16 v[66:69], v[182:185], v[214:217], v[66:69]
	s_barrier
	s_add_i32 s62, s57, s30
	v_lshl_add_u64 v[150:151], s[40:41], 0, v[132:133]
	s_mov_b32 m0, s62
	ds_read_b128 v[186:189], v156 offset:16384
	ds_read_b128 v[190:193], v156 offset:17408
	ds_read_b128 v[194:197], v156 offset:18432
	ds_read_b128 v[198:201], v156 offset:19456
	ds_read_b128 v[202:205], v156 offset:20480
	ds_read_b128 v[206:209], v156 offset:21504
	ds_read_b128 v[210:213], v156 offset:22528
	ds_read_b128 v[214:217], v156 offset:23552
	global_load_lds_dwordx4 v132, s[40:41]
	s_add_i32 m0, s62, 0x2000
	s_add_u32 s62, s40, 0x10000
	v_lshl_add_u64 v[218:219], s[40:41], 0, v[136:137]
	s_addc_u32 s63, s41, 0
	s_add_i32 s64, s58, s30
	global_load_lds_dwordx4 v136, s[40:41]
	s_mov_b32 m0, s64
	v_lshl_add_u64 v[222:223], s[42:43], 0, v[134:135]
	global_load_lds_dwordx4 v132, s[62:63]
	s_add_i32 m0, s64, 0x2000
	s_nop 0
	global_load_lds_dwordx4 v136, s[62:63]
	v_lshl_add_u64 v[220:221], s[42:43], 0, v[130:131]
	s_mov_b32 m0, s31
	s_nop 0
	global_load_lds_dwordx4 v130, s[42:43]
	s_mov_b32 m0, s33
	s_nop 0
	global_load_lds_dwordx4 v134, s[42:43]
	s_waitcnt vmcnt(8) lgkmcnt(0)
	s_barrier
	v_mfma_f32_16x16x32_bf16 v[62:65], v[146:149], v[186:189], v[62:65]
	v_mfma_f32_16x16x32_bf16 v[58:61], v[162:165], v[186:189], v[58:61]
	v_mfma_f32_16x16x32_bf16 v[46:49], v[146:149], v[194:197], v[46:49]
	v_mfma_f32_16x16x32_bf16 v[42:45], v[162:165], v[194:197], v[42:45]
	v_mfma_f32_16x16x32_bf16 v[30:33], v[146:149], v[202:205], v[30:33]
	v_mfma_f32_16x16x32_bf16 v[26:29], v[162:165], v[202:205], v[26:29]
	v_mfma_f32_16x16x32_bf16 v[14:17], v[146:149], v[210:213], v[14:17]
	v_mfma_f32_16x16x32_bf16 v[10:13], v[162:165], v[210:213], v[10:13]
	v_mfma_f32_16x16x32_bf16 v[62:65], v[158:161], v[190:193], v[62:65]
	v_mfma_f32_16x16x32_bf16 v[58:61], v[166:169], v[190:193], v[58:61]
	v_mfma_f32_16x16x32_bf16 v[46:49], v[158:161], v[198:201], v[46:49]
	v_mfma_f32_16x16x32_bf16 v[42:45], v[166:169], v[198:201], v[42:45]
	v_mfma_f32_16x16x32_bf16 v[30:33], v[158:161], v[206:209], v[30:33]
	v_mfma_f32_16x16x32_bf16 v[26:29], v[166:169], v[206:209], v[26:29]
	v_mfma_f32_16x16x32_bf16 v[14:17], v[158:161], v[214:217], v[14:17]
	v_mfma_f32_16x16x32_bf16 v[10:13], v[166:169], v[214:217], v[10:13]
	v_mfma_f32_16x16x32_bf16 v[54:57], v[170:173], v[186:189], v[54:57]
	v_mfma_f32_16x16x32_bf16 v[50:53], v[178:181], v[186:189], v[50:53]
	v_mfma_f32_16x16x32_bf16 v[38:41], v[170:173], v[194:197], v[38:41]
	v_mfma_f32_16x16x32_bf16 v[34:37], v[178:181], v[194:197], v[34:37]
	v_mfma_f32_16x16x32_bf16 v[22:25], v[170:173], v[202:205], v[22:25]
	v_mfma_f32_16x16x32_bf16 v[18:21], v[178:181], v[202:205], v[18:21]
	v_mfma_f32_16x16x32_bf16 v[6:9], v[170:173], v[210:213], v[6:9]
	v_mfma_f32_16x16x32_bf16 v[2:5], v[178:181], v[210:213], v[2:5]
	v_mfma_f32_16x16x32_bf16 v[54:57], v[174:177], v[190:193], v[54:57]
	v_mfma_f32_16x16x32_bf16 v[50:53], v[182:185], v[190:193], v[50:53]
	v_mfma_f32_16x16x32_bf16 v[38:41], v[174:177], v[198:201], v[38:41]
	v_mfma_f32_16x16x32_bf16 v[34:37], v[182:185], v[198:201], v[34:37]
	v_mfma_f32_16x16x32_bf16 v[22:25], v[174:177], v[206:209], v[22:25]
	v_mfma_f32_16x16x32_bf16 v[18:21], v[182:185], v[206:209], v[18:21]
	v_mfma_f32_16x16x32_bf16 v[6:9], v[174:177], v[214:217], v[6:9]
	v_mfma_f32_16x16x32_bf16 v[2:5], v[182:185], v[214:217], v[2:5]
	s_barrier
; #define PG8_STAGE(bufoff, gbase, voff) do { _Pragma("unroll") for (int _i = 0; _i < 2; ++_i) \
;         __builtin_amdgcn_global_load_lds((const unsigned*)((const char*)(gbase) + (voff)[_i]), (PG8_LAS unsigned*)(lds + (bufoff) + ldsw + _i * 8192), 16, 0, 0); } while (0)
; #define PG8_LDA(dst, b, h) do { _Pragma("unroll") for (int m = 0; m < 4; ++m) _Pragma("unroll") for (int k = 0; k < 2; ++k) dst[m][k] = *(const PG8_LAS bf16x8*)(lds + PG8_SA(b, h) + aoff + m * 2048 + k * 1024); } while (0)
; #define PG8_LDB(dst, b, h) do { _Pragma("unroll") for (int n = 0; n < 2; ++n) _Pragma("unroll") for (int k = 0; k < 2; ++k) dst[n][k] = *(const PG8_LAS bf16x8*)(lds + PG8_SB(b, h) + boff + n * 2048 + k * 1024); } while (0)
; #define PG8_MMA(ai, bj, At, Bt) do { __builtin_amdgcn_s_setprio(1); _Pragma("unroll") for (int m = 0; m < 4; ++m) _Pragma("unroll") for (int n = 0; n < 2; ++n) _Pragma("unroll") for (int k = 0; k < 2; ++k) \
;         acc[ai][bj][m][n] = __builtin_amdgcn_mfma_f32_16x16x32_bf16(Bt[n][k], At[m][k], acc[ai][bj][m][n], 0, 0, 0); __builtin_amdgcn_s_setprio(0); } while (0)
; #define PG8_WAIT_V(n) asm volatile("s_waitcnt vmcnt(" #n ")" ::: "memory")
; #define PG8_WAIT_L(n) asm volatile("s_waitcnt lgkmcnt(" #n ")" ::: "memory")
; #define PG8_BAR __builtin_amdgcn_s_barrier()
; #define PG8_SCHED __builtin_amdgcn_sched_barrier(0)
; template <class Epi, class Sched, bool ALIGN_EPI = false, bool SP2 = false>
; __device__ __forceinline__ void gemm_phase(PG8_LAS unsigned char* lds, const Gemm g, const Sched& S, const Epi& E) {
;     ...
;             PG8_LDB(B0, 1, 0); PG8_LDB(B1, 1, 1); PG8_SCHED; PG8_LDA(At, 1, 0); PG8_STAGE(PG8_SA(0, 1), a2 + hstep, voffA);
;             PG8_WAIT_V(8); PG8_WAIT_L(0); PG8_BAR; PG8_MMA(0, 0, At, B0); PG8_MMA(0, 1, At, B1); PG8_BAR; PG8_SCHED;
;             PG8_LDA(At, 1, 1); PG8_STAGE(PG8_SB(1, 0), b3, voffB); PG8_STAGE(PG8_SB(1, 1), b3 + hstepB, voffB); PG8_STAGE(PG8_SA(1, 0), a3, voffA);
;             PG8_WAIT_V(8); PG8_WAIT_L(0); PG8_BAR; PG8_MMA(1, 0, At, B0); PG8_MMA(1, 1, At, B1); PG8_BAR; PG8_SCHED;
	s_add_i32 s62, 0, 0x18000
	v_add_u32_e32 v157, s62, v152
	s_add_i32 s63, 0, 0x1c000
	ds_read_b128 v[146:149], v157
	ds_read_b128 v[158:161], v157 offset:1024
	ds_read_b128 v[162:165], v157 offset:2048
	ds_read_b128 v[166:169], v157 offset:3072
	v_add_u32_e32 v157, s63, v152
	ds_read_b128 v[170:173], v157
	ds_read_b128 v[174:177], v157 offset:1024
	ds_read_b128 v[178:181], v157 offset:2048
	ds_read_b128 v[182:185], v157 offset:3072
	s_add_u32 s42, s42, 0x40000
	s_addc_u32 s43, s43, 0
	s_mov_b32 m0, s44
	ds_read_b128 v[186:189], v156 offset:32768
	ds_read_b128 v[190:193], v156 offset:33792
	ds_read_b128 v[194:197], v156 offset:34816
	ds_read_b128 v[198:201], v156 offset:35840
	ds_read_b128 v[202:205], v156 offset:36864
	ds_read_b128 v[206:209], v156 offset:37888
	ds_read_b128 v[210:213], v156 offset:38912
	ds_read_b128 v[214:217], v156 offset:39936
	global_load_lds_dwordx4 v130, s[42:43]
	s_mov_b32 m0, s45
	s_nop 0
	global_load_lds_dwordx4 v134, s[42:43]
	s_waitcnt vmcnt(8) lgkmcnt(0)
	s_barrier
	v_mfma_f32_16x16x32_bf16 v[126:129], v[146:149], v[186:189], v[126:129]
	v_mfma_f32_16x16x32_bf16 v[122:125], v[162:165], v[186:189], v[122:125]
	v_mfma_f32_16x16x32_bf16 v[110:113], v[146:149], v[194:197], v[110:113]
	v_mfma_f32_16x16x32_bf16 v[106:109], v[162:165], v[194:197], v[106:109]
	v_mfma_f32_16x16x32_bf16 v[94:97], v[146:149], v[202:205], v[94:97]
	v_mfma_f32_16x16x32_bf16 v[90:93], v[162:165], v[202:205], v[90:93]
	v_mfma_f32_16x16x32_bf16 v[78:81], v[146:149], v[210:213], v[78:81]
	v_mfma_f32_16x16x32_bf16 v[74:77], v[162:165], v[210:213], v[74:77]
	v_mfma_f32_16x16x32_bf16 v[126:129], v[158:161], v[190:193], v[126:129]
	v_mfma_f32_16x16x32_bf16 v[122:125], v[166:169], v[190:193], v[122:125]
	v_mfma_f32_16x16x32_bf16 v[110:113], v[158:161], v[198:201], v[110:113]
	v_mfma_f32_16x16x32_bf16 v[106:109], v[166:169], v[198:201], v[106:109]
	v_mfma_f32_16x16x32_bf16 v[94:97], v[158:161], v[206:209], v[94:97]
	v_mfma_f32_16x16x32_bf16 v[90:93], v[166:169], v[206:209], v[90:93]
	v_mfma_f32_16x16x32_bf16 v[78:81], v[158:161], v[214:217], v[78:81]
	v_mfma_f32_16x16x32_bf16 v[74:77], v[166:169], v[214:217], v[74:77]
	v_mfma_f32_16x16x32_bf16 v[118:121], v[170:173], v[186:189], v[118:121]
	v_mfma_f32_16x16x32_bf16 v[114:117], v[178:181], v[186:189], v[114:117]
	v_mfma_f32_16x16x32_bf16 v[102:105], v[170:173], v[194:197], v[102:105]
	v_mfma_f32_16x16x32_bf16 v[98:101], v[178:181], v[194:197], v[98:101]
	v_mfma_f32_16x16x32_bf16 v[86:89], v[170:173], v[202:205], v[86:89]
	v_mfma_f32_16x16x32_bf16 v[82:85], v[178:181], v[202:205], v[82:85]
	v_mfma_f32_16x16x32_bf16 v[70:73], v[170:173], v[210:213], v[70:73]
	v_mfma_f32_16x16x32_bf16 v[66:69], v[178:181], v[210:213], v[66:69]
	v_mfma_f32_16x16x32_bf16 v[118:121], v[174:177], v[190:193], v[118:121]
	v_mfma_f32_16x16x32_bf16 v[114:117], v[182:185], v[190:193], v[114:117]
	v_mfma_f32_16x16x32_bf16 v[102:105], v[174:177], v[198:201], v[102:105]
	v_mfma_f32_16x16x32_bf16 v[98:101], v[182:185], v[198:201], v[98:101]
	v_mfma_f32_16x16x32_bf16 v[86:89], v[174:177], v[206:209], v[86:89]
	v_mfma_f32_16x16x32_bf16 v[82:85], v[182:185], v[206:209], v[82:85]
	v_mfma_f32_16x16x32_bf16 v[70:73], v[174:177], v[214:217], v[70:73]
	v_mfma_f32_16x16x32_bf16 v[66:69], v[182:185], v[214:217], v[66:69]
	s_barrier
	s_add_i32 s42, s62, s30
	v_lshl_add_u64 v[150:151], v[150:151], 0, s[10:11]
	s_mov_b32 m0, s42
	ds_read_b128 v[186:189], v156 offset:49152
	ds_read_b128 v[190:193], v156 offset:50176
	ds_read_b128 v[194:197], v156 offset:51200
	ds_read_b128 v[198:201], v156 offset:52224
	ds_read_b128 v[202:205], v156 offset:53248
	ds_read_b128 v[206:209], v156 offset:54272
	ds_read_b128 v[210:213], v156 offset:55296
	ds_read_b128 v[214:217], v156 offset:56320
	global_load_lds_dwordx4 v[150:151], off
	s_add_i32 m0, s42, 0x2000
	s_add_u32 s40, s40, 0x10080
	v_lshl_add_u64 v[150:151], v[218:219], 0, s[10:11]
	s_addc_u32 s41, s41, 0
	s_add_i32 s42, s63, s30
	global_load_lds_dwordx4 v[150:151], off
	s_mov_b32 m0, s42
	s_nop 0
	global_load_lds_dwordx4 v132, s[40:41]
	s_add_i32 m0, s42, 0x2000
	s_nop 0
	global_load_lds_dwordx4 v136, s[40:41]
	v_lshl_add_u64 v[150:151], v[220:221], 0, s[10:11]
	s_mov_b32 m0, s47
	s_nop 0
	global_load_lds_dwordx4 v[150:151], off
	v_lshl_add_u64 v[150:151], v[222:223], 0, s[10:11]
	s_mov_b32 m0, s54
	s_nop 0
	global_load_lds_dwordx4 v[150:151], off
	s_waitcnt vmcnt(8) lgkmcnt(0)
	s_barrier
	v_mfma_f32_16x16x32_bf16 v[62:65], v[146:149], v[186:189], v[62:65]
	v_mfma_f32_16x16x32_bf16 v[58:61], v[162:165], v[186:189], v[58:61]
	v_mfma_f32_16x16x32_bf16 v[46:49], v[146:149], v[194:197], v[46:49]
	v_mfma_f32_16x16x32_bf16 v[42:45], v[162:165], v[194:197], v[42:45]
	v_mfma_f32_16x16x32_bf16 v[30:33], v[146:149], v[202:205], v[30:33]
	v_mfma_f32_16x16x32_bf16 v[26:29], v[162:165], v[202:205], v[26:29]
	v_mfma_f32_16x16x32_bf16 v[14:17], v[146:149], v[210:213], v[14:17]
	v_mfma_f32_16x16x32_bf16 v[10:13], v[162:165], v[210:213], v[10:13]
	v_mfma_f32_16x16x32_bf16 v[62:65], v[158:161], v[190:193], v[62:65]
	v_mfma_f32_16x16x32_bf16 v[58:61], v[166:169], v[190:193], v[58:61]
	v_mfma_f32_16x16x32_bf16 v[46:49], v[158:161], v[198:201], v[46:49]
	v_mfma_f32_16x16x32_bf16 v[42:45], v[166:169], v[198:201], v[42:45]
	v_mfma_f32_16x16x32_bf16 v[30:33], v[158:161], v[206:209], v[30:33]
	v_mfma_f32_16x16x32_bf16 v[26:29], v[166:169], v[206:209], v[26:29]
	v_mfma_f32_16x16x32_bf16 v[14:17], v[158:161], v[214:217], v[14:17]
	v_mfma_f32_16x16x32_bf16 v[10:13], v[166:169], v[214:217], v[10:13]
	v_mfma_f32_16x16x32_bf16 v[54:57], v[170:173], v[186:189], v[54:57]
	v_mfma_f32_16x16x32_bf16 v[50:53], v[178:181], v[186:189], v[50:53]
	v_mfma_f32_16x16x32_bf16 v[38:41], v[170:173], v[194:197], v[38:41]
	v_mfma_f32_16x16x32_bf16 v[34:37], v[178:181], v[194:197], v[34:37]
	v_mfma_f32_16x16x32_bf16 v[22:25], v[170:173], v[202:205], v[22:25]
	v_mfma_f32_16x16x32_bf16 v[18:21], v[178:181], v[202:205], v[18:21]
	v_mfma_f32_16x16x32_bf16 v[6:9], v[170:173], v[210:213], v[6:9]
	v_mfma_f32_16x16x32_bf16 v[2:5], v[178:181], v[210:213], v[2:5]
	v_mfma_f32_16x16x32_bf16 v[54:57], v[174:177], v[190:193], v[54:57]
	v_mfma_f32_16x16x32_bf16 v[50:53], v[182:185], v[190:193], v[50:53]
	v_mfma_f32_16x16x32_bf16 v[38:41], v[174:177], v[198:201], v[38:41]
	v_mfma_f32_16x16x32_bf16 v[34:37], v[182:185], v[198:201], v[34:37]
	v_mfma_f32_16x16x32_bf16 v[22:25], v[174:177], v[206:209], v[22:25]
	v_mfma_f32_16x16x32_bf16 v[18:21], v[182:185], v[206:209], v[18:21]
	v_mfma_f32_16x16x32_bf16 v[6:9], v[174:177], v[214:217], v[6:9]
	v_mfma_f32_16x16x32_bf16 v[2:5], v[182:185], v[214:217], v[2:5]
	s_barrier
	s_add_i32 s61, s61, 2
	s_add_u32 s38, s38, 0x100
	s_addc_u32 s39, s39, 0
	s_add_u32 s59, s59, 0x100
	s_addc_u32 s60, s60, 0
	s_cmp_gt_u32 s61, 13
	s_cbranch_scc0 .LBB0_1313

; #define PG8_STAGE(bufoff, gbase, voff) do { _Pragma("unroll") for (int _i = 0; _i < 2; ++_i) \
;         __builtin_amdgcn_global_load_lds((const unsigned*)((const char*)(gbase) + (voff)[_i]), (PG8_LAS unsigned*)(lds + (bufoff) + ldsw + _i * 8192), 16, 0, 0); } while (0)
; #define PG8_LDA(dst, b, h) do { _Pragma("unroll") for (int m = 0; m < 4; ++m) _Pragma("unroll") for (int k = 0; k < 2; ++k) dst[m][k] = *(const PG8_LAS bf16x8*)(lds + PG8_SA(b, h) + aoff + m * 2048 + k * 1024); } while (0)
; #define PG8_LDB(dst, b, h) do { _Pragma("unroll") for (int n = 0; n < 2; ++n) _Pragma("unroll") for (int k = 0; k < 2; ++k) dst[n][k] = *(const PG8_LAS bf16x8*)(lds + PG8_SB(b, h) + boff + n * 2048 + k * 1024); } while (0)
; #define PG8_MMA(ai, bj, At, Bt) do { __builtin_amdgcn_s_setprio(1); _Pragma("unroll") for (int m = 0; m < 4; ++m) _Pragma("unroll") for (int n = 0; n < 2; ++n) _Pragma("unroll") for (int k = 0; k < 2; ++k) \
;         acc[ai][bj][m][n] = __builtin_amdgcn_mfma_f32_16x16x32_bf16(Bt[n][k], At[m][k], acc[ai][bj][m][n], 0, 0, 0); __builtin_amdgcn_s_setprio(0); } while (0)
; #define PG8_WAIT_V(n) asm volatile("s_waitcnt vmcnt(" #n ")" ::: "memory")
; #define PG8_WAIT_L(n) asm volatile("s_waitcnt lgkmcnt(" #n ")" ::: "memory")
; #define PG8_BAR __builtin_amdgcn_s_barrier()
; #define PG8_SCHED __builtin_amdgcn_sched_barrier(0)
; template <class Epi, class Sched, bool ALIGN_EPI = false, bool SP2 = false>
; __device__ __forceinline__ void gemm_phase(PG8_LAS unsigned char* lds, const Gemm g, const Sched& S, const Epi& E) {
;     ...
;             const bool last = (t == nt - 2);
;             const char* a1 = cA + (size_t)(t + 1) * kstep;
;             const char* a2 = last ? nA : cA + (size_t)(t + 2) * kstep; const char* b2 = last ? nB : cB + (size_t)(t + 2) * kstep;
;             const char* a3 = a2 + kstep; const char* b3 = b2 + kstep;
;             if (last && has_next) S.a_ready(nxt);
;             if constexpr (SP2) {
;             PG8_LDB(B0, 0, 0); PG8_LDB(B1, 0, 1); PG8_SCHED; PG8_LDA(At, 0, 0); PG8_STAGE(PG8_SA(1, 1), a1 + hstep, voffA);
;             PG8_WAIT_V(8); PG8_WAIT_L(0); PG8_BAR; PG8_MMA(0, 0, At, B0); PG8_MMA(0, 1, At, B1); PG8_BAR; PG8_SCHED;
;             PG8_LDA(At, 0, 1); PG8_STAGE(PG8_SB(0, 0), b2, voffB); PG8_STAGE(PG8_SB(0, 1), b2 + hstepB, voffB); PG8_STAGE(PG8_SA(0, 0), a2, voffA);
.LBB0_1429:
	v_add_u32_e32 v164, s43, v150
	v_add_u32_e32 v180, s44, v150
	s_add_u32 s26, s8, s24
	ds_read_b128 v[152:155], v164
	ds_read_b128 v[156:159], v164 offset:1024
	ds_read_b128 v[160:163], v164 offset:2048
	ds_read_b128 v[164:167], v164 offset:3072
	ds_read_b128 v[168:171], v180
	ds_read_b128 v[172:175], v180 offset:1024
	ds_read_b128 v[176:179], v180 offset:2048
	ds_read_b128 v[180:183], v180 offset:3072
	s_addc_u32 s27, s9, s25
	s_add_u32 s26, s26, 0x100
	s_addc_u32 s27, s27, 0
	s_add_u32 s55, s21, s24
	s_addc_u32 s56, s45, s25
	s_cmpk_eq_i32 s24, 0x1f00
	s_cselect_b32 s29, s17, s27
	s_cselect_b32 s28, s46, s26
	s_cselect_b32 s27, s15, s56
	s_cselect_b32 s26, s47, s55
	v_lshl_add_u64 v[212:213], v[146:147], 0, s[24:25]
	s_add_i32 m0, s35, 0xc000
	ds_read_b128 v[184:187], v151
	ds_read_b128 v[188:191], v151 offset:1024
	ds_read_b128 v[192:195], v151 offset:2048
	ds_read_b128 v[196:199], v151 offset:3072
	ds_read_b128 v[200:203], v151 offset:4096
	ds_read_b128 v[204:207], v151 offset:5120
	ds_read_b128 v[208:211], v151 offset:6144
	ds_read_b128 v[218:221], v151 offset:7168
	global_load_lds_dwordx4 v[212:213], off
	v_lshl_add_u64 v[212:213], v[148:149], 0, s[24:25]
	s_add_i32 m0, s35, 0xe000
	s_nop 0
	global_load_lds_dwordx4 v[212:213], off
	s_waitcnt vmcnt(8) lgkmcnt(0)
	s_barrier
	v_mfma_f32_16x16x32_bf16 v[126:129], v[152:155], v[184:187], v[126:129]
	v_mfma_f32_16x16x32_bf16 v[122:125], v[160:163], v[184:187], v[122:125]
	v_mfma_f32_16x16x32_bf16 v[110:113], v[152:155], v[192:195], v[110:113]
	v_mfma_f32_16x16x32_bf16 v[106:109], v[160:163], v[192:195], v[106:109]
	v_mfma_f32_16x16x32_bf16 v[94:97], v[152:155], v[200:203], v[94:97]
	v_mfma_f32_16x16x32_bf16 v[90:93], v[160:163], v[200:203], v[90:93]
	v_mfma_f32_16x16x32_bf16 v[78:81], v[152:155], v[208:211], v[78:81]
	v_mfma_f32_16x16x32_bf16 v[74:77], v[160:163], v[208:211], v[74:77]
	v_mfma_f32_16x16x32_bf16 v[126:129], v[156:159], v[188:191], v[126:129]
	v_mfma_f32_16x16x32_bf16 v[122:125], v[164:167], v[188:191], v[122:125]
	v_mfma_f32_16x16x32_bf16 v[110:113], v[156:159], v[196:199], v[110:113]
	v_mfma_f32_16x16x32_bf16 v[106:109], v[164:167], v[196:199], v[106:109]
	v_mfma_f32_16x16x32_bf16 v[94:97], v[156:159], v[204:207], v[94:97]
	v_mfma_f32_16x16x32_bf16 v[90:93], v[164:167], v[204:207], v[90:93]
	v_mfma_f32_16x16x32_bf16 v[78:81], v[156:159], v[218:221], v[78:81]
	v_mfma_f32_16x16x32_bf16 v[74:77], v[164:167], v[218:221], v[74:77]
	v_mfma_f32_16x16x32_bf16 v[118:121], v[168:171], v[184:187], v[118:121]
	v_mfma_f32_16x16x32_bf16 v[114:117], v[176:179], v[184:187], v[114:117]
	v_mfma_f32_16x16x32_bf16 v[102:105], v[168:171], v[192:195], v[102:105]
	v_mfma_f32_16x16x32_bf16 v[98:101], v[176:179], v[192:195], v[98:101]
	v_mfma_f32_16x16x32_bf16 v[86:89], v[168:171], v[200:203], v[86:89]
	v_mfma_f32_16x16x32_bf16 v[82:85], v[176:179], v[200:203], v[82:85]
	v_mfma_f32_16x16x32_bf16 v[70:73], v[168:171], v[208:211], v[70:73]
	v_mfma_f32_16x16x32_bf16 v[66:69], v[176:179], v[208:211], v[66:69]
	v_mfma_f32_16x16x32_bf16 v[118:121], v[172:175], v[188:191], v[118:121]
	v_mfma_f32_16x16x32_bf16 v[114:117], v[180:183], v[188:191], v[114:117]
	v_mfma_f32_16x16x32_bf16 v[102:105], v[172:175], v[196:199], v[102:105]
	v_mfma_f32_16x16x32_bf16 v[98:101], v[180:183], v[196:199], v[98:101]
	v_mfma_f32_16x16x32_bf16 v[86:89], v[172:175], v[204:207], v[86:89]
	v_mfma_f32_16x16x32_bf16 v[82:85], v[180:183], v[204:207], v[82:85]
	v_mfma_f32_16x16x32_bf16 v[70:73], v[172:175], v[218:221], v[70:73]
	v_mfma_f32_16x16x32_bf16 v[66:69], v[180:183], v[218:221], v[66:69]
	s_barrier
	s_add_i32 s55, s43, s34
	v_lshl_add_u64 v[212:213], s[26:27], 0, v[132:133]
	s_mov_b32 m0, s55
	ds_read_b128 v[184:187], v151 offset:16384
	ds_read_b128 v[188:191], v151 offset:17408
	ds_read_b128 v[192:195], v151 offset:18432
	ds_read_b128 v[196:199], v151 offset:19456
	ds_read_b128 v[200:203], v151 offset:20480
	ds_read_b128 v[204:207], v151 offset:21504
	ds_read_b128 v[208:211], v151 offset:22528
	ds_read_b128 v[218:221], v151 offset:23552
	global_load_lds_dwordx4 v132, s[26:27]
	s_add_i32 m0, s55, 0x2000
	s_add_u32 s56, s26, 0x40000
	v_lshl_add_u64 v[222:223], s[26:27], 0, v[136:137]
	s_addc_u32 s57, s27, 0
	s_add_i32 s55, s44, s34
	global_load_lds_dwordx4 v136, s[26:27]
	s_mov_b32 m0, s55
	v_lshl_add_u64 v[226:227], s[28:29], 0, v[134:135]
	global_load_lds_dwordx4 v132, s[56:57]
	s_add_i32 m0, s55, 0x2000
	s_nop 0
	global_load_lds_dwordx4 v136, s[56:57]
	v_lshl_add_u64 v[224:225], s[28:29], 0, v[130:131]
	s_mov_b32 m0, s35
	s_nop 0
	global_load_lds_dwordx4 v130, s[28:29]
	s_mov_b32 m0, s36
	s_nop 0
	global_load_lds_dwordx4 v134, s[28:29]
	s_waitcnt vmcnt(8) lgkmcnt(0)
	s_barrier
; #define PG8_STAGE(bufoff, gbase, voff) do { _Pragma("unroll") for (int _i = 0; _i < 2; ++_i) \
;         __builtin_amdgcn_global_load_lds((const unsigned*)((const char*)(gbase) + (voff)[_i]), (PG8_LAS unsigned*)(lds + (bufoff) + ldsw + _i * 8192), 16, 0, 0); } while (0)
; #define PG8_LDA(dst, b, h) do { _Pragma("unroll") for (int m = 0; m < 4; ++m) _Pragma("unroll") for (int k = 0; k < 2; ++k) dst[m][k] = *(const PG8_LAS bf16x8*)(lds + PG8_SA(b, h) + aoff + m * 2048 + k * 1024); } while (0)
; #define PG8_LDB(dst, b, h) do { _Pragma("unroll") for (int n = 0; n < 2; ++n) _Pragma("unroll") for (int k = 0; k < 2; ++k) dst[n][k] = *(const PG8_LAS bf16x8*)(lds + PG8_SB(b, h) + boff + n * 2048 + k * 1024); } while (0)
; #define PG8_MMA(ai, bj, At, Bt) do { __builtin_amdgcn_s_setprio(1); _Pragma("unroll") for (int m = 0; m < 4; ++m) _Pragma("unroll") for (int n = 0; n < 2; ++n) _Pragma("unroll") for (int k = 0; k < 2; ++k) \
;         acc[ai][bj][m][n] = __builtin_amdgcn_mfma_f32_16x16x32_bf16(Bt[n][k], At[m][k], acc[ai][bj][m][n], 0, 0, 0); __builtin_amdgcn_s_setprio(0); } while (0)
; #define PG8_WAIT_V(n) asm volatile("s_waitcnt vmcnt(" #n ")" ::: "memory")
; #define PG8_WAIT_L(n) asm volatile("s_waitcnt lgkmcnt(" #n ")" ::: "memory")
; #define PG8_BAR __builtin_amdgcn_s_barrier()
; #define PG8_SCHED __builtin_amdgcn_sched_barrier(0)
; template <class Epi, class Sched, bool ALIGN_EPI = false, bool SP2 = false>
; __device__ __forceinline__ void gemm_phase(PG8_LAS unsigned char* lds, const Gemm g, const Sched& S, const Epi& E) {
;     ...
;             PG8_WAIT_V(8); PG8_WAIT_L(0); PG8_BAR; PG8_MMA(1, 0, At, B0); PG8_MMA(1, 1, At, B1); PG8_BAR; PG8_SCHED;
;             PG8_LDB(B0, 1, 0); PG8_LDB(B1, 1, 1); PG8_SCHED; PG8_LDA(At, 1, 0); PG8_STAGE(PG8_SA(0, 1), a2 + hstep, voffA);
;             PG8_WAIT_V(8); PG8_WAIT_L(0); PG8_BAR; PG8_MMA(0, 0, At, B0); PG8_MMA(0, 1, At, B1); PG8_BAR; PG8_SCHED;
	v_mfma_f32_16x16x32_bf16 v[62:65], v[152:155], v[184:187], v[62:65]
	v_mfma_f32_16x16x32_bf16 v[58:61], v[160:163], v[184:187], v[58:61]
	v_mfma_f32_16x16x32_bf16 v[46:49], v[152:155], v[192:195], v[46:49]
	v_mfma_f32_16x16x32_bf16 v[42:45], v[160:163], v[192:195], v[42:45]
	v_mfma_f32_16x16x32_bf16 v[30:33], v[152:155], v[200:203], v[30:33]
	v_mfma_f32_16x16x32_bf16 v[26:29], v[160:163], v[200:203], v[26:29]
	v_mfma_f32_16x16x32_bf16 v[14:17], v[152:155], v[208:211], v[14:17]
	v_mfma_f32_16x16x32_bf16 v[10:13], v[160:163], v[208:211], v[10:13]
	v_mfma_f32_16x16x32_bf16 v[62:65], v[156:159], v[188:191], v[62:65]
	v_mfma_f32_16x16x32_bf16 v[58:61], v[164:167], v[188:191], v[58:61]
	v_mfma_f32_16x16x32_bf16 v[46:49], v[156:159], v[196:199], v[46:49]
	v_mfma_f32_16x16x32_bf16 v[42:45], v[164:167], v[196:199], v[42:45]
	v_mfma_f32_16x16x32_bf16 v[30:33], v[156:159], v[204:207], v[30:33]
	v_mfma_f32_16x16x32_bf16 v[26:29], v[164:167], v[204:207], v[26:29]
	v_mfma_f32_16x16x32_bf16 v[14:17], v[156:159], v[218:221], v[14:17]
	v_mfma_f32_16x16x32_bf16 v[10:13], v[164:167], v[218:221], v[10:13]
	v_mfma_f32_16x16x32_bf16 v[54:57], v[168:171], v[184:187], v[54:57]
	v_mfma_f32_16x16x32_bf16 v[50:53], v[176:179], v[184:187], v[50:53]
	v_mfma_f32_16x16x32_bf16 v[38:41], v[168:171], v[192:195], v[38:41]
	v_mfma_f32_16x16x32_bf16 v[34:37], v[176:179], v[192:195], v[34:37]
	v_mfma_f32_16x16x32_bf16 v[22:25], v[168:171], v[200:203], v[22:25]
	v_mfma_f32_16x16x32_bf16 v[18:21], v[176:179], v[200:203], v[18:21]
	v_mfma_f32_16x16x32_bf16 v[6:9], v[168:171], v[208:211], v[6:9]
	v_mfma_f32_16x16x32_bf16 v[2:5], v[176:179], v[208:211], v[2:5]
	v_mfma_f32_16x16x32_bf16 v[54:57], v[172:175], v[188:191], v[54:57]
	v_mfma_f32_16x16x32_bf16 v[50:53], v[180:183], v[188:191], v[50:53]
	v_mfma_f32_16x16x32_bf16 v[38:41], v[172:175], v[196:199], v[38:41]
	v_mfma_f32_16x16x32_bf16 v[34:37], v[180:183], v[196:199], v[34:37]
	v_mfma_f32_16x16x32_bf16 v[22:25], v[172:175], v[204:207], v[22:25]
	v_mfma_f32_16x16x32_bf16 v[18:21], v[180:183], v[204:207], v[18:21]
	v_mfma_f32_16x16x32_bf16 v[6:9], v[172:175], v[218:221], v[6:9]
	v_mfma_f32_16x16x32_bf16 v[2:5], v[180:183], v[218:221], v[2:5]
	s_barrier
	s_add_i32 s55, 0, 0x18000
	s_add_i32 s56, 0, 0x1c000
	v_add_u32_e32 v164, s55, v150
	v_add_u32_e32 v180, s56, v150
	ds_read_b128 v[152:155], v164
	ds_read_b128 v[156:159], v164 offset:1024
	ds_read_b128 v[160:163], v164 offset:2048
	ds_read_b128 v[164:167], v164 offset:3072
	ds_read_b128 v[168:171], v180
	ds_read_b128 v[172:175], v180 offset:1024
	ds_read_b128 v[176:179], v180 offset:2048
	ds_read_b128 v[180:183], v180 offset:3072
	s_add_u32 s28, s28, 0x100000
	s_addc_u32 s29, s29, 0
	s_mov_b32 m0, s37
	ds_read_b128 v[184:187], v151 offset:32768
	ds_read_b128 v[188:191], v151 offset:33792
	ds_read_b128 v[192:195], v151 offset:34816
	ds_read_b128 v[196:199], v151 offset:35840
	ds_read_b128 v[200:203], v151 offset:36864
	ds_read_b128 v[204:207], v151 offset:37888
	ds_read_b128 v[208:211], v151 offset:38912
	ds_read_b128 v[218:221], v151 offset:39936
	global_load_lds_dwordx4 v130, s[28:29]
	s_mov_b32 m0, s39
	s_nop 0
	global_load_lds_dwordx4 v134, s[28:29]
	s_waitcnt vmcnt(8) lgkmcnt(0)
	s_barrier
	v_mfma_f32_16x16x32_bf16 v[126:129], v[152:155], v[184:187], v[126:129]
	v_mfma_f32_16x16x32_bf16 v[122:125], v[160:163], v[184:187], v[122:125]
	v_mfma_f32_16x16x32_bf16 v[110:113], v[152:155], v[192:195], v[110:113]
	v_mfma_f32_16x16x32_bf16 v[106:109], v[160:163], v[192:195], v[106:109]
	v_mfma_f32_16x16x32_bf16 v[94:97], v[152:155], v[200:203], v[94:97]
	v_mfma_f32_16x16x32_bf16 v[90:93], v[160:163], v[200:203], v[90:93]
	v_mfma_f32_16x16x32_bf16 v[78:81], v[152:155], v[208:211], v[78:81]
	v_mfma_f32_16x16x32_bf16 v[74:77], v[160:163], v[208:211], v[74:77]
	v_mfma_f32_16x16x32_bf16 v[126:129], v[156:159], v[188:191], v[126:129]
	v_mfma_f32_16x16x32_bf16 v[122:125], v[164:167], v[188:191], v[122:125]
	v_mfma_f32_16x16x32_bf16 v[110:113], v[156:159], v[196:199], v[110:113]
	v_mfma_f32_16x16x32_bf16 v[106:109], v[164:167], v[196:199], v[106:109]
	v_mfma_f32_16x16x32_bf16 v[94:97], v[156:159], v[204:207], v[94:97]
	v_mfma_f32_16x16x32_bf16 v[90:93], v[164:167], v[204:207], v[90:93]
	v_mfma_f32_16x16x32_bf16 v[78:81], v[156:159], v[218:221], v[78:81]
	v_mfma_f32_16x16x32_bf16 v[74:77], v[164:167], v[218:221], v[74:77]
	v_mfma_f32_16x16x32_bf16 v[118:121], v[168:171], v[184:187], v[118:121]
	v_mfma_f32_16x16x32_bf16 v[114:117], v[176:179], v[184:187], v[114:117]
	v_mfma_f32_16x16x32_bf16 v[102:105], v[168:171], v[192:195], v[102:105]
	v_mfma_f32_16x16x32_bf16 v[98:101], v[176:179], v[192:195], v[98:101]
	v_mfma_f32_16x16x32_bf16 v[86:89], v[168:171], v[200:203], v[86:89]
	v_mfma_f32_16x16x32_bf16 v[82:85], v[176:179], v[200:203], v[82:85]
	v_mfma_f32_16x16x32_bf16 v[70:73], v[168:171], v[208:211], v[70:73]
	v_mfma_f32_16x16x32_bf16 v[66:69], v[176:179], v[208:211], v[66:69]
	v_mfma_f32_16x16x32_bf16 v[118:121], v[172:175], v[188:191], v[118:121]
	v_mfma_f32_16x16x32_bf16 v[114:117], v[180:183], v[188:191], v[114:117]
	v_mfma_f32_16x16x32_bf16 v[102:105], v[172:175], v[196:199], v[102:105]
	v_mfma_f32_16x16x32_bf16 v[98:101], v[180:183], v[196:199], v[98:101]
	v_mfma_f32_16x16x32_bf16 v[86:89], v[172:175], v[204:207], v[86:89]
	v_mfma_f32_16x16x32_bf16 v[82:85], v[180:183], v[204:207], v[82:85]
	v_mfma_f32_16x16x32_bf16 v[70:73], v[172:175], v[218:221], v[70:73]
	v_mfma_f32_16x16x32_bf16 v[66:69], v[180:183], v[218:221], v[66:69]
	s_barrier
; #define PG8_STAGE(bufoff, gbase, voff) do { _Pragma("unroll") for (int _i = 0; _i < 2; ++_i) \
;         __builtin_amdgcn_global_load_lds((const unsigned*)((const char*)(gbase) + (voff)[_i]), (PG8_LAS unsigned*)(lds + (bufoff) + ldsw + _i * 8192), 16, 0, 0); } while (0)
; #define PG8_LDA(dst, b, h) do { _Pragma("unroll") for (int m = 0; m < 4; ++m) _Pragma("unroll") for (int k = 0; k < 2; ++k) dst[m][k] = *(const PG8_LAS bf16x8*)(lds + PG8_SA(b, h) + aoff + m * 2048 + k * 1024); } while (0)
; #define PG8_MMA(ai, bj, At, Bt) do { __builtin_amdgcn_s_setprio(1); _Pragma("unroll") for (int m = 0; m < 4; ++m) _Pragma("unroll") for (int n = 0; n < 2; ++n) _Pragma("unroll") for (int k = 0; k < 2; ++k) \
;         acc[ai][bj][m][n] = __builtin_amdgcn_mfma_f32_16x16x32_bf16(Bt[n][k], At[m][k], acc[ai][bj][m][n], 0, 0, 0); __builtin_amdgcn_s_setprio(0); } while (0)
; #define PG8_WAIT_V(n) asm volatile("s_waitcnt vmcnt(" #n ")" ::: "memory")
; #define PG8_WAIT_L(n) asm volatile("s_waitcnt lgkmcnt(" #n ")" ::: "memory")
; #define PG8_BAR __builtin_amdgcn_s_barrier()
; #define PG8_SCHED __builtin_amdgcn_sched_barrier(0)
; template <class Epi, class Sched, bool ALIGN_EPI = false, bool SP2 = false>
; __device__ __forceinline__ void gemm_phase(PG8_LAS unsigned char* lds, const Gemm g, const Sched& S, const Epi& E) {
;     ...
;             PG8_LDA(At, 1, 1); PG8_STAGE(PG8_SB(1, 0), b3, voffB); PG8_STAGE(PG8_SB(1, 1), b3 + hstepB, voffB); PG8_STAGE(PG8_SA(1, 0), a3, voffA);
;             PG8_WAIT_V(8); PG8_WAIT_L(0); PG8_BAR; PG8_MMA(1, 0, At, B0); PG8_MMA(1, 1, At, B1); PG8_BAR; PG8_SCHED;
;     ...
;         if (!has_next) break;
; #pragma unroll
;         for (int a = 0; a < 2; ++a)
; #pragma unroll
;             for (int b = 0; b < 2; ++b)
; #pragma unroll
;                 for (int m = 0; m < 4; ++m)
; #pragma unroll
;                     for (int n = 0; n < 2; ++n) acc[a][b][m][n] = (f32x4){0.f, 0.f, 0.f, 0.f};
;         cur = nxt; cA = nA; cB = nB; ++ui;
	s_add_i32 s28, s55, s34
	v_lshl_add_u64 v[212:213], v[212:213], 0, s[10:11]
	s_mov_b32 m0, s28
	ds_read_b128 v[184:187], v151 offset:49152
	ds_read_b128 v[188:191], v151 offset:50176
	ds_read_b128 v[192:195], v151 offset:51200
	ds_read_b128 v[196:199], v151 offset:52224
	ds_read_b128 v[200:203], v151 offset:53248
	ds_read_b128 v[204:207], v151 offset:54272
	ds_read_b128 v[208:211], v151 offset:55296
	ds_read_b128 v[218:221], v151 offset:56320
	global_load_lds_dwordx4 v[212:213], off
	s_add_i32 m0, s28, 0x2000
	s_add_u32 s26, s26, 0x40080
	v_lshl_add_u64 v[212:213], v[222:223], 0, s[10:11]
	s_addc_u32 s27, s27, 0
	s_add_i32 s28, s56, s34
	global_load_lds_dwordx4 v[212:213], off
	s_mov_b32 m0, s28
	s_nop 0
	global_load_lds_dwordx4 v132, s[26:27]
	s_add_i32 m0, s28, 0x2000
	s_nop 0
	global_load_lds_dwordx4 v136, s[26:27]
	v_lshl_add_u64 v[212:213], v[224:225], 0, s[10:11]
	s_mov_b32 m0, s40
	s_nop 0
	global_load_lds_dwordx4 v[212:213], off
	v_lshl_add_u64 v[212:213], v[226:227], 0, s[10:11]
	s_mov_b32 m0, s41
	s_nop 0
	global_load_lds_dwordx4 v[212:213], off
	s_waitcnt vmcnt(8) lgkmcnt(0)
	s_barrier
	v_mfma_f32_16x16x32_bf16 v[62:65], v[152:155], v[184:187], v[62:65]
	v_mfma_f32_16x16x32_bf16 v[58:61], v[160:163], v[184:187], v[58:61]
	v_mfma_f32_16x16x32_bf16 v[46:49], v[152:155], v[192:195], v[46:49]
	v_mfma_f32_16x16x32_bf16 v[42:45], v[160:163], v[192:195], v[42:45]
	v_mfma_f32_16x16x32_bf16 v[30:33], v[152:155], v[200:203], v[30:33]
	v_mfma_f32_16x16x32_bf16 v[26:29], v[160:163], v[200:203], v[26:29]
	v_mfma_f32_16x16x32_bf16 v[14:17], v[152:155], v[208:211], v[14:17]
	v_mfma_f32_16x16x32_bf16 v[10:13], v[160:163], v[208:211], v[10:13]
	v_mfma_f32_16x16x32_bf16 v[62:65], v[156:159], v[188:191], v[62:65]
	v_mfma_f32_16x16x32_bf16 v[58:61], v[164:167], v[188:191], v[58:61]
	v_mfma_f32_16x16x32_bf16 v[46:49], v[156:159], v[196:199], v[46:49]
	v_mfma_f32_16x16x32_bf16 v[42:45], v[164:167], v[196:199], v[42:45]
	v_mfma_f32_16x16x32_bf16 v[30:33], v[156:159], v[204:207], v[30:33]
	v_mfma_f32_16x16x32_bf16 v[26:29], v[164:167], v[204:207], v[26:29]
	v_mfma_f32_16x16x32_bf16 v[14:17], v[156:159], v[218:221], v[14:17]
	v_mfma_f32_16x16x32_bf16 v[10:13], v[164:167], v[218:221], v[10:13]
	v_mfma_f32_16x16x32_bf16 v[54:57], v[168:171], v[184:187], v[54:57]
	v_mfma_f32_16x16x32_bf16 v[50:53], v[176:179], v[184:187], v[50:53]
	v_mfma_f32_16x16x32_bf16 v[38:41], v[168:171], v[192:195], v[38:41]
	v_mfma_f32_16x16x32_bf16 v[34:37], v[176:179], v[192:195], v[34:37]
	v_mfma_f32_16x16x32_bf16 v[22:25], v[168:171], v[200:203], v[22:25]
	v_mfma_f32_16x16x32_bf16 v[18:21], v[176:179], v[200:203], v[18:21]
	v_mfma_f32_16x16x32_bf16 v[6:9], v[168:171], v[208:211], v[6:9]
	v_mfma_f32_16x16x32_bf16 v[2:5], v[176:179], v[208:211], v[2:5]
	v_mfma_f32_16x16x32_bf16 v[54:57], v[172:175], v[188:191], v[54:57]
	v_mfma_f32_16x16x32_bf16 v[50:53], v[180:183], v[188:191], v[50:53]
	v_mfma_f32_16x16x32_bf16 v[38:41], v[172:175], v[196:199], v[38:41]
	v_mfma_f32_16x16x32_bf16 v[34:37], v[180:183], v[196:199], v[34:37]
	v_mfma_f32_16x16x32_bf16 v[22:25], v[172:175], v[204:207], v[22:25]
	v_mfma_f32_16x16x32_bf16 v[18:21], v[180:183], v[204:207], v[18:21]
	v_mfma_f32_16x16x32_bf16 v[6:9], v[172:175], v[218:221], v[6:9]
	v_mfma_f32_16x16x32_bf16 v[2:5], v[180:183], v[218:221], v[2:5]
	s_barrier
	s_add_i32 s54, s54, 2
	s_add_u32 s24, s24, 0x100
	s_addc_u32 s25, s25, 0
	s_cmp_gt_u32 s54, 61
	s_cbranch_scc0 .LBB0_1429
	s_add_u32 s24, s21, 0xffffff00
	s_addc_u32 s25, s45, -1
	s_andn2_b64 vcc, exec, s[2:3]
	s_cbranch_vccnz .LBB0_1420
	v_mov_b32_e32 v2, 0
	s_mov_b32 s6, s14
	s_mov_b32 s4, s16
	s_mov_b64 s[8:9], s[22:23]
	s_mov_b32 s42, s20
	v_mov_b32_e32 v3, 0
	v_mov_b64_e32 v[4:5], 0
	v_mov_b64_e32 v[6:7], 0
	v_mov_b64_e32 v[8:9], 0
	v_mov_b64_e32 v[18:19], 0
	v_mov_b64_e32 v[20:21], 0
	v_mov_b64_e32 v[22:23], 0
	v_mov_b64_e32 v[24:25], 0
	v_mov_b64_e32 v[34:35], 0
	v_mov_b64_e32 v[36:37], 0
	v_mov_b64_e32 v[38:39], 0
	v_mov_b64_e32 v[40:41], 0
	v_mov_b64_e32 v[50:51], 0
	v_mov_b64_e32 v[52:53], 0
	v_mov_b64_e32 v[54:55], 0
	v_mov_b64_e32 v[56:57], 0
	v_mov_b64_e32 v[10:11], 0
	v_mov_b64_e32 v[12:13], 0
	v_mov_b64_e32 v[14:15], 0
	v_mov_b64_e32 v[16:17], 0
	v_mov_b64_e32 v[26:27], 0
	v_mov_b64_e32 v[28:29], 0
	v_mov_b64_e32 v[30:31], 0
	v_mov_b64_e32 v[32:33], 0
	v_mov_b64_e32 v[42:43], 0
	v_mov_b64_e32 v[44:45], 0
	v_mov_b64_e32 v[46:47], 0
	v_mov_b64_e32 v[48:49], 0
	v_mov_b64_e32 v[58:59], 0
	v_mov_b64_e32 v[60:61], 0
	v_mov_b64_e32 v[62:63], 0
	v_mov_b64_e32 v[64:65], 0
	v_mov_b64_e32 v[66:67], 0
	v_mov_b64_e32 v[68:69], 0
	v_mov_b64_e32 v[70:71], 0
	v_mov_b64_e32 v[72:73], 0
	v_mov_b64_e32 v[82:83], 0
	v_mov_b64_e32 v[84:85], 0
	v_mov_b64_e32 v[86:87], 0
	v_mov_b64_e32 v[88:89], 0
	v_mov_b64_e32 v[98:99], 0
	v_mov_b64_e32 v[100:101], 0
	v_mov_b64_e32 v[102:103], 0
	v_mov_b64_e32 v[104:105], 0
	v_mov_b64_e32 v[114:115], 0
	v_mov_b64_e32 v[116:117], 0
	v_mov_b64_e32 v[118:119], 0
	v_mov_b64_e32 v[120:121], 0
	v_mov_b64_e32 v[74:75], 0
	v_mov_b64_e32 v[76:77], 0
	v_mov_b64_e32 v[78:79], 0
	v_mov_b64_e32 v[80:81], 0
	v_mov_b64_e32 v[90:91], 0
	v_mov_b64_e32 v[92:93], 0
	v_mov_b64_e32 v[94:95], 0
	v_mov_b64_e32 v[96:97], 0
	v_mov_b64_e32 v[106:107], 0
	v_mov_b64_e32 v[108:109], 0
	v_mov_b64_e32 v[110:111], 0
	v_mov_b64_e32 v[112:113], 0
	v_mov_b64_e32 v[122:123], 0
	v_mov_b64_e32 v[124:125], 0
	v_mov_b64_e32 v[126:127], 0
	v_mov_b64_e32 v[128:129], 0
	s_andn2_b64 vcc, exec, s[0:1]
	s_cbranch_vccnz .LBB0_1421

;     __device__ __forceinline__ bool run(const f32x4 (&v)[2][2][4][2], const Unit& u, int wr, int wc, int fr, int fq, PG8_LAS unsigned char* lds, int wid, int lane) const {
;     ...
;         if (wid == 0) {
;             bool dead = false; const unsigned long long t0 = __builtin_amdgcn_s_memrealtime(); const unsigned want = 8u * (unsigned)ntn;
;             for (;;) {
;                 if ((unsigned)__builtin_amdgcn_readfirstlane(__hip_atomic_load(cnt + 64 * u.pm, __ATOMIC_RELAXED, __HIP_MEMORY_SCOPE_AGENT)) >= want) break;
;                 if (__builtin_amdgcn_s_memrealtime() - t0 > 2000000ull) {
;                     if (lane == 0) { unsigned expect = 0u; __hip_atomic_compare_exchange_strong(tmo + 1, &expect, code | (unsigned)(u.pm & 0xff), __ATOMIC_RELAXED, __ATOMIC_RELAXED, __HIP_MEMORY_SCOPE_AGENT);
;                                      __hip_atomic_store(tmo, 1u, __ATOMIC_RELAXED, __HIP_MEMORY_SCOPE_AGENT); }
;                     dead = true; break; }
;                 __builtin_amdgcn_s_sleep(2);
;             }
;             if (lane == 0) flag[0] = dead ? 1u : 0u;
;         }
;         asm volatile("s_waitcnt vmcnt(0) lgkmcnt(0)" ::: "memory"); __builtin_amdgcn_s_barrier(); asm volatile("" ::: "memory");
;         const bool bad = flag[0] != 0u;
;         if (lane < 32) {
;             const unsigned long long* slot = (const unsigned long long*)xbuf + (size_t)(u.pm * BM + row) * 4; float q = 0.f;
; #pragma unroll
;             for (int t = 0; t < 4; ++t) if (t < ntn) { const unsigned long long w = __hip_atomic_load(slot + t, __ATOMIC_RELAXED, __HIP_MEMORY_SCOPE_AGENT); q += __uint_as_float((unsigned)(w >> 32)); }
.Lxp8:
	global_load_dwordx2 v[222:223], v[218:219], off sc1
	global_load_dwordx2 v[224:225], v[218:219], off offset:8 sc1
	global_load_dwordx2 v[226:227], v[218:219], off offset:16 sc1
	global_load_dwordx2 v[228:229], v[218:219], off offset:24 sc1
	s_bitcmp1_b32 s98, 0
	s_cbranch_scc1 .Lxk8
	s_waitcnt vmcnt(0)
	v_and_b32_e32 v213, v222, v224
	v_and_b32_e32 v213, v213, v226
	v_and_b32_e32 v213, v213, v228
	v_cmp_ne_u32_e32 vcc, 1, v213
	s_cbranch_vccz .Lxk8
	s_add_i32 s100, s100, 1
	s_cmp_lt_u32 s100, 0x40000
	s_cbranch_scc1 .Lxp8
